# speedup vs baseline: 1.0465x; 1.0134x over previous
;     ...
;   for (int kt = 0; kt < nk; ++kt) {
;     const int kn = (kt + 1 < nk) ? kt + 1 : kt;
;     GW_LOAD2(kn * 64, kn * bkstep)
;     __builtin_amdgcn_sched_barrier(0);
;     __builtin_amdgcn_s_setprio(1);
; #pragma unroll
;     for (int st = 0; st < 4; ++st) {
;       bf16x8 a0 = *(const bf16x8*)(Ab + st * 32);
;       bf16x8 a1 = *(const bf16x8*)(Ab + 32 * LSTR + st * 32);
;       bf16x8 b0 = *(const bf16x8*)(Bb + st * 32);
;       bf16x8 b1 = *(const bf16x8*)(Bb + 32 * LSTR + st * 32);
;       bf16x8 b2 = *(const bf16x8*)(Bb + 64 * LSTR + st * 32);
;       bf16x8 b3 = *(const bf16x8*)(Bb + 96 * LSTR + st * 32);
;       acc[0][0] = mfma32(a0, b0, acc[0][0]);
;       acc[0][1] = mfma32(a0, b1, acc[0][1]);
;       acc[0][2] = mfma32(a0, b2, acc[0][2]);
;       acc[0][3] = mfma32(a0, b3, acc[0][3]);
;       acc[1][0] = mfma32(a1, b0, acc[1][0]);
;       acc[1][1] = mfma32(a1, b1, acc[1][1]);
;       acc[1][2] = mfma32(a1, b2, acc[1][2]);
;       acc[1][3] = mfma32(a1, b3, acc[1][3]);
;     }
;     __builtin_amdgcn_s_setprio(0);
;     __builtin_amdgcn_sched_barrier(0);
.LBB0_238:
	s_setprio 1
	ds_read_b128 v[202:205], v131 offset:0
	ds_read_b128 v[214:217], v136 offset:18432
	ds_read_b128 v[218:221], v136 offset:23040
	ds_read_b128 v[224:227], v136 offset:27648
	ds_read_b128 v[228:231], v136 offset:32256
	ds_read_b128 v[210:213], v131 offset:4608
	s_waitcnt lgkmcnt(4)
	v_mfma_f32_32x32x16_bf16 v[114:129], v[202:205], v[214:217], v[114:129]
	ds_read_b128 v[206:209], v131 offset:32
	ds_read_b128 v[232:235], v136 offset:18464
	s_waitcnt lgkmcnt(5)
	v_mfma_f32_32x32x16_bf16 v[98:113], v[202:205], v[218:221], v[98:113]
	ds_read_b128 v[236:239], v136 offset:23072
	s_waitcnt lgkmcnt(5)
	v_mfma_f32_32x32x16_bf16 v[82:97], v[202:205], v[224:227], v[82:97]
	ds_read_b128 v[240:243], v136 offset:27680
	s_waitcnt lgkmcnt(5)
	v_mfma_f32_32x32x16_bf16 v[66:81], v[202:205], v[228:231], v[66:81]
	ds_read_b128 v[244:247], v136 offset:32288
	s_waitcnt lgkmcnt(5)
	v_mfma_f32_32x32x16_bf16 v[50:65], v[210:213], v[214:217], v[50:65]
	v_lshl_add_u64 v[150:151], v[148:149], 0, s[10:11]
	v_add_co_u32_e32 v150, vcc, 0x12c31000, v150
	s_nop 1
	v_addc_co_u32_e32 v151, vcc, 0, v151, vcc
	global_load_dwordx4 v[150:153], v[150:151], off offset:384
	v_mfma_f32_32x32x16_bf16 v[34:49], v[210:213], v[218:221], v[34:49]
	v_lshl_add_u64 v[154:155], v[148:149], 0, s[10:11]
	v_add_co_u32_e32 v154, vcc, 0x12c41000, v154
	s_nop 1
	v_addc_co_u32_e32 v155, vcc, 0, v155, vcc
	global_load_dwordx4 v[154:157], v[154:155], off offset:384
	v_mfma_f32_32x32x16_bf16 v[18:33], v[210:213], v[224:227], v[18:33]
	v_lshl_add_u64 v[158:159], v[148:149], 0, s[10:11]
	v_add_co_u32_e32 v158, vcc, 0x12c51000, v158
	s_nop 1
	v_addc_co_u32_e32 v159, vcc, 0, v159, vcc
	global_load_dwordx4 v[158:161], v[158:159], off offset:384
	v_mfma_f32_32x32x16_bf16 v[2:17], v[210:213], v[228:231], v[2:17]
	v_lshl_add_u64 v[162:163], v[148:149], 0, s[10:11]
	v_add_co_u32_e32 v162, vcc, 0x12c61000, v162
	s_nop 1
	v_addc_co_u32_e32 v163, vcc, 0, v163, vcc
	global_load_dwordx4 v[162:165], v[162:163], off offset:384
	ds_read_b128 v[210:213], v131 offset:4640
	s_waitcnt lgkmcnt(4)
	v_mfma_f32_32x32x16_bf16 v[114:129], v[206:209], v[232:235], v[114:129]
	ds_read_b128 v[202:205], v131 offset:64
	ds_read_b128 v[214:217], v136 offset:18496
	s_waitcnt lgkmcnt(5)
	v_mfma_f32_32x32x16_bf16 v[98:113], v[206:209], v[236:239], v[98:113]
	ds_read_b128 v[218:221], v136 offset:23104
	s_waitcnt lgkmcnt(5)
	v_mfma_f32_32x32x16_bf16 v[82:97], v[206:209], v[240:243], v[82:97]
	ds_read_b128 v[224:227], v136 offset:27712
	s_waitcnt lgkmcnt(5)
	v_mfma_f32_32x32x16_bf16 v[66:81], v[206:209], v[244:247], v[66:81]
	ds_read_b128 v[228:231], v136 offset:32320
	s_waitcnt lgkmcnt(5)
	v_mfma_f32_32x32x16_bf16 v[50:65], v[210:213], v[232:235], v[50:65]
	v_lshl_add_u64 v[166:167], v[132:133], 0, s[10:11]
	global_load_dwordx4 v[166:169], v[166:167], off offset:128
	v_mfma_f32_32x32x16_bf16 v[34:49], v[210:213], v[236:239], v[34:49]
	v_lshl_add_u64 v[170:171], v[132:133], 0, s[10:11]
	v_add_co_u32_e32 v170, vcc, s37, v170
	s_nop 1
	v_addc_co_u32_e32 v171, vcc, 0, v171, vcc
	global_load_dwordx4 v[170:173], v[170:171], off offset:128
	v_mfma_f32_32x32x16_bf16 v[18:33], v[210:213], v[240:243], v[18:33]
	v_lshl_add_u64 v[174:175], v[132:133], 0, s[10:11]
	v_add_co_u32_e32 v174, vcc, s38, v174
	s_nop 1
	v_addc_co_u32_e32 v175, vcc, 0, v175, vcc
	global_load_dwordx4 v[174:177], v[174:175], off offset:128
	v_mfma_f32_32x32x16_bf16 v[2:17], v[210:213], v[244:247], v[2:17]
	v_lshl_add_u64 v[178:179], v[132:133], 0, s[10:11]
	v_add_co_u32_e32 v178, vcc, s39, v178
	s_nop 1
	v_addc_co_u32_e32 v179, vcc, 0, v179, vcc
	global_load_dwordx4 v[178:181], v[178:179], off offset:128
	ds_read_b128 v[210:213], v131 offset:4672
	s_waitcnt lgkmcnt(4)
	v_mfma_f32_32x32x16_bf16 v[114:129], v[202:205], v[214:217], v[114:129]
	ds_read_b128 v[206:209], v131 offset:96
	ds_read_b128 v[232:235], v136 offset:18528
	s_waitcnt lgkmcnt(5)
	v_mfma_f32_32x32x16_bf16 v[98:113], v[202:205], v[218:221], v[98:113]
	ds_read_b128 v[236:239], v136 offset:23136
	s_waitcnt lgkmcnt(5)
	v_mfma_f32_32x32x16_bf16 v[82:97], v[202:205], v[224:227], v[82:97]
	ds_read_b128 v[240:243], v136 offset:27744
	s_waitcnt lgkmcnt(5)
	v_mfma_f32_32x32x16_bf16 v[66:81], v[202:205], v[228:231], v[66:81]
	ds_read_b128 v[244:247], v136 offset:32352
	s_waitcnt lgkmcnt(5)
	v_mfma_f32_32x32x16_bf16 v[50:65], v[210:213], v[214:217], v[50:65]
	v_lshl_add_u64 v[186:187], v[132:133], 0, s[10:11]
	v_add_co_u32_e32 v186, vcc, s40, v186
	s_nop 1
	v_addc_co_u32_e32 v187, vcc, 0, v187, vcc
	global_load_dwordx4 v[186:189], v[186:187], off offset:128
	v_mfma_f32_32x32x16_bf16 v[34:49], v[210:213], v[218:221], v[34:49]
	v_lshl_add_u64 v[190:191], v[132:133], 0, s[10:11]
	v_add_co_u32_e32 v190, vcc, s41, v190
	s_nop 1
	v_addc_co_u32_e32 v191, vcc, 0, v191, vcc
	global_load_dwordx4 v[190:193], v[190:191], off offset:128
	v_mfma_f32_32x32x16_bf16 v[18:33], v[210:213], v[224:227], v[18:33]
	v_lshl_add_u64 v[194:195], v[132:133], 0, s[10:11]
	v_add_co_u32_e32 v194, vcc, s42, v194
	s_nop 1
	v_addc_co_u32_e32 v195, vcc, 0, v195, vcc
	global_load_dwordx4 v[194:197], v[194:195], off offset:128
	v_mfma_f32_32x32x16_bf16 v[2:17], v[210:213], v[228:231], v[2:17]
	v_lshl_add_u64 v[198:199], v[132:133], 0, s[10:11]
	v_add_co_u32_e32 v198, vcc, s43, v198
	s_nop 1
	v_addc_co_u32_e32 v199, vcc, 0, v199, vcc
	global_load_dwordx4 v[198:201], v[198:199], off offset:128
	ds_read_b128 v[210:213], v131 offset:4704
	s_waitcnt lgkmcnt(4)
	v_mfma_f32_32x32x16_bf16 v[114:129], v[206:209], v[232:235], v[114:129]
	s_waitcnt lgkmcnt(3)
	v_mfma_f32_32x32x16_bf16 v[98:113], v[206:209], v[236:239], v[98:113]
	s_waitcnt lgkmcnt(2)
	v_mfma_f32_32x32x16_bf16 v[82:97], v[206:209], v[240:243], v[82:97]
	s_waitcnt lgkmcnt(1)
	v_mfma_f32_32x32x16_bf16 v[66:81], v[206:209], v[244:247], v[66:81]
	s_waitcnt lgkmcnt(0)
	v_mfma_f32_32x32x16_bf16 v[50:65], v[210:213], v[232:235], v[50:65]
	v_mfma_f32_32x32x16_bf16 v[34:49], v[210:213], v[236:239], v[34:49]
	v_mfma_f32_32x32x16_bf16 v[18:33], v[210:213], v[240:243], v[18:33]
	v_mfma_f32_32x32x16_bf16 v[2:17], v[210:213], v[244:247], v[2:17]
	s_setprio 0
	s_add_u32 s10, s10, 0x80
	s_addc_u32 s11, s11, 0
	s_cmpk_lg_i32 s10, 0x700
	s_barrier
; #define GW_LOAD(KOFF) GW_LOAD2(KOFF, 0)
;     ...
;   GW_LOAD(0)
;   GW_STORE()
;   __syncthreads();
;   const int nk = K >> 6;
;   const char* Ab = smem + (wm * 64 + (lane & 31)) * LSTR + (lane >> 5) * 16;
;   const char* Bb = smem + WTILE_A + (wn * 128 + (lane & 31)) * LSTR + (lane >> 5) * 16;
;   for (int kt = 0; kt < nk; ++kt) {
;     const int kn = (kt + 1 < nk) ? kt + 1 : kt;
;     GW_LOAD2(kn * 64, kn * bkstep)
;     __builtin_amdgcn_sched_barrier(0);
;     __builtin_amdgcn_s_setprio(1);
; #pragma unroll
;     for (int st = 0; st < 4; ++st) {
;       bf16x8 a0 = *(const bf16x8*)(Ab + st * 32);
;       bf16x8 a1 = *(const bf16x8*)(Ab + 32 * LSTR + st * 32);
;       bf16x8 b0 = *(const bf16x8*)(Bb + st * 32);
;       bf16x8 b1 = *(const bf16x8*)(Bb + 32 * LSTR + st * 32);
;       bf16x8 b2 = *(const bf16x8*)(Bb + 64 * LSTR + st * 32);
;       bf16x8 b3 = *(const bf16x8*)(Bb + 96 * LSTR + st * 32);
;       acc[0][0] = mfma32(a0, b0, acc[0][0]);
;       acc[0][1] = mfma32(a0, b1, acc[0][1]);
;       acc[0][2] = mfma32(a0, b2, acc[0][2]);
;       acc[0][3] = mfma32(a0, b3, acc[0][3]);
;       acc[1][0] = mfma32(a1, b0, acc[1][0]);
;       acc[1][1] = mfma32(a1, b1, acc[1][1]);
;       acc[1][2] = mfma32(a1, b2, acc[1][2]);
;       acc[1][3] = mfma32(a1, b3, acc[1][3]);
;     }
;     __builtin_amdgcn_s_setprio(0);
;     __builtin_amdgcn_sched_barrier(0);
;     __syncthreads();
;     GW_STORE()
;     __syncthreads();
	s_waitcnt vmcnt(11)
	ds_write_b128 v130, v[150:153]
	s_waitcnt vmcnt(10)
	ds_write_b128 v130, v[154:157] offset:4608
	s_waitcnt vmcnt(9)
	ds_write_b128 v130, v[158:161] offset:9216
	s_waitcnt vmcnt(8)
	ds_write_b128 v130, v[162:165] offset:13824
	s_waitcnt vmcnt(7)
	ds_write_b128 v130, v[166:169] offset:18432
	s_waitcnt vmcnt(6)
	ds_write_b128 v130, v[170:173] offset:23040
	s_waitcnt vmcnt(5)
	ds_write_b128 v130, v[174:177] offset:27648
	s_waitcnt vmcnt(4)
	ds_write_b128 v130, v[178:181] offset:32256
	s_waitcnt vmcnt(3)
	ds_write_b128 v130, v[186:189] offset:36864
	s_waitcnt vmcnt(2)
	ds_write_b128 v130, v[190:193] offset:41472
	s_waitcnt vmcnt(1)
	ds_write_b128 v130, v[194:197] offset:46080
	s_waitcnt vmcnt(0)
	ds_write_b128 v130, v[198:201] offset:50688
	s_waitcnt lgkmcnt(0)
	s_barrier
	s_cbranch_scc1 .LBB0_238
	s_setprio 1
	ds_read_b128 v[202:205], v131 offset:0
	ds_read_b128 v[214:217], v136 offset:18432
	ds_read_b128 v[218:221], v136 offset:23040
	ds_read_b128 v[224:227], v136 offset:27648
	ds_read_b128 v[228:231], v136 offset:32256
	ds_read_b128 v[210:213], v131 offset:4608
	s_waitcnt lgkmcnt(4)
	v_mfma_f32_32x32x16_bf16 v[114:129], v[202:205], v[214:217], v[114:129]
	ds_read_b128 v[206:209], v131 offset:32
	ds_read_b128 v[232:235], v136 offset:18464
	s_waitcnt lgkmcnt(5)
	v_mfma_f32_32x32x16_bf16 v[98:113], v[202:205], v[218:221], v[98:113]
	ds_read_b128 v[236:239], v136 offset:23072
	s_waitcnt lgkmcnt(5)
	v_mfma_f32_32x32x16_bf16 v[82:97], v[202:205], v[224:227], v[82:97]
	ds_read_b128 v[240:243], v136 offset:27680
	s_waitcnt lgkmcnt(5)
	v_mfma_f32_32x32x16_bf16 v[66:81], v[202:205], v[228:231], v[66:81]
	ds_read_b128 v[244:247], v136 offset:32288
	s_waitcnt lgkmcnt(5)
	v_mfma_f32_32x32x16_bf16 v[50:65], v[210:213], v[214:217], v[50:65]
	v_lshl_add_u64 v[150:151], v[148:149], 0, s[10:11]
	v_add_co_u32_e32 v150, vcc, 0x12c31000, v150
	s_nop 1
	v_addc_co_u32_e32 v151, vcc, 0, v151, vcc
	global_load_dwordx4 v[150:153], v[150:151], off offset:384
	v_mfma_f32_32x32x16_bf16 v[34:49], v[210:213], v[218:221], v[34:49]
	v_lshl_add_u64 v[154:155], v[148:149], 0, s[10:11]
	v_add_co_u32_e32 v154, vcc, 0x12c41000, v154
	s_nop 1
	v_addc_co_u32_e32 v155, vcc, 0, v155, vcc
	global_load_dwordx4 v[154:157], v[154:155], off offset:384
	v_mfma_f32_32x32x16_bf16 v[18:33], v[210:213], v[224:227], v[18:33]
	v_lshl_add_u64 v[158:159], v[148:149], 0, s[10:11]
	v_add_co_u32_e32 v158, vcc, 0x12c51000, v158
	s_nop 1
	v_addc_co_u32_e32 v159, vcc, 0, v159, vcc
	global_load_dwordx4 v[158:161], v[158:159], off offset:384
	v_mfma_f32_32x32x16_bf16 v[2:17], v[210:213], v[228:231], v[2:17]
	v_lshl_add_u64 v[162:163], v[148:149], 0, s[10:11]
	v_add_co_u32_e32 v162, vcc, 0x12c61000, v162
	s_nop 1
	v_addc_co_u32_e32 v163, vcc, 0, v163, vcc
	global_load_dwordx4 v[162:165], v[162:163], off offset:384
	ds_read_b128 v[210:213], v131 offset:4640
	s_waitcnt lgkmcnt(4)
	v_mfma_f32_32x32x16_bf16 v[114:129], v[206:209], v[232:235], v[114:129]
	ds_read_b128 v[202:205], v131 offset:64
	ds_read_b128 v[214:217], v136 offset:18496
	s_waitcnt lgkmcnt(5)
	v_mfma_f32_32x32x16_bf16 v[98:113], v[206:209], v[236:239], v[98:113]
	ds_read_b128 v[218:221], v136 offset:23104
	s_waitcnt lgkmcnt(5)
	v_mfma_f32_32x32x16_bf16 v[82:97], v[206:209], v[240:243], v[82:97]
	ds_read_b128 v[224:227], v136 offset:27712
	s_waitcnt lgkmcnt(5)
	v_mfma_f32_32x32x16_bf16 v[66:81], v[206:209], v[244:247], v[66:81]
	ds_read_b128 v[228:231], v136 offset:32320
	s_waitcnt lgkmcnt(5)
	v_mfma_f32_32x32x16_bf16 v[50:65], v[210:213], v[232:235], v[50:65]
	v_lshl_add_u64 v[166:167], v[132:133], 0, s[10:11]
	global_load_dwordx4 v[166:169], v[166:167], off offset:128
	v_mfma_f32_32x32x16_bf16 v[34:49], v[210:213], v[236:239], v[34:49]
	v_lshl_add_u64 v[170:171], v[132:133], 0, s[10:11]
	v_add_co_u32_e32 v170, vcc, s37, v170
	s_nop 1
	v_addc_co_u32_e32 v171, vcc, 0, v171, vcc
	global_load_dwordx4 v[170:173], v[170:171], off offset:128
	v_mfma_f32_32x32x16_bf16 v[18:33], v[210:213], v[240:243], v[18:33]
	v_lshl_add_u64 v[174:175], v[132:133], 0, s[10:11]
	v_add_co_u32_e32 v174, vcc, s38, v174
	s_nop 1
	v_addc_co_u32_e32 v175, vcc, 0, v175, vcc
	global_load_dwordx4 v[174:177], v[174:175], off offset:128
	v_mfma_f32_32x32x16_bf16 v[2:17], v[210:213], v[244:247], v[2:17]
	v_lshl_add_u64 v[178:179], v[132:133], 0, s[10:11]
	v_add_co_u32_e32 v178, vcc, s39, v178
	s_nop 1
	v_addc_co_u32_e32 v179, vcc, 0, v179, vcc
	global_load_dwordx4 v[178:181], v[178:179], off offset:128
	ds_read_b128 v[210:213], v131 offset:4672
	s_waitcnt lgkmcnt(4)
	v_mfma_f32_32x32x16_bf16 v[114:129], v[202:205], v[214:217], v[114:129]
	ds_read_b128 v[206:209], v131 offset:96
	ds_read_b128 v[232:235], v136 offset:18528
	s_waitcnt lgkmcnt(5)
	v_mfma_f32_32x32x16_bf16 v[98:113], v[202:205], v[218:221], v[98:113]
	ds_read_b128 v[236:239], v136 offset:23136
	s_waitcnt lgkmcnt(5)
	v_mfma_f32_32x32x16_bf16 v[82:97], v[202:205], v[224:227], v[82:97]
	ds_read_b128 v[240:243], v136 offset:27744
	s_waitcnt lgkmcnt(5)
	v_mfma_f32_32x32x16_bf16 v[66:81], v[202:205], v[228:231], v[66:81]
	ds_read_b128 v[244:247], v136 offset:32352
	s_waitcnt lgkmcnt(5)
	v_mfma_f32_32x32x16_bf16 v[50:65], v[210:213], v[214:217], v[50:65]
	v_lshl_add_u64 v[186:187], v[132:133], 0, s[10:11]
	v_add_co_u32_e32 v186, vcc, s40, v186
	s_nop 1
	v_addc_co_u32_e32 v187, vcc, 0, v187, vcc
	global_load_dwordx4 v[186:189], v[186:187], off offset:128
	v_mfma_f32_32x32x16_bf16 v[34:49], v[210:213], v[218:221], v[34:49]
	v_lshl_add_u64 v[190:191], v[132:133], 0, s[10:11]
	v_add_co_u32_e32 v190, vcc, s41, v190
	s_nop 1
	v_addc_co_u32_e32 v191, vcc, 0, v191, vcc
	global_load_dwordx4 v[190:193], v[190:191], off offset:128
	v_mfma_f32_32x32x16_bf16 v[18:33], v[210:213], v[224:227], v[18:33]
	v_lshl_add_u64 v[194:195], v[132:133], 0, s[10:11]
	v_add_co_u32_e32 v194, vcc, s42, v194
	s_nop 1
	v_addc_co_u32_e32 v195, vcc, 0, v195, vcc
	global_load_dwordx4 v[194:197], v[194:195], off offset:128
	v_mfma_f32_32x32x16_bf16 v[2:17], v[210:213], v[228:231], v[2:17]
	v_lshl_add_u64 v[198:199], v[132:133], 0, s[10:11]
	v_add_co_u32_e32 v198, vcc, s43, v198
	s_nop 1
	v_addc_co_u32_e32 v199, vcc, 0, v199, vcc
	global_load_dwordx4 v[198:201], v[198:199], off offset:128
	ds_read_b128 v[210:213], v131 offset:4704
	s_waitcnt lgkmcnt(4)
	v_mfma_f32_32x32x16_bf16 v[114:129], v[206:209], v[232:235], v[114:129]
	s_waitcnt lgkmcnt(3)
	v_mfma_f32_32x32x16_bf16 v[98:113], v[206:209], v[236:239], v[98:113]
	s_waitcnt lgkmcnt(2)
	v_mfma_f32_32x32x16_bf16 v[82:97], v[206:209], v[240:243], v[82:97]
	s_waitcnt lgkmcnt(1)
	v_mfma_f32_32x32x16_bf16 v[66:81], v[206:209], v[244:247], v[66:81]
	s_waitcnt lgkmcnt(0)
	v_mfma_f32_32x32x16_bf16 v[50:65], v[210:213], v[232:235], v[50:65]
	v_mfma_f32_32x32x16_bf16 v[34:49], v[210:213], v[236:239], v[34:49]
	v_mfma_f32_32x32x16_bf16 v[18:33], v[210:213], v[240:243], v[18:33]
	v_mfma_f32_32x32x16_bf16 v[2:17], v[210:213], v[244:247], v[2:17]
	s_setprio 0
	s_add_u32 s10, s10, 0x80
	s_addc_u32 s11, s11, 0
	s_barrier
; #define GW_LOAD(KOFF) GW_LOAD2(KOFF, 0)
;     ...
;   GW_LOAD(0)
;   GW_STORE()
;   __syncthreads();
;   const int nk = K >> 6;
;   const char* Ab = smem + (wm * 64 + (lane & 31)) * LSTR + (lane >> 5) * 16;
;   const char* Bb = smem + WTILE_A + (wn * 128 + (lane & 31)) * LSTR + (lane >> 5) * 16;
;   for (int kt = 0; kt < nk; ++kt) {
;     const int kn = (kt + 1 < nk) ? kt + 1 : kt;
;     GW_LOAD2(kn * 64, kn * bkstep)
;     __builtin_amdgcn_sched_barrier(0);
;     __builtin_amdgcn_s_setprio(1);
; #pragma unroll
;     for (int st = 0; st < 4; ++st) {
;       bf16x8 a0 = *(const bf16x8*)(Ab + st * 32);
;       bf16x8 a1 = *(const bf16x8*)(Ab + 32 * LSTR + st * 32);
;       bf16x8 b0 = *(const bf16x8*)(Bb + st * 32);
;       bf16x8 b1 = *(const bf16x8*)(Bb + 32 * LSTR + st * 32);
;       bf16x8 b2 = *(const bf16x8*)(Bb + 64 * LSTR + st * 32);
;       bf16x8 b3 = *(const bf16x8*)(Bb + 96 * LSTR + st * 32);
;       acc[0][0] = mfma32(a0, b0, acc[0][0]);
;       acc[0][1] = mfma32(a0, b1, acc[0][1]);
;       acc[0][2] = mfma32(a0, b2, acc[0][2]);
;       acc[0][3] = mfma32(a0, b3, acc[0][3]);
;       acc[1][0] = mfma32(a1, b0, acc[1][0]);
;       acc[1][1] = mfma32(a1, b1, acc[1][1]);
;       acc[1][2] = mfma32(a1, b2, acc[1][2]);
;       acc[1][3] = mfma32(a1, b3, acc[1][3]);
;     }
;     __builtin_amdgcn_s_setprio(0);
;     __builtin_amdgcn_sched_barrier(0);
;     __syncthreads();
;     GW_STORE()
;     __syncthreads();
; __device__ __forceinline__ void inproj_tile(const Params& P, int l, int mt, int ntw, char* smem) {
;     ...
;   const int row0 = mt * 128;
;   const bool isctx = row0 >= NLAT;
;   const int b = isctx ? ((row0 - NLAT) >> 8) : (row0 >> 12);
;   const int pos0 = isctx ? ((row0 - NLAT) & 255) : (row0 & 4095);
;   const int tk0 = isctx ? (SEQ + pos0) : pos0;
	s_waitcnt vmcnt(11)
	ds_write_b128 v130, v[150:153]
	s_waitcnt vmcnt(10)
	ds_write_b128 v130, v[154:157] offset:4608
	s_waitcnt vmcnt(9)
	ds_write_b128 v130, v[158:161] offset:9216
	s_waitcnt vmcnt(8)
	ds_write_b128 v130, v[162:165] offset:13824
	s_waitcnt vmcnt(7)
	ds_write_b128 v130, v[166:169] offset:18432
	s_waitcnt vmcnt(6)
	ds_write_b128 v130, v[170:173] offset:23040
	s_waitcnt vmcnt(5)
	ds_write_b128 v130, v[174:177] offset:27648
	s_waitcnt vmcnt(4)
	ds_write_b128 v130, v[178:181] offset:32256
	s_waitcnt vmcnt(3)
	ds_write_b128 v130, v[186:189] offset:36864
	s_waitcnt vmcnt(2)
	ds_write_b128 v130, v[190:193] offset:41472
	s_waitcnt vmcnt(1)
	ds_write_b128 v130, v[194:197] offset:46080
	s_waitcnt vmcnt(0)
	ds_write_b128 v130, v[198:201] offset:50688
	s_waitcnt lgkmcnt(0)
	s_barrier
	v_add_co_u32_e32 v160, vcc, 0x10000, v132
	s_nop 0
	s_nop 0
	s_nop 0
	v_addc_co_u32_e32 v161, vcc, 0, v133, vcc
	v_add_co_u32_e32 v164, vcc, 0x20000, v132
	s_nop 0
	v_addc_co_u32_e32 v165, vcc, 0, v133, vcc
	v_add_co_u32_e32 v168, vcc, 0x30000, v132
	s_mov_b32 s52, 0
	s_nop 0
	v_addc_co_u32_e32 v169, vcc, 0, v133, vcc
	v_add_co_u32_e32 v172, vcc, 0x40000, v132
	s_nop 0
	v_addc_co_u32_e32 v173, vcc, 0, v133, vcc
	v_add_co_u32_e32 v176, vcc, 0x50000, v132
	s_nop 1
	v_addc_co_u32_e32 v177, vcc, 0, v133, vcc
	v_add_co_u32_e32 v180, vcc, 0x60000, v132
	s_nop 0
	v_addc_co_u32_e32 v181, vcc, 0, v133, vcc
	v_add_co_u32_e32 v132, vcc, 0x70000, v132
	s_nop 1
	v_addc_co_u32_e32 v133, vcc, 0, v133, vcc
	s_setprio 1
	ds_read_b128 v[194:197], v131 offset:0
	ds_read_b128 v[206:209], v136 offset:18432
	ds_read_b128 v[210:213], v136 offset:23040
	ds_read_b128 v[214:217], v136 offset:27648
	ds_read_b128 v[218:221], v136 offset:32256
	ds_read_b128 v[202:205], v131 offset:4608
	s_waitcnt lgkmcnt(4)
	v_mfma_f32_32x32x16_bf16 v[114:129], v[194:197], v[206:209], v[114:129]
	ds_read_b128 v[198:201], v131 offset:32
	ds_read_b128 v[224:227], v136 offset:18464
	s_waitcnt lgkmcnt(5)
	v_mfma_f32_32x32x16_bf16 v[98:113], v[194:197], v[210:213], v[98:113]
	ds_read_b128 v[228:231], v136 offset:23072
	s_waitcnt lgkmcnt(5)
	v_mfma_f32_32x32x16_bf16 v[82:97], v[194:197], v[214:217], v[82:97]
	ds_read_b128 v[232:235], v136 offset:27680
	s_waitcnt lgkmcnt(5)
	v_mfma_f32_32x32x16_bf16 v[66:81], v[194:197], v[218:221], v[66:81]
	ds_read_b128 v[236:239], v136 offset:32288
	s_waitcnt lgkmcnt(5)
	v_mfma_f32_32x32x16_bf16 v[50:65], v[202:205], v[206:209], v[50:65]
	v_mfma_f32_32x32x16_bf16 v[34:49], v[202:205], v[210:213], v[34:49]
	v_mfma_f32_32x32x16_bf16 v[18:33], v[202:205], v[214:217], v[18:33]
	v_mfma_f32_32x32x16_bf16 v[2:17], v[202:205], v[218:221], v[2:17]
	ds_read_b128 v[202:205], v131 offset:4640
	s_waitcnt lgkmcnt(4)
	v_mfma_f32_32x32x16_bf16 v[114:129], v[198:201], v[224:227], v[114:129]
	ds_read_b128 v[194:197], v131 offset:64
	ds_read_b128 v[206:209], v136 offset:18496
	s_waitcnt lgkmcnt(5)
	v_mfma_f32_32x32x16_bf16 v[98:113], v[198:201], v[228:231], v[98:113]
	ds_read_b128 v[210:213], v136 offset:23104
	s_waitcnt lgkmcnt(5)
	v_mfma_f32_32x32x16_bf16 v[82:97], v[198:201], v[232:235], v[82:97]
	ds_read_b128 v[214:217], v136 offset:27712
	s_waitcnt lgkmcnt(5)
	v_mfma_f32_32x32x16_bf16 v[66:81], v[198:201], v[236:239], v[66:81]
	ds_read_b128 v[218:221], v136 offset:32320
	s_waitcnt lgkmcnt(5)
	v_mfma_f32_32x32x16_bf16 v[50:65], v[202:205], v[224:227], v[50:65]
	v_mfma_f32_32x32x16_bf16 v[34:49], v[202:205], v[228:231], v[34:49]
	v_mfma_f32_32x32x16_bf16 v[18:33], v[202:205], v[232:235], v[18:33]
	v_mfma_f32_32x32x16_bf16 v[2:17], v[202:205], v[236:239], v[2:17]
	ds_read_b128 v[202:205], v131 offset:4672
	s_waitcnt lgkmcnt(4)
	v_mfma_f32_32x32x16_bf16 v[114:129], v[194:197], v[206:209], v[114:129]
	ds_read_b128 v[198:201], v131 offset:96
	ds_read_b128 v[224:227], v136 offset:18528
	s_waitcnt lgkmcnt(5)
	v_mfma_f32_32x32x16_bf16 v[98:113], v[194:197], v[210:213], v[98:113]
	ds_read_b128 v[228:231], v136 offset:23136
	s_waitcnt lgkmcnt(5)
	v_mfma_f32_32x32x16_bf16 v[82:97], v[194:197], v[214:217], v[82:97]
	ds_read_b128 v[232:235], v136 offset:27744
	s_waitcnt lgkmcnt(5)
	v_mfma_f32_32x32x16_bf16 v[66:81], v[194:197], v[218:221], v[66:81]
	ds_read_b128 v[236:239], v136 offset:32352
	s_waitcnt lgkmcnt(5)
	v_mfma_f32_32x32x16_bf16 v[50:65], v[202:205], v[206:209], v[50:65]
	v_mfma_f32_32x32x16_bf16 v[34:49], v[202:205], v[210:213], v[34:49]
	v_mfma_f32_32x32x16_bf16 v[18:33], v[202:205], v[214:217], v[18:33]
	v_mfma_f32_32x32x16_bf16 v[2:17], v[202:205], v[218:221], v[2:17]
	ds_read_b128 v[202:205], v131 offset:4704
	s_waitcnt lgkmcnt(4)
	v_mfma_f32_32x32x16_bf16 v[114:129], v[198:201], v[224:227], v[114:129]
	s_waitcnt lgkmcnt(3)
	v_mfma_f32_32x32x16_bf16 v[98:113], v[198:201], v[228:231], v[98:113]
	s_waitcnt lgkmcnt(2)
	v_mfma_f32_32x32x16_bf16 v[82:97], v[198:201], v[232:235], v[82:97]
	s_waitcnt lgkmcnt(1)
	v_mfma_f32_32x32x16_bf16 v[66:81], v[198:201], v[236:239], v[66:81]
	s_waitcnt lgkmcnt(0)
	v_mfma_f32_32x32x16_bf16 v[50:65], v[202:205], v[224:227], v[50:65]
	v_mfma_f32_32x32x16_bf16 v[34:49], v[202:205], v[228:231], v[34:49]
	v_mfma_f32_32x32x16_bf16 v[18:33], v[202:205], v[232:235], v[18:33]
	v_mfma_f32_32x32x16_bf16 v[2:17], v[202:205], v[236:239], v[2:17]
	s_setprio 0
	s_lshl_b32 s20, s12, 7
	s_cmpk_lt_i32 s12, 0x100
	s_cselect_b64 s[10:11], -1, 0
	s_add_i32 s8, s20, 0xffff8000
	s_and_b32 s51, s20, 0x80
	s_lshr_b32 s8, s8, 8
	s_ashr_i32 s22, s18, 2
	s_and_b32 s53, s20, 0xf80
	s_or_b32 s13, s51, 0x1000
	s_barrier
; __device__ __forceinline__ void inproj_tile(const Params& P, int l, int mt, int ntw, char* smem) {
;     ...
;   const int row0 = mt * 128;
;   const bool isctx = row0 >= NLAT;
;   const int b = isctx ? ((row0 - NLAT) >> 8) : (row0 >> 12);
;   const int pos0 = isctx ? ((row0 - NLAT) & 255) : (row0 & 4095);
;   const int tk0 = isctx ? (SEQ + pos0) : pos0;
;   int tid_ = threadIdx.x;
;   asm volatile("" : "+v"(tid_));
;   const int lane = tid_ & 63, wave = tid_ >> 6;
;   const int r = 32 * wave + (lane & 31), half = lane >> 5;
;   const size_t grow = (size_t)row0 + r;
;   const float* crow = cs + r * CSTR + half * 64;
; #pragma unroll 1
;   for (int hsel = 0; hsel < 2; ++hsel) {
;     const int nt = ntw * 2 + hsel;
;     wide_acc_to_lds(acc, cs, hsel);
;     if (nt < 4) {
;       const int part = nt >> 1, cb = (nt & 1) * 128;
;       if (!isctx) {
;         u16* base = WSP(u16, OFF_FTT) + (size_t)b * 256 * 8192 + part * 4096 + pos0;
;         epi_transposed(cs, [&](int ch) { return base + (size_t)(cb + ch) * 8192; });
;       } else {
;         u16* base = WSP(u16, OFF_FTTC) + (size_t)b * 256 * 512 + part * 256 + pos0;
;         epi_transposed(cs, [&](int ch) { return base + (size_t)(cb + ch) * 512; });
	s_cmpk_gt_i32 s12, 0xff
	v_mov_b32_e32 v152, v134
	s_waitcnt lgkmcnt(0)
	s_cselect_b32 s54, s13, s53
	s_movk_i32 s13, 0xffe0
	v_ashrrev_i32_e32 v153, 1, v152
	v_bfi_b32 v130, s13, v153, v152
	s_cselect_b32 s12, s8, s22
	s_cselect_b32 s15, s51, s53
	s_ashr_i32 s21, s20, 31
	v_ashrrev_i32_e32 v131, 31, v130
	s_ashr_i32 s23, s22, 31
	v_lshl_add_u64 v[132:133], v[130:131], 0, s[20:21]
	s_lshl_b64 s[20:21], s[22:23], 22
	s_lshl_b32 s22, s14, 12
	s_movk_i32 s13, 0x210
	s_lshl_b32 s33, s14, 1
	s_ashr_i32 s23, s22, 31
	s_lshl_b64 s[24:25], s[8:9], 18
	v_mul_lo_u32 v136, v130, s13
	v_lshlrev_b32_e32 v139, 1, v152
	s_mul_i32 s13, s12, 6
	s_cmp_gt_u32 s33, 9
	v_and_b32_e32 v185, 64, v139
	s_mul_i32 s55, s12, 0x330000
	s_mul_hi_i32 s56, s13, 0x88000
	s_cselect_b64 s[12:13], -1, 0
	s_cmp_gt_u32 s33, 21
	v_lshl_add_u32 v186, v185, 2, v136
	v_add_u32_e32 v136, s15, v153
	s_cselect_b64 s[14:15], -1, 0
	s_cmp_lt_u32 s33, 16
	s_cselect_b64 s[26:27], -1, 0
	s_and_b64 s[26:27], s[26:27], exec
	s_mov_b32 s8, 0x1fffff3
	s_cselect_b32 s50, s8, 0x1ffffed
	s_mov_b32 s8, 0x32a31100
	s_cselect_b32 s8, s8, 0x343b1100
	v_mov_b64_e32 v[144:145], s[90:91]
	v_mad_u64_u32 v[144:145], s[26:27], v132, s44, v[144:145]
	s_add_u32 s8, s90, s8
	s_addc_u32 s26, s91, 0
	s_add_u32 s8, s8, s55
	s_addc_u32 s27, s26, s56
	s_lshl_b32 s26, s54, 1
	s_add_u32 s26, s8, s26
	s_addc_u32 s27, s27, 0
	v_mov_b32_e32 v139, v137
	s_add_u32 s8, s30, s20
	v_lshl_add_u64 v[146:147], s[26:27], 0, v[138:139]
	s_addc_u32 s26, s31, s21
	s_lshl_b64 s[20:21], s[22:23], 1
	s_add_u32 s8, s8, s20
	s_addc_u32 s21, s26, s21
	s_lshl_b32 s20, s53, 1
	s_add_u32 s20, s8, s20
	s_addc_u32 s21, s21, 0
	s_add_u32 s8, s34, s24
	v_lshl_add_u64 v[148:149], s[20:21], 0, v[138:139]
	s_addc_u32 s22, s35, s25
	s_lshl_b64 s[20:21], s[16:17], 1
	s_add_u32 s8, s8, s20
	s_addc_u32 s17, s22, s21
	s_lshl_b32 s20, s51, 1
	v_ashrrev_i32_e32 v136, 2, v136
	s_add_u32 s20, s8, s20
	v_and_b32_e32 v140, -16, v136
	v_lshlrev_b32_e32 v136, 4, v130
	s_addc_u32 s21, s17, 0
	s_lshl_b32 s8, s18, 10
	s_lshl_b32 s17, s19, 7
	v_and_b32_e32 v136, 0x3f0, v136
	s_or_b32 s18, s8, s17
	v_and_b32_e32 v154, 31, v152
	v_mov_b64_e32 v[142:143], v[136:137]
	v_lshrrev_b32_e32 v132, 5, v153
	v_bfe_u32 v136, v152, 5, 1
	s_ashr_i32 s19, s18, 31
	v_mad_i32_i24 v145, v133, s44, v145
	v_lshl_add_u64 v[150:151], s[20:21], 0, v[138:139]
	v_mul_lo_u32 v132, v132, s45
	v_mul_u32_u24_e32 v133, 0x210, v154
	v_lshlrev_b32_e32 v139, 8, v136
	v_lshl_add_u64 v[130:131], s[18:19], 0, v[130:131]
	v_add3_u32 v139, v132, v133, v139
	v_mad_u64_u32 v[132:133], s[18:19], v130, s46, 0
	v_mad_i32_i24 v133, v131, s46, v133
	v_lshl_or_b32 v132, v136, 7, v132
	v_lshl_add_u64 v[152:153], s[4:5], 0, v[132:133]
	v_mov_b64_e32 v[132:133], s[6:7]
	s_add_i32 s51, s16, 0xfffff500
	v_mad_u64_u32 v[154:155], s[16:17], v130, s44, v[132:133]
	v_ashrrev_i32_e32 v141, 31, v140
	v_mad_i32_i24 v155, v131, s44, v155
	s_mov_b64 s[16:17], -1
	s_branch .LBB0_241

;     ...
;   for (int kt = 0; kt < nk; ++kt) {
;     const int kn = (kt + 1 < nk) ? kt + 1 : kt;
;     GW_LOAD2(kn * 64, kn * bkstep)
;     __builtin_amdgcn_sched_barrier(0);
;     __builtin_amdgcn_s_setprio(1);
; #pragma unroll
;     for (int st = 0; st < 4; ++st) {
;       bf16x8 a0 = *(const bf16x8*)(Ab + st * 32);
;       bf16x8 a1 = *(const bf16x8*)(Ab + 32 * LSTR + st * 32);
;       bf16x8 b0 = *(const bf16x8*)(Bb + st * 32);
;       bf16x8 b1 = *(const bf16x8*)(Bb + 32 * LSTR + st * 32);
;       bf16x8 b2 = *(const bf16x8*)(Bb + 64 * LSTR + st * 32);
;       bf16x8 b3 = *(const bf16x8*)(Bb + 96 * LSTR + st * 32);
;       acc[0][0] = mfma32(a0, b0, acc[0][0]);
;       acc[0][1] = mfma32(a0, b1, acc[0][1]);
;       acc[0][2] = mfma32(a0, b2, acc[0][2]);
;       acc[0][3] = mfma32(a0, b3, acc[0][3]);
;       acc[1][0] = mfma32(a1, b0, acc[1][0]);
;       acc[1][1] = mfma32(a1, b1, acc[1][1]);
;       acc[1][2] = mfma32(a1, b2, acc[1][2]);
;       acc[1][3] = mfma32(a1, b3, acc[1][3]);
;     }
;     __builtin_amdgcn_s_setprio(0);
;     __builtin_amdgcn_sched_barrier(0);
.LBB0_707:
	s_setprio 1
	ds_read_b128 v[200:203], v130 offset:0
	ds_read_b128 v[212:215], v133 offset:18432
	ds_read_b128 v[216:219], v133 offset:23040
	ds_read_b128 v[224:227], v133 offset:27648
	ds_read_b128 v[228:231], v133 offset:32256
	ds_read_b128 v[208:211], v130 offset:4608
	s_waitcnt lgkmcnt(4)
	v_mfma_f32_32x32x16_bf16 v[114:129], v[200:203], v[212:215], v[114:129]
	ds_read_b128 v[204:207], v130 offset:32
	ds_read_b128 v[232:235], v133 offset:18464
	s_waitcnt lgkmcnt(5)
	v_mfma_f32_32x32x16_bf16 v[98:113], v[200:203], v[216:219], v[98:113]
	ds_read_b128 v[236:239], v133 offset:23072
	s_waitcnt lgkmcnt(5)
	v_mfma_f32_32x32x16_bf16 v[82:97], v[200:203], v[224:227], v[82:97]
	ds_read_b128 v[240:243], v133 offset:27680
	s_waitcnt lgkmcnt(5)
	v_mfma_f32_32x32x16_bf16 v[66:81], v[200:203], v[228:231], v[66:81]
	ds_read_b128 v[244:247], v133 offset:32288
	s_waitcnt lgkmcnt(5)
	v_mfma_f32_32x32x16_bf16 v[50:65], v[208:211], v[212:215], v[50:65]
	v_lshl_add_u64 v[152:153], v[146:147], 0, s[18:19]
	v_add_co_u32_e32 v152, vcc, s39, v152
	s_nop 1
	v_addc_co_u32_e32 v153, vcc, 0, v153, vcc
	global_load_dwordx4 v[152:155], v[152:153], off offset:384
	v_mfma_f32_32x32x16_bf16 v[34:49], v[208:211], v[216:219], v[34:49]
	v_lshl_add_u64 v[156:157], v[146:147], 0, s[18:19]
	v_add_co_u32_e32 v156, vcc, s40, v156
	s_nop 1
	v_addc_co_u32_e32 v157, vcc, 0, v157, vcc
	global_load_dwordx4 v[156:159], v[156:157], off offset:384
	v_mfma_f32_32x32x16_bf16 v[18:33], v[208:211], v[224:227], v[18:33]
	v_lshl_add_u64 v[160:161], v[146:147], 0, s[18:19]
	v_add_co_u32_e32 v160, vcc, s41, v160
	s_nop 1
	v_addc_co_u32_e32 v161, vcc, 0, v161, vcc
	global_load_dwordx4 v[160:163], v[160:161], off offset:384
	v_mfma_f32_32x32x16_bf16 v[2:17], v[208:211], v[228:231], v[2:17]
	v_lshl_add_u64 v[164:165], v[146:147], 0, s[18:19]
	v_add_co_u32_e32 v164, vcc, s42, v164
	s_nop 1
	v_addc_co_u32_e32 v165, vcc, 0, v165, vcc
	global_load_dwordx4 v[164:167], v[164:165], off offset:384
	ds_read_b128 v[208:211], v130 offset:4640
	s_waitcnt lgkmcnt(4)
	v_mfma_f32_32x32x16_bf16 v[114:129], v[204:207], v[232:235], v[114:129]
	ds_read_b128 v[200:203], v130 offset:64
	ds_read_b128 v[212:215], v133 offset:18496
	s_waitcnt lgkmcnt(5)
	v_mfma_f32_32x32x16_bf16 v[98:113], v[204:207], v[236:239], v[98:113]
	ds_read_b128 v[216:219], v133 offset:23104
	s_waitcnt lgkmcnt(5)
	v_mfma_f32_32x32x16_bf16 v[82:97], v[204:207], v[240:243], v[82:97]
	ds_read_b128 v[224:227], v133 offset:27712
	s_waitcnt lgkmcnt(5)
	v_mfma_f32_32x32x16_bf16 v[66:81], v[204:207], v[244:247], v[66:81]
	ds_read_b128 v[228:231], v133 offset:32320
	s_waitcnt lgkmcnt(5)
	v_mfma_f32_32x32x16_bf16 v[50:65], v[208:211], v[232:235], v[50:65]
	v_lshl_add_u64 v[168:169], v[148:149], 0, s[18:19]
	v_add_co_u32_e32 v168, vcc, s43, v168
	s_nop 1
	v_addc_co_u32_e32 v169, vcc, 0, v169, vcc
	global_load_dwordx4 v[168:171], v[168:169], off offset:128
	v_mfma_f32_32x32x16_bf16 v[34:49], v[208:211], v[236:239], v[34:49]
	v_lshl_add_u64 v[172:173], v[148:149], 0, s[18:19]
	v_add_co_u32_e32 v172, vcc, s44, v172
	s_nop 1
	v_addc_co_u32_e32 v173, vcc, 0, v173, vcc
	global_load_dwordx4 v[172:175], v[172:173], off offset:128
	v_mfma_f32_32x32x16_bf16 v[18:33], v[208:211], v[240:243], v[18:33]
	v_lshl_add_u64 v[176:177], v[148:149], 0, s[18:19]
	v_add_co_u32_e32 v176, vcc, s45, v176
	s_nop 1
	v_addc_co_u32_e32 v177, vcc, 0, v177, vcc
	global_load_dwordx4 v[176:179], v[176:177], off offset:128
	v_mfma_f32_32x32x16_bf16 v[2:17], v[208:211], v[244:247], v[2:17]
	v_lshl_add_u64 v[180:181], v[148:149], 0, s[18:19]
	v_add_co_u32_e32 v180, vcc, s46, v180
	s_nop 1
	v_addc_co_u32_e32 v181, vcc, 0, v181, vcc
	global_load_dwordx4 v[180:183], v[180:181], off offset:128
	ds_read_b128 v[208:211], v130 offset:4672
	s_waitcnt lgkmcnt(4)
	v_mfma_f32_32x32x16_bf16 v[114:129], v[200:203], v[212:215], v[114:129]
	ds_read_b128 v[204:207], v130 offset:96
	ds_read_b128 v[232:235], v133 offset:18528
	s_waitcnt lgkmcnt(5)
	v_mfma_f32_32x32x16_bf16 v[98:113], v[200:203], v[216:219], v[98:113]
	ds_read_b128 v[236:239], v133 offset:23136
	s_waitcnt lgkmcnt(5)
	v_mfma_f32_32x32x16_bf16 v[82:97], v[200:203], v[224:227], v[82:97]
	ds_read_b128 v[240:243], v133 offset:27744
	s_waitcnt lgkmcnt(5)
	v_mfma_f32_32x32x16_bf16 v[66:81], v[200:203], v[228:231], v[66:81]
	ds_read_b128 v[244:247], v133 offset:32352
	s_waitcnt lgkmcnt(5)
	v_mfma_f32_32x32x16_bf16 v[50:65], v[208:211], v[212:215], v[50:65]
	v_lshl_add_u64 v[184:185], v[148:149], 0, s[18:19]
	v_add_co_u32_e32 v184, vcc, s47, v184
	s_nop 1
	v_addc_co_u32_e32 v185, vcc, 0, v185, vcc
	global_load_dwordx4 v[184:187], v[184:185], off offset:128
	v_mfma_f32_32x32x16_bf16 v[34:49], v[208:211], v[216:219], v[34:49]
	v_lshl_add_u64 v[188:189], v[148:149], 0, s[18:19]
	v_add_co_u32_e32 v188, vcc, s48, v188
	s_nop 1
	v_addc_co_u32_e32 v189, vcc, 0, v189, vcc
	global_load_dwordx4 v[188:191], v[188:189], off offset:128
	v_mfma_f32_32x32x16_bf16 v[18:33], v[208:211], v[224:227], v[18:33]
	v_lshl_add_u64 v[192:193], v[148:149], 0, s[18:19]
	v_add_co_u32_e32 v192, vcc, s49, v192
	s_nop 1
	v_addc_co_u32_e32 v193, vcc, 0, v193, vcc
	global_load_dwordx4 v[192:195], v[192:193], off offset:128
	v_mfma_f32_32x32x16_bf16 v[2:17], v[208:211], v[228:231], v[2:17]
	v_lshl_add_u64 v[196:197], v[148:149], 0, s[18:19]
	v_add_co_u32_e32 v196, vcc, s50, v196
	s_nop 1
	v_addc_co_u32_e32 v197, vcc, 0, v197, vcc
	global_load_dwordx4 v[196:199], v[196:197], off offset:128
	ds_read_b128 v[208:211], v130 offset:4704
	s_waitcnt lgkmcnt(4)
	v_mfma_f32_32x32x16_bf16 v[114:129], v[204:207], v[232:235], v[114:129]
	s_waitcnt lgkmcnt(3)
	v_mfma_f32_32x32x16_bf16 v[98:113], v[204:207], v[236:239], v[98:113]
	s_waitcnt lgkmcnt(2)
	v_mfma_f32_32x32x16_bf16 v[82:97], v[204:207], v[240:243], v[82:97]
	s_waitcnt lgkmcnt(1)
	v_mfma_f32_32x32x16_bf16 v[66:81], v[204:207], v[244:247], v[66:81]
	s_waitcnt lgkmcnt(0)
	v_mfma_f32_32x32x16_bf16 v[50:65], v[208:211], v[232:235], v[50:65]
	v_mfma_f32_32x32x16_bf16 v[34:49], v[208:211], v[236:239], v[34:49]
	v_mfma_f32_32x32x16_bf16 v[18:33], v[208:211], v[240:243], v[18:33]
	v_mfma_f32_32x32x16_bf16 v[2:17], v[208:211], v[244:247], v[2:17]
	s_setprio 0
	s_add_u32 s18, s18, 0x80
	s_addc_u32 s19, s19, 0
	s_cmpk_lg_i32 s18, 0x700
	s_barrier
; #define GW_LOAD(KOFF) GW_LOAD2(KOFF, 0)
;     ...
;   GW_LOAD(0)
;   GW_STORE()
;   __syncthreads();
;   const int nk = K >> 6;
;   const char* Ab = smem + (wm * 64 + (lane & 31)) * LSTR + (lane >> 5) * 16;
;   const char* Bb = smem + WTILE_A + (wn * 128 + (lane & 31)) * LSTR + (lane >> 5) * 16;
;   for (int kt = 0; kt < nk; ++kt) {
;     const int kn = (kt + 1 < nk) ? kt + 1 : kt;
;     GW_LOAD2(kn * 64, kn * bkstep)
;     __builtin_amdgcn_sched_barrier(0);
;     __builtin_amdgcn_s_setprio(1);
; #pragma unroll
;     for (int st = 0; st < 4; ++st) {
;       bf16x8 a0 = *(const bf16x8*)(Ab + st * 32);
;       bf16x8 a1 = *(const bf16x8*)(Ab + 32 * LSTR + st * 32);
;       bf16x8 b0 = *(const bf16x8*)(Bb + st * 32);
;       bf16x8 b1 = *(const bf16x8*)(Bb + 32 * LSTR + st * 32);
;       bf16x8 b2 = *(const bf16x8*)(Bb + 64 * LSTR + st * 32);
;       bf16x8 b3 = *(const bf16x8*)(Bb + 96 * LSTR + st * 32);
;       acc[0][0] = mfma32(a0, b0, acc[0][0]);
;       acc[0][1] = mfma32(a0, b1, acc[0][1]);
;       acc[0][2] = mfma32(a0, b2, acc[0][2]);
;       acc[0][3] = mfma32(a0, b3, acc[0][3]);
;       acc[1][0] = mfma32(a1, b0, acc[1][0]);
;       acc[1][1] = mfma32(a1, b1, acc[1][1]);
;       acc[1][2] = mfma32(a1, b2, acc[1][2]);
;       acc[1][3] = mfma32(a1, b3, acc[1][3]);
;     }
;     __builtin_amdgcn_s_setprio(0);
;     __builtin_amdgcn_sched_barrier(0);
;     __syncthreads();
;     GW_STORE()
;     __syncthreads();
	s_waitcnt vmcnt(11)
	ds_write_b128 v132, v[152:155]
	s_waitcnt vmcnt(10)
	ds_write_b128 v132, v[156:159] offset:4608
	s_waitcnt vmcnt(9)
	ds_write_b128 v132, v[160:163] offset:9216
	s_waitcnt vmcnt(8)
	ds_write_b128 v132, v[164:167] offset:13824
	s_waitcnt vmcnt(7)
	ds_write_b128 v132, v[168:171] offset:18432
	s_waitcnt vmcnt(6)
	ds_write_b128 v132, v[172:175] offset:23040
	s_waitcnt vmcnt(5)
	ds_write_b128 v132, v[176:179] offset:27648
	s_waitcnt vmcnt(4)
	ds_write_b128 v132, v[180:183] offset:32256
	s_waitcnt vmcnt(3)
	ds_write_b128 v132, v[184:187] offset:36864
	s_waitcnt vmcnt(2)
	ds_write_b128 v132, v[188:191] offset:41472
	s_waitcnt vmcnt(1)
	ds_write_b128 v132, v[192:195] offset:46080
	s_waitcnt vmcnt(0)
	ds_write_b128 v132, v[196:199] offset:50688
	s_waitcnt lgkmcnt(0)
	s_barrier
	s_cbranch_scc1 .LBB0_707
	s_setprio 1
	ds_read_b128 v[200:203], v130 offset:0
	ds_read_b128 v[212:215], v133 offset:18432
	ds_read_b128 v[216:219], v133 offset:23040
	ds_read_b128 v[224:227], v133 offset:27648
	ds_read_b128 v[228:231], v133 offset:32256
	ds_read_b128 v[208:211], v130 offset:4608
	s_waitcnt lgkmcnt(4)
	v_mfma_f32_32x32x16_bf16 v[114:129], v[200:203], v[212:215], v[114:129]
	ds_read_b128 v[204:207], v130 offset:32
	ds_read_b128 v[232:235], v133 offset:18464
	s_waitcnt lgkmcnt(5)
	v_mfma_f32_32x32x16_bf16 v[98:113], v[200:203], v[216:219], v[98:113]
	ds_read_b128 v[236:239], v133 offset:23072
	s_waitcnt lgkmcnt(5)
	v_mfma_f32_32x32x16_bf16 v[82:97], v[200:203], v[224:227], v[82:97]
	ds_read_b128 v[240:243], v133 offset:27680
	s_waitcnt lgkmcnt(5)
	v_mfma_f32_32x32x16_bf16 v[66:81], v[200:203], v[228:231], v[66:81]
	ds_read_b128 v[244:247], v133 offset:32288
	s_waitcnt lgkmcnt(5)
	v_mfma_f32_32x32x16_bf16 v[50:65], v[208:211], v[212:215], v[50:65]
	v_lshl_add_u64 v[152:153], v[146:147], 0, s[18:19]
	v_add_co_u32_e32 v152, vcc, s39, v152
	s_nop 1
	v_addc_co_u32_e32 v153, vcc, 0, v153, vcc
	global_load_dwordx4 v[152:155], v[152:153], off offset:384
	v_mfma_f32_32x32x16_bf16 v[34:49], v[208:211], v[216:219], v[34:49]
	v_lshl_add_u64 v[156:157], v[146:147], 0, s[18:19]
	v_add_co_u32_e32 v156, vcc, s40, v156
	s_nop 1
	v_addc_co_u32_e32 v157, vcc, 0, v157, vcc
	global_load_dwordx4 v[156:159], v[156:157], off offset:384
	v_mfma_f32_32x32x16_bf16 v[18:33], v[208:211], v[224:227], v[18:33]
	v_lshl_add_u64 v[160:161], v[146:147], 0, s[18:19]
	v_add_co_u32_e32 v160, vcc, s41, v160
	s_nop 1
	v_addc_co_u32_e32 v161, vcc, 0, v161, vcc
	global_load_dwordx4 v[160:163], v[160:161], off offset:384
	v_mfma_f32_32x32x16_bf16 v[2:17], v[208:211], v[228:231], v[2:17]
	v_lshl_add_u64 v[164:165], v[146:147], 0, s[18:19]
	v_add_co_u32_e32 v164, vcc, s42, v164
	s_nop 1
	v_addc_co_u32_e32 v165, vcc, 0, v165, vcc
	global_load_dwordx4 v[164:167], v[164:165], off offset:384
	ds_read_b128 v[208:211], v130 offset:4640
	s_waitcnt lgkmcnt(4)
	v_mfma_f32_32x32x16_bf16 v[114:129], v[204:207], v[232:235], v[114:129]
	ds_read_b128 v[200:203], v130 offset:64
	ds_read_b128 v[212:215], v133 offset:18496
	s_waitcnt lgkmcnt(5)
	v_mfma_f32_32x32x16_bf16 v[98:113], v[204:207], v[236:239], v[98:113]
	ds_read_b128 v[216:219], v133 offset:23104
	s_waitcnt lgkmcnt(5)
	v_mfma_f32_32x32x16_bf16 v[82:97], v[204:207], v[240:243], v[82:97]
	ds_read_b128 v[224:227], v133 offset:27712
	s_waitcnt lgkmcnt(5)
	v_mfma_f32_32x32x16_bf16 v[66:81], v[204:207], v[244:247], v[66:81]
	ds_read_b128 v[228:231], v133 offset:32320
	s_waitcnt lgkmcnt(5)
	v_mfma_f32_32x32x16_bf16 v[50:65], v[208:211], v[232:235], v[50:65]
	v_lshl_add_u64 v[168:169], v[148:149], 0, s[18:19]
	v_add_co_u32_e32 v168, vcc, s43, v168
	s_nop 1
	v_addc_co_u32_e32 v169, vcc, 0, v169, vcc
	global_load_dwordx4 v[168:171], v[168:169], off offset:128
	v_mfma_f32_32x32x16_bf16 v[34:49], v[208:211], v[236:239], v[34:49]
	v_lshl_add_u64 v[172:173], v[148:149], 0, s[18:19]
	v_add_co_u32_e32 v172, vcc, s44, v172
	s_nop 1
	v_addc_co_u32_e32 v173, vcc, 0, v173, vcc
	global_load_dwordx4 v[172:175], v[172:173], off offset:128
	v_mfma_f32_32x32x16_bf16 v[18:33], v[208:211], v[240:243], v[18:33]
	v_lshl_add_u64 v[176:177], v[148:149], 0, s[18:19]
	v_add_co_u32_e32 v176, vcc, s45, v176
	s_nop 1
	v_addc_co_u32_e32 v177, vcc, 0, v177, vcc
	global_load_dwordx4 v[176:179], v[176:177], off offset:128
	v_mfma_f32_32x32x16_bf16 v[2:17], v[208:211], v[244:247], v[2:17]
	v_lshl_add_u64 v[180:181], v[148:149], 0, s[18:19]
	v_add_co_u32_e32 v180, vcc, s46, v180
	s_nop 1
	v_addc_co_u32_e32 v181, vcc, 0, v181, vcc
	global_load_dwordx4 v[180:183], v[180:181], off offset:128
	ds_read_b128 v[208:211], v130 offset:4672
	s_waitcnt lgkmcnt(4)
	v_mfma_f32_32x32x16_bf16 v[114:129], v[200:203], v[212:215], v[114:129]
	ds_read_b128 v[204:207], v130 offset:96
	ds_read_b128 v[232:235], v133 offset:18528
	s_waitcnt lgkmcnt(5)
	v_mfma_f32_32x32x16_bf16 v[98:113], v[200:203], v[216:219], v[98:113]
	ds_read_b128 v[236:239], v133 offset:23136
	s_waitcnt lgkmcnt(5)
	v_mfma_f32_32x32x16_bf16 v[82:97], v[200:203], v[224:227], v[82:97]
	ds_read_b128 v[240:243], v133 offset:27744
	s_waitcnt lgkmcnt(5)
	v_mfma_f32_32x32x16_bf16 v[66:81], v[200:203], v[228:231], v[66:81]
	ds_read_b128 v[244:247], v133 offset:32352
	s_waitcnt lgkmcnt(5)
;     ...
; #pragma unroll
;     for (int st = 0; st < 4; ++st) {
;       bf16x8 a0 = *(const bf16x8*)(Ab + st * 32);
;       bf16x8 a1 = *(const bf16x8*)(Ab + 32 * LSTR + st * 32);
;       bf16x8 b0 = *(const bf16x8*)(Bb + st * 32);
;       bf16x8 b1 = *(const bf16x8*)(Bb + 32 * LSTR + st * 32);
;       bf16x8 b2 = *(const bf16x8*)(Bb + 64 * LSTR + st * 32);
;       bf16x8 b3 = *(const bf16x8*)(Bb + 96 * LSTR + st * 32);
;       acc[0][0] = mfma32(a0, b0, acc[0][0]);
;       acc[0][1] = mfma32(a0, b1, acc[0][1]);
;       acc[0][2] = mfma32(a0, b2, acc[0][2]);
;       acc[0][3] = mfma32(a0, b3, acc[0][3]);
;       acc[1][0] = mfma32(a1, b0, acc[1][0]);
;       acc[1][1] = mfma32(a1, b1, acc[1][1]);
;       acc[1][2] = mfma32(a1, b2, acc[1][2]);
;       acc[1][3] = mfma32(a1, b3, acc[1][3]);
;     }
;     __builtin_amdgcn_s_setprio(0);
;     __builtin_amdgcn_sched_barrier(0);
;     __syncthreads();
;     GW_STORE()
;     __syncthreads();
	v_mfma_f32_32x32x16_bf16 v[50:65], v[208:211], v[212:215], v[50:65]
	v_lshl_add_u64 v[184:185], v[148:149], 0, s[18:19]
	v_add_co_u32_e32 v184, vcc, s47, v184
	s_nop 1
	v_addc_co_u32_e32 v185, vcc, 0, v185, vcc
	global_load_dwordx4 v[184:187], v[184:185], off offset:128
	v_mfma_f32_32x32x16_bf16 v[34:49], v[208:211], v[216:219], v[34:49]
	v_lshl_add_u64 v[188:189], v[148:149], 0, s[18:19]
	v_add_co_u32_e32 v188, vcc, s48, v188
	s_nop 1
	v_addc_co_u32_e32 v189, vcc, 0, v189, vcc
	global_load_dwordx4 v[188:191], v[188:189], off offset:128
	v_mfma_f32_32x32x16_bf16 v[18:33], v[208:211], v[224:227], v[18:33]
	v_lshl_add_u64 v[192:193], v[148:149], 0, s[18:19]
	v_add_co_u32_e32 v192, vcc, s49, v192
	s_nop 1
	v_addc_co_u32_e32 v193, vcc, 0, v193, vcc
	global_load_dwordx4 v[192:195], v[192:193], off offset:128
	v_mfma_f32_32x32x16_bf16 v[2:17], v[208:211], v[228:231], v[2:17]
	v_lshl_add_u64 v[196:197], v[148:149], 0, s[18:19]
	v_add_co_u32_e32 v196, vcc, s50, v196
	s_nop 1
	v_addc_co_u32_e32 v197, vcc, 0, v197, vcc
	global_load_dwordx4 v[196:199], v[196:197], off offset:128
	ds_read_b128 v[208:211], v130 offset:4704
	s_waitcnt lgkmcnt(4)
	v_mfma_f32_32x32x16_bf16 v[114:129], v[204:207], v[232:235], v[114:129]
	s_waitcnt lgkmcnt(3)
	v_mfma_f32_32x32x16_bf16 v[98:113], v[204:207], v[236:239], v[98:113]
	s_waitcnt lgkmcnt(2)
	v_mfma_f32_32x32x16_bf16 v[82:97], v[204:207], v[240:243], v[82:97]
	s_waitcnt lgkmcnt(1)
	v_mfma_f32_32x32x16_bf16 v[66:81], v[204:207], v[244:247], v[66:81]
	s_waitcnt lgkmcnt(0)
	v_mfma_f32_32x32x16_bf16 v[50:65], v[208:211], v[232:235], v[50:65]
	v_mfma_f32_32x32x16_bf16 v[34:49], v[208:211], v[236:239], v[34:49]
	v_mfma_f32_32x32x16_bf16 v[18:33], v[208:211], v[240:243], v[18:33]
	v_mfma_f32_32x32x16_bf16 v[2:17], v[208:211], v[244:247], v[2:17]
	s_setprio 0
	s_add_u32 s18, s18, 0x80
	s_addc_u32 s19, s19, 0
	s_barrier
	s_waitcnt vmcnt(11)
	ds_write_b128 v132, v[152:155]
	s_waitcnt vmcnt(10)
	ds_write_b128 v132, v[156:159] offset:4608
	s_waitcnt vmcnt(9)
	ds_write_b128 v132, v[160:163] offset:9216
	s_waitcnt vmcnt(8)
	ds_write_b128 v132, v[164:167] offset:13824
	s_waitcnt vmcnt(7)
	ds_write_b128 v132, v[168:171] offset:18432
	s_waitcnt vmcnt(6)
	ds_write_b128 v132, v[172:175] offset:23040
	s_waitcnt vmcnt(5)
	ds_write_b128 v132, v[176:179] offset:27648
	s_waitcnt vmcnt(4)
	ds_write_b128 v132, v[180:183] offset:32256
	s_waitcnt vmcnt(3)
	ds_write_b128 v132, v[184:187] offset:36864
	s_waitcnt vmcnt(2)
	ds_write_b128 v132, v[188:191] offset:41472
	s_waitcnt vmcnt(1)
	ds_write_b128 v132, v[192:195] offset:46080
	s_waitcnt vmcnt(0)
	ds_write_b128 v132, v[196:199] offset:50688
	s_waitcnt lgkmcnt(0)
	s_barrier
;     ...
; #pragma unroll
;     for (int st = 0; st < 4; ++st) {
;       bf16x8 a0 = *(const bf16x8*)(Ab + st * 32);
;       bf16x8 a1 = *(const bf16x8*)(Ab + 32 * LSTR + st * 32);
;       bf16x8 b0 = *(const bf16x8*)(Bb + st * 32);
;       bf16x8 b1 = *(const bf16x8*)(Bb + 32 * LSTR + st * 32);
;       bf16x8 b2 = *(const bf16x8*)(Bb + 64 * LSTR + st * 32);
;       bf16x8 b3 = *(const bf16x8*)(Bb + 96 * LSTR + st * 32);
;       acc[0][0] = mfma32(a0, b0, acc[0][0]);
;       acc[0][1] = mfma32(a0, b1, acc[0][1]);
;       acc[0][2] = mfma32(a0, b2, acc[0][2]);
;       acc[0][3] = mfma32(a0, b3, acc[0][3]);
;       acc[1][0] = mfma32(a1, b0, acc[1][0]);
;       acc[1][1] = mfma32(a1, b1, acc[1][1]);
;       acc[1][2] = mfma32(a1, b2, acc[1][2]);
;       acc[1][3] = mfma32(a1, b3, acc[1][3]);
;     }
;     __builtin_amdgcn_s_setprio(0);
	v_add_co_u32_e32 v160, vcc, 0x10000, v136
	s_nop 0
	s_nop 0
	s_nop 0
	v_addc_co_u32_e32 v161, vcc, 0, v137, vcc
	v_add_co_u32_e32 v164, vcc, 0x20000, v136
	s_nop 0
	v_addc_co_u32_e32 v165, vcc, 0, v137, vcc
	v_add_co_u32_e32 v168, vcc, 0x30000, v136
	s_lshl_b64 s[16:17], s[16:17], 7
	s_nop 0
	v_addc_co_u32_e32 v169, vcc, 0, v137, vcc
	v_add_co_u32_e32 v172, vcc, 0x40000, v136
	s_nop 0
	v_addc_co_u32_e32 v173, vcc, 0, v137, vcc
	v_add_co_u32_e32 v176, vcc, 0x50000, v136
	s_mov_b32 s15, 0
	s_nop 0
	v_addc_co_u32_e32 v177, vcc, 0, v137, vcc
	v_add_co_u32_e32 v180, vcc, 0x60000, v136
	s_nop 0
	v_addc_co_u32_e32 v181, vcc, 0, v137, vcc
	v_add_co_u32_e32 v136, vcc, 0x70000, v136
	s_nop 1
	v_addc_co_u32_e32 v137, vcc, 0, v137, vcc
	s_nop 0
	s_setprio 1
	ds_read_b128 v[188:191], v130 offset:0
	ds_read_b128 v[200:203], v133 offset:18432
	ds_read_b128 v[204:207], v133 offset:23040
	ds_read_b128 v[208:211], v133 offset:27648
	ds_read_b128 v[212:215], v133 offset:32256
	ds_read_b128 v[196:199], v130 offset:4608
	s_waitcnt lgkmcnt(4)
	v_mfma_f32_32x32x16_bf16 v[114:129], v[188:191], v[200:203], v[114:129]
	ds_read_b128 v[192:195], v130 offset:32
	ds_read_b128 v[216:219], v133 offset:18464
	s_waitcnt lgkmcnt(5)
	v_mfma_f32_32x32x16_bf16 v[98:113], v[188:191], v[204:207], v[98:113]
	ds_read_b128 v[224:227], v133 offset:23072
	s_waitcnt lgkmcnt(5)
	v_mfma_f32_32x32x16_bf16 v[82:97], v[188:191], v[208:211], v[82:97]
	ds_read_b128 v[228:231], v133 offset:27680
	s_waitcnt lgkmcnt(5)
	v_mfma_f32_32x32x16_bf16 v[66:81], v[188:191], v[212:215], v[66:81]
	ds_read_b128 v[232:235], v133 offset:32288
	s_waitcnt lgkmcnt(5)
	v_mfma_f32_32x32x16_bf16 v[50:65], v[196:199], v[200:203], v[50:65]
	v_mfma_f32_32x32x16_bf16 v[34:49], v[196:199], v[204:207], v[34:49]
	v_mfma_f32_32x32x16_bf16 v[18:33], v[196:199], v[208:211], v[18:33]
	v_mfma_f32_32x32x16_bf16 v[2:17], v[196:199], v[212:215], v[2:17]
	ds_read_b128 v[196:199], v130 offset:4640
	s_waitcnt lgkmcnt(4)
	v_mfma_f32_32x32x16_bf16 v[114:129], v[192:195], v[216:219], v[114:129]
	ds_read_b128 v[188:191], v130 offset:64
	ds_read_b128 v[200:203], v133 offset:18496
	s_waitcnt lgkmcnt(5)
	v_mfma_f32_32x32x16_bf16 v[98:113], v[192:195], v[224:227], v[98:113]
	ds_read_b128 v[204:207], v133 offset:23104
	s_waitcnt lgkmcnt(5)
	v_mfma_f32_32x32x16_bf16 v[82:97], v[192:195], v[228:231], v[82:97]
	ds_read_b128 v[208:211], v133 offset:27712
	s_waitcnt lgkmcnt(5)
	v_mfma_f32_32x32x16_bf16 v[66:81], v[192:195], v[232:235], v[66:81]
	ds_read_b128 v[212:215], v133 offset:32320
	s_waitcnt lgkmcnt(5)
	v_mfma_f32_32x32x16_bf16 v[50:65], v[196:199], v[216:219], v[50:65]
	v_mfma_f32_32x32x16_bf16 v[34:49], v[196:199], v[224:227], v[34:49]
	v_mfma_f32_32x32x16_bf16 v[18:33], v[196:199], v[228:231], v[18:33]
	v_mfma_f32_32x32x16_bf16 v[2:17], v[196:199], v[232:235], v[2:17]
	ds_read_b128 v[196:199], v130 offset:4672
	s_waitcnt lgkmcnt(4)
	v_mfma_f32_32x32x16_bf16 v[114:129], v[188:191], v[200:203], v[114:129]
	ds_read_b128 v[192:195], v130 offset:96
	ds_read_b128 v[216:219], v133 offset:18528
	s_waitcnt lgkmcnt(5)
	v_mfma_f32_32x32x16_bf16 v[98:113], v[188:191], v[204:207], v[98:113]
	ds_read_b128 v[224:227], v133 offset:23136
	s_waitcnt lgkmcnt(5)
	v_mfma_f32_32x32x16_bf16 v[82:97], v[188:191], v[208:211], v[82:97]
	ds_read_b128 v[228:231], v133 offset:27744
	s_waitcnt lgkmcnt(5)
	v_mfma_f32_32x32x16_bf16 v[66:81], v[188:191], v[212:215], v[66:81]
	ds_read_b128 v[232:235], v133 offset:32352
	s_waitcnt lgkmcnt(5)
	v_mfma_f32_32x32x16_bf16 v[50:65], v[196:199], v[200:203], v[50:65]
	v_mfma_f32_32x32x16_bf16 v[34:49], v[196:199], v[204:207], v[34:49]
	v_mfma_f32_32x32x16_bf16 v[18:33], v[196:199], v[208:211], v[18:33]
	v_mfma_f32_32x32x16_bf16 v[2:17], v[196:199], v[212:215], v[2:17]
	ds_read_b128 v[196:199], v130 offset:4704
	s_waitcnt lgkmcnt(4)
	v_mfma_f32_32x32x16_bf16 v[114:129], v[192:195], v[216:219], v[114:129]
	s_waitcnt lgkmcnt(3)
	v_mfma_f32_32x32x16_bf16 v[98:113], v[192:195], v[224:227], v[98:113]
	s_waitcnt lgkmcnt(2)
	v_mfma_f32_32x32x16_bf16 v[82:97], v[192:195], v[228:231], v[82:97]
	s_waitcnt lgkmcnt(1)
	v_mfma_f32_32x32x16_bf16 v[66:81], v[192:195], v[232:235], v[66:81]
	s_waitcnt lgkmcnt(0)
	v_mfma_f32_32x32x16_bf16 v[50:65], v[196:199], v[216:219], v[50:65]
	v_mfma_f32_32x32x16_bf16 v[34:49], v[196:199], v[224:227], v[34:49]
	v_mfma_f32_32x32x16_bf16 v[18:33], v[196:199], v[228:231], v[18:33]
	v_mfma_f32_32x32x16_bf16 v[2:17], v[196:199], v[232:235], v[2:17]
	s_setprio 0
	s_mov_b64 s[18:19], -1
	s_barrier
	s_waitcnt lgkmcnt(0)

;     ...
;   for (int kt = 0; kt < nk; ++kt) {
;     const int kn = (kt + 1 < nk) ? kt + 1 : kt;
;     GW_LOAD2(kn * 64, kn * bkstep)
;     __builtin_amdgcn_sched_barrier(0);
;     __builtin_amdgcn_s_setprio(1);
; #pragma unroll
;     for (int st = 0; st < 4; ++st) {
;       bf16x8 a0 = *(const bf16x8*)(Ab + st * 32);
;       bf16x8 a1 = *(const bf16x8*)(Ab + 32 * LSTR + st * 32);
;       bf16x8 b0 = *(const bf16x8*)(Bb + st * 32);
;       bf16x8 b1 = *(const bf16x8*)(Bb + 32 * LSTR + st * 32);
;       bf16x8 b2 = *(const bf16x8*)(Bb + 64 * LSTR + st * 32);
;       bf16x8 b3 = *(const bf16x8*)(Bb + 96 * LSTR + st * 32);
;       acc[0][0] = mfma32(a0, b0, acc[0][0]);
;       acc[0][1] = mfma32(a0, b1, acc[0][1]);
;       acc[0][2] = mfma32(a0, b2, acc[0][2]);
;       acc[0][3] = mfma32(a0, b3, acc[0][3]);
;       acc[1][0] = mfma32(a1, b0, acc[1][0]);
;       acc[1][1] = mfma32(a1, b1, acc[1][1]);
;       acc[1][2] = mfma32(a1, b2, acc[1][2]);
;       acc[1][3] = mfma32(a1, b3, acc[1][3]);
;     }
;     __builtin_amdgcn_s_setprio(0);
;     __builtin_amdgcn_sched_barrier(0);
.LBB0_1035:
	s_setprio 1
	ds_read_b128 v[206:209], v133 offset:0
	ds_read_b128 v[218:221], v156 offset:18432
	ds_read_b128 v[224:227], v156 offset:23040
	ds_read_b128 v[228:231], v156 offset:27648
	ds_read_b128 v[232:235], v156 offset:32256
	ds_read_b128 v[214:217], v133 offset:4608
	s_waitcnt lgkmcnt(4)
	v_mfma_f32_32x32x16_bf16 v[114:129], v[206:209], v[218:221], v[114:129]
	ds_read_b128 v[210:213], v133 offset:32
	ds_read_b128 v[236:239], v156 offset:18464
	s_waitcnt lgkmcnt(5)
	v_mfma_f32_32x32x16_bf16 v[98:113], v[206:209], v[224:227], v[98:113]
	ds_read_b128 v[240:243], v156 offset:23072
	s_waitcnt lgkmcnt(5)
	v_mfma_f32_32x32x16_bf16 v[82:97], v[206:209], v[228:231], v[82:97]
	ds_read_b128 v[244:247], v156 offset:27680
	s_waitcnt lgkmcnt(5)
	v_mfma_f32_32x32x16_bf16 v[66:81], v[206:209], v[232:235], v[66:81]
	ds_read_b128 v[248:251], v156 offset:32288
	s_waitcnt lgkmcnt(5)
	v_mfma_f32_32x32x16_bf16 v[50:65], v[214:217], v[218:221], v[50:65]
	v_lshl_add_u64 v[158:159], v[148:149], 0, v[130:131]
	global_load_dwordx4 v[158:161], v[158:159], off
	v_mfma_f32_32x32x16_bf16 v[34:49], v[214:217], v[224:227], v[34:49]
	v_lshl_add_u64 v[162:163], v[150:151], 0, v[130:131]
	global_load_dwordx4 v[162:165], v[162:163], off
	v_mfma_f32_32x32x16_bf16 v[18:33], v[214:217], v[228:231], v[18:33]
	v_lshl_add_u64 v[166:167], v[152:153], 0, v[130:131]
	global_load_dwordx4 v[166:169], v[166:167], off
	v_mfma_f32_32x32x16_bf16 v[2:17], v[214:217], v[232:235], v[2:17]
	v_lshl_add_u64 v[170:171], v[154:155], 0, v[130:131]
	global_load_dwordx4 v[170:173], v[170:171], off
	ds_read_b128 v[214:217], v133 offset:4640
	s_waitcnt lgkmcnt(4)
	v_mfma_f32_32x32x16_bf16 v[114:129], v[210:213], v[236:239], v[114:129]
	ds_read_b128 v[206:209], v133 offset:64
	ds_read_b128 v[218:221], v156 offset:18496
	s_waitcnt lgkmcnt(5)
	v_mfma_f32_32x32x16_bf16 v[98:113], v[210:213], v[240:243], v[98:113]
	ds_read_b128 v[224:227], v156 offset:23104
	s_waitcnt lgkmcnt(5)
	v_mfma_f32_32x32x16_bf16 v[82:97], v[210:213], v[244:247], v[82:97]
	ds_read_b128 v[228:231], v156 offset:27712
	s_waitcnt lgkmcnt(5)
	v_mfma_f32_32x32x16_bf16 v[66:81], v[210:213], v[248:251], v[66:81]
	ds_read_b128 v[232:235], v156 offset:32320
	s_waitcnt lgkmcnt(5)
	v_mfma_f32_32x32x16_bf16 v[50:65], v[214:217], v[236:239], v[50:65]
	v_lshl_add_u64 v[174:175], v[146:147], 0, v[130:131]
	v_add_co_u32_e32 v174, vcc, s35, v174
	s_nop 1
	v_addc_co_u32_e32 v175, vcc, 0, v175, vcc
	global_load_dwordx4 v[174:177], v[174:175], off offset:-4096
	v_mfma_f32_32x32x16_bf16 v[34:49], v[214:217], v[240:243], v[34:49]
	v_lshl_add_u64 v[178:179], v[146:147], 0, v[130:131]
	v_add_co_u32_e32 v178, vcc, s35, v178
	s_nop 1
	v_addc_co_u32_e32 v179, vcc, 0, v179, vcc
	global_load_dwordx4 v[178:181], v[178:179], off
	v_mfma_f32_32x32x16_bf16 v[18:33], v[214:217], v[244:247], v[18:33]
	v_lshl_add_u64 v[182:183], v[146:147], 0, v[130:131]
	v_add_co_u32_e32 v182, vcc, s36, v182
	s_nop 1
	v_addc_co_u32_e32 v183, vcc, 0, v183, vcc
	global_load_dwordx4 v[182:185], v[182:183], off offset:-4096
	v_mfma_f32_32x32x16_bf16 v[2:17], v[214:217], v[248:251], v[2:17]
	v_lshl_add_u64 v[186:187], v[146:147], 0, v[130:131]
	v_add_co_u32_e32 v186, vcc, s36, v186
	s_nop 1
	v_addc_co_u32_e32 v187, vcc, 0, v187, vcc
	global_load_dwordx4 v[186:189], v[186:187], off
	ds_read_b128 v[214:217], v133 offset:4672
	s_waitcnt lgkmcnt(4)
	v_mfma_f32_32x32x16_bf16 v[114:129], v[206:209], v[218:221], v[114:129]
	ds_read_b128 v[210:213], v133 offset:96
	ds_read_b128 v[236:239], v156 offset:18528
	s_waitcnt lgkmcnt(5)
	v_mfma_f32_32x32x16_bf16 v[98:113], v[206:209], v[224:227], v[98:113]
	ds_read_b128 v[240:243], v156 offset:23136
	s_waitcnt lgkmcnt(5)
	v_mfma_f32_32x32x16_bf16 v[82:97], v[206:209], v[228:231], v[82:97]
	ds_read_b128 v[244:247], v156 offset:27744
	s_waitcnt lgkmcnt(5)
	v_mfma_f32_32x32x16_bf16 v[66:81], v[206:209], v[232:235], v[66:81]
	ds_read_b128 v[248:251], v156 offset:32352
	s_waitcnt lgkmcnt(5)
	v_mfma_f32_32x32x16_bf16 v[50:65], v[214:217], v[218:221], v[50:65]
	v_lshl_add_u64 v[190:191], v[146:147], 0, v[130:131]
	v_add_co_u32_e32 v190, vcc, s37, v190
	s_nop 1
	v_addc_co_u32_e32 v191, vcc, 0, v191, vcc
	global_load_dwordx4 v[190:193], v[190:191], off offset:-4096
	v_mfma_f32_32x32x16_bf16 v[34:49], v[214:217], v[224:227], v[34:49]
	v_lshl_add_u64 v[194:195], v[146:147], 0, v[130:131]
	v_add_co_u32_e32 v194, vcc, s37, v194
	s_nop 1
	v_addc_co_u32_e32 v195, vcc, 0, v195, vcc
	global_load_dwordx4 v[194:197], v[194:195], off
	v_mfma_f32_32x32x16_bf16 v[18:33], v[214:217], v[228:231], v[18:33]
	v_lshl_add_u64 v[198:199], v[146:147], 0, v[130:131]
	v_add_co_u32_e32 v198, vcc, s38, v198
	s_nop 1
	v_addc_co_u32_e32 v199, vcc, 0, v199, vcc
	global_load_dwordx4 v[198:201], v[198:199], off offset:-4096
	v_mfma_f32_32x32x16_bf16 v[2:17], v[214:217], v[232:235], v[2:17]
	v_lshl_add_u64 v[202:203], v[146:147], 0, v[130:131]
	v_add_co_u32_e32 v202, vcc, s38, v202
	s_nop 1
	v_addc_co_u32_e32 v203, vcc, 0, v203, vcc
	global_load_dwordx4 v[202:205], v[202:203], off
	ds_read_b128 v[214:217], v133 offset:4704
	s_waitcnt lgkmcnt(4)
	v_mfma_f32_32x32x16_bf16 v[114:129], v[210:213], v[236:239], v[114:129]
	s_waitcnt lgkmcnt(3)
	v_mfma_f32_32x32x16_bf16 v[98:113], v[210:213], v[240:243], v[98:113]
	s_waitcnt lgkmcnt(2)
	v_mfma_f32_32x32x16_bf16 v[82:97], v[210:213], v[244:247], v[82:97]
	s_waitcnt lgkmcnt(1)
	v_mfma_f32_32x32x16_bf16 v[66:81], v[210:213], v[248:251], v[66:81]
	s_waitcnt lgkmcnt(0)
	v_mfma_f32_32x32x16_bf16 v[50:65], v[214:217], v[236:239], v[50:65]
	v_mfma_f32_32x32x16_bf16 v[34:49], v[214:217], v[240:243], v[34:49]
	v_mfma_f32_32x32x16_bf16 v[18:33], v[214:217], v[244:247], v[18:33]
	v_mfma_f32_32x32x16_bf16 v[2:17], v[214:217], v[248:251], v[2:17]
	s_setprio 0
	s_add_i32 s41, s41, -1
	v_lshl_add_u64 v[146:147], v[146:147], 0, s[8:9]
	v_lshl_add_u64 v[148:149], v[148:149], 0, s[10:11]
	v_lshl_add_u64 v[150:151], v[150:151], 0, s[10:11]
	v_lshl_add_u64 v[152:153], v[152:153], 0, s[10:11]
	s_cmp_lg_u32 s41, 0
	v_lshl_add_u64 v[154:155], v[154:155], 0, s[10:11]
	s_barrier
; #define GW_LOAD(KOFF) GW_LOAD2(KOFF, 0)
;     ...
;   GW_LOAD(0)
;   GW_STORE()
;   __syncthreads();
;   const int nk = K >> 6;
;   const char* Ab = smem + (wm * 64 + (lane & 31)) * LSTR + (lane >> 5) * 16;
;   const char* Bb = smem + WTILE_A + (wn * 128 + (lane & 31)) * LSTR + (lane >> 5) * 16;
;   for (int kt = 0; kt < nk; ++kt) {
;     const int kn = (kt + 1 < nk) ? kt + 1 : kt;
;     GW_LOAD2(kn * 64, kn * bkstep)
;     __builtin_amdgcn_sched_barrier(0);
;     __builtin_amdgcn_s_setprio(1);
; #pragma unroll
;     for (int st = 0; st < 4; ++st) {
;       bf16x8 a0 = *(const bf16x8*)(Ab + st * 32);
;       bf16x8 a1 = *(const bf16x8*)(Ab + 32 * LSTR + st * 32);
;       bf16x8 b0 = *(const bf16x8*)(Bb + st * 32);
;       bf16x8 b1 = *(const bf16x8*)(Bb + 32 * LSTR + st * 32);
;       bf16x8 b2 = *(const bf16x8*)(Bb + 64 * LSTR + st * 32);
;       bf16x8 b3 = *(const bf16x8*)(Bb + 96 * LSTR + st * 32);
;       acc[0][0] = mfma32(a0, b0, acc[0][0]);
;       acc[0][1] = mfma32(a0, b1, acc[0][1]);
;       acc[0][2] = mfma32(a0, b2, acc[0][2]);
;       acc[0][3] = mfma32(a0, b3, acc[0][3]);
;       acc[1][0] = mfma32(a1, b0, acc[1][0]);
;       acc[1][1] = mfma32(a1, b1, acc[1][1]);
;       acc[1][2] = mfma32(a1, b2, acc[1][2]);
;       acc[1][3] = mfma32(a1, b3, acc[1][3]);
;     }
;     __builtin_amdgcn_s_setprio(0);
;     __builtin_amdgcn_sched_barrier(0);
;     __syncthreads();
;     GW_STORE()
;     __syncthreads();
	s_waitcnt vmcnt(11)
	ds_write_b128 v132, v[158:161]
	s_waitcnt vmcnt(10)
	ds_write_b128 v132, v[162:165] offset:4608
	s_waitcnt vmcnt(9)
	ds_write_b128 v132, v[166:169] offset:9216
	s_waitcnt vmcnt(8)
	ds_write_b128 v132, v[170:173] offset:13824
	s_waitcnt vmcnt(7)
	ds_write_b128 v132, v[174:177] offset:18432
	s_waitcnt vmcnt(6)
	ds_write_b128 v132, v[178:181] offset:23040
	s_waitcnt vmcnt(5)
	ds_write_b128 v132, v[182:185] offset:27648
	s_waitcnt vmcnt(4)
	ds_write_b128 v132, v[186:189] offset:32256
	s_waitcnt vmcnt(3)
	ds_write_b128 v132, v[190:193] offset:36864
	s_waitcnt vmcnt(2)
	ds_write_b128 v132, v[194:197] offset:41472
	s_waitcnt vmcnt(1)
	ds_write_b128 v132, v[198:201] offset:46080
	s_waitcnt vmcnt(0)
	ds_write_b128 v132, v[202:205] offset:50688
	s_waitcnt lgkmcnt(0)
	s_barrier
	s_cbranch_scc1 .LBB0_1035
	s_setprio 1
	ds_read_b128 v[206:209], v133 offset:0
	ds_read_b128 v[218:221], v156 offset:18432
	ds_read_b128 v[224:227], v156 offset:23040
	ds_read_b128 v[228:231], v156 offset:27648
	ds_read_b128 v[232:235], v156 offset:32256
	ds_read_b128 v[214:217], v133 offset:4608
	s_waitcnt lgkmcnt(4)
	v_mfma_f32_32x32x16_bf16 v[114:129], v[206:209], v[218:221], v[114:129]
	ds_read_b128 v[210:213], v133 offset:32
	ds_read_b128 v[236:239], v156 offset:18464
	s_waitcnt lgkmcnt(5)
	v_mfma_f32_32x32x16_bf16 v[98:113], v[206:209], v[224:227], v[98:113]
	ds_read_b128 v[240:243], v156 offset:23072
	s_waitcnt lgkmcnt(5)
	v_mfma_f32_32x32x16_bf16 v[82:97], v[206:209], v[228:231], v[82:97]
	ds_read_b128 v[244:247], v156 offset:27680
	s_waitcnt lgkmcnt(5)
	v_mfma_f32_32x32x16_bf16 v[66:81], v[206:209], v[232:235], v[66:81]
	ds_read_b128 v[248:251], v156 offset:32288
	s_waitcnt lgkmcnt(5)
	v_mfma_f32_32x32x16_bf16 v[50:65], v[214:217], v[218:221], v[50:65]
	v_lshl_add_u64 v[158:159], v[148:149], 0, v[130:131]
	global_load_dwordx4 v[158:161], v[158:159], off
	v_mfma_f32_32x32x16_bf16 v[34:49], v[214:217], v[224:227], v[34:49]
	v_lshl_add_u64 v[162:163], v[150:151], 0, v[130:131]
	global_load_dwordx4 v[162:165], v[162:163], off
	v_mfma_f32_32x32x16_bf16 v[18:33], v[214:217], v[228:231], v[18:33]
	v_lshl_add_u64 v[166:167], v[152:153], 0, v[130:131]
	global_load_dwordx4 v[166:169], v[166:167], off
	v_mfma_f32_32x32x16_bf16 v[2:17], v[214:217], v[232:235], v[2:17]
	v_lshl_add_u64 v[170:171], v[154:155], 0, v[130:131]
	global_load_dwordx4 v[170:173], v[170:171], off
	ds_read_b128 v[214:217], v133 offset:4640
	s_waitcnt lgkmcnt(4)
	v_mfma_f32_32x32x16_bf16 v[114:129], v[210:213], v[236:239], v[114:129]
	ds_read_b128 v[206:209], v133 offset:64
	ds_read_b128 v[218:221], v156 offset:18496
	s_waitcnt lgkmcnt(5)
	v_mfma_f32_32x32x16_bf16 v[98:113], v[210:213], v[240:243], v[98:113]
	ds_read_b128 v[224:227], v156 offset:23104
	s_waitcnt lgkmcnt(5)
	v_mfma_f32_32x32x16_bf16 v[82:97], v[210:213], v[244:247], v[82:97]
	ds_read_b128 v[228:231], v156 offset:27712
	s_waitcnt lgkmcnt(5)
	v_mfma_f32_32x32x16_bf16 v[66:81], v[210:213], v[248:251], v[66:81]
	ds_read_b128 v[232:235], v156 offset:32320
	s_waitcnt lgkmcnt(5)
	v_mfma_f32_32x32x16_bf16 v[50:65], v[214:217], v[236:239], v[50:65]
	v_lshl_add_u64 v[174:175], v[146:147], 0, v[130:131]
	v_add_co_u32_e32 v174, vcc, s35, v174
	s_nop 1
	v_addc_co_u32_e32 v175, vcc, 0, v175, vcc
	global_load_dwordx4 v[174:177], v[174:175], off offset:-4096
	v_mfma_f32_32x32x16_bf16 v[34:49], v[214:217], v[240:243], v[34:49]
	v_lshl_add_u64 v[178:179], v[146:147], 0, v[130:131]
	v_add_co_u32_e32 v178, vcc, s35, v178
	s_nop 1
	v_addc_co_u32_e32 v179, vcc, 0, v179, vcc
	global_load_dwordx4 v[178:181], v[178:179], off
	v_mfma_f32_32x32x16_bf16 v[18:33], v[214:217], v[244:247], v[18:33]
	v_lshl_add_u64 v[182:183], v[146:147], 0, v[130:131]
	v_add_co_u32_e32 v182, vcc, s36, v182
	s_nop 1
	v_addc_co_u32_e32 v183, vcc, 0, v183, vcc
	global_load_dwordx4 v[182:185], v[182:183], off offset:-4096
	v_mfma_f32_32x32x16_bf16 v[2:17], v[214:217], v[248:251], v[2:17]
	v_lshl_add_u64 v[186:187], v[146:147], 0, v[130:131]
	v_add_co_u32_e32 v186, vcc, s36, v186
	s_nop 1
	v_addc_co_u32_e32 v187, vcc, 0, v187, vcc
	global_load_dwordx4 v[186:189], v[186:187], off
	ds_read_b128 v[214:217], v133 offset:4672
	s_waitcnt lgkmcnt(4)
	v_mfma_f32_32x32x16_bf16 v[114:129], v[206:209], v[218:221], v[114:129]
	ds_read_b128 v[210:213], v133 offset:96
	ds_read_b128 v[236:239], v156 offset:18528
	s_waitcnt lgkmcnt(5)
	v_mfma_f32_32x32x16_bf16 v[98:113], v[206:209], v[224:227], v[98:113]
	ds_read_b128 v[240:243], v156 offset:23136
	s_waitcnt lgkmcnt(5)
	v_mfma_f32_32x32x16_bf16 v[82:97], v[206:209], v[228:231], v[82:97]
	ds_read_b128 v[244:247], v156 offset:27744
	s_waitcnt lgkmcnt(5)
	v_mfma_f32_32x32x16_bf16 v[66:81], v[206:209], v[232:235], v[66:81]
	ds_read_b128 v[248:251], v156 offset:32352
	s_waitcnt lgkmcnt(5)
	v_mfma_f32_32x32x16_bf16 v[50:65], v[214:217], v[218:221], v[50:65]
	v_lshl_add_u64 v[190:191], v[146:147], 0, v[130:131]
	v_add_co_u32_e32 v190, vcc, s37, v190
	s_nop 1
	v_addc_co_u32_e32 v191, vcc, 0, v191, vcc
	global_load_dwordx4 v[190:193], v[190:191], off offset:-4096
	v_mfma_f32_32x32x16_bf16 v[34:49], v[214:217], v[224:227], v[34:49]
	v_lshl_add_u64 v[194:195], v[146:147], 0, v[130:131]
	v_add_co_u32_e32 v194, vcc, s37, v194
	s_nop 1
	v_addc_co_u32_e32 v195, vcc, 0, v195, vcc
	global_load_dwordx4 v[194:197], v[194:195], off
	v_mfma_f32_32x32x16_bf16 v[18:33], v[214:217], v[228:231], v[18:33]
	v_lshl_add_u64 v[198:199], v[146:147], 0, v[130:131]
	v_add_co_u32_e32 v198, vcc, s38, v198
	s_nop 1
	v_addc_co_u32_e32 v199, vcc, 0, v199, vcc
	global_load_dwordx4 v[198:201], v[198:199], off offset:-4096
	v_mfma_f32_32x32x16_bf16 v[2:17], v[214:217], v[232:235], v[2:17]
	v_lshl_add_u64 v[202:203], v[146:147], 0, v[130:131]
	v_add_co_u32_e32 v202, vcc, s38, v202
	s_nop 1
	v_addc_co_u32_e32 v203, vcc, 0, v203, vcc
	global_load_dwordx4 v[202:205], v[202:203], off
	ds_read_b128 v[214:217], v133 offset:4704
	s_waitcnt lgkmcnt(4)
	v_mfma_f32_32x32x16_bf16 v[114:129], v[210:213], v[236:239], v[114:129]
	s_waitcnt lgkmcnt(3)
	v_mfma_f32_32x32x16_bf16 v[98:113], v[210:213], v[240:243], v[98:113]
	s_waitcnt lgkmcnt(2)
	v_mfma_f32_32x32x16_bf16 v[82:97], v[210:213], v[244:247], v[82:97]
	s_waitcnt lgkmcnt(1)
	v_mfma_f32_32x32x16_bf16 v[66:81], v[210:213], v[248:251], v[66:81]
	s_waitcnt lgkmcnt(0)
	v_mfma_f32_32x32x16_bf16 v[50:65], v[214:217], v[236:239], v[50:65]
	v_mfma_f32_32x32x16_bf16 v[34:49], v[214:217], v[240:243], v[34:49]
	v_mfma_f32_32x32x16_bf16 v[18:33], v[214:217], v[244:247], v[18:33]
	v_mfma_f32_32x32x16_bf16 v[2:17], v[214:217], v[248:251], v[2:17]
	s_setprio 0
	v_lshl_add_u64 v[146:147], v[146:147], 0, s[8:9]
	v_lshl_add_u64 v[148:149], v[148:149], 0, s[10:11]
	v_lshl_add_u64 v[150:151], v[150:151], 0, s[10:11]
	v_lshl_add_u64 v[152:153], v[152:153], 0, s[10:11]
	v_lshl_add_u64 v[154:155], v[154:155], 0, s[10:11]
	s_barrier
; #define GW_LOAD(KOFF) GW_LOAD2(KOFF, 0)
;     ...
;   GW_LOAD(0)
;   GW_STORE()
;   __syncthreads();
;   const int nk = K >> 6;
;   const char* Ab = smem + (wm * 64 + (lane & 31)) * LSTR + (lane >> 5) * 16;
;   const char* Bb = smem + WTILE_A + (wn * 128 + (lane & 31)) * LSTR + (lane >> 5) * 16;
;   for (int kt = 0; kt < nk; ++kt) {
;     const int kn = (kt + 1 < nk) ? kt + 1 : kt;
;     GW_LOAD2(kn * 64, kn * bkstep)
;     __builtin_amdgcn_sched_barrier(0);
;     __builtin_amdgcn_s_setprio(1);
; #pragma unroll
;     for (int st = 0; st < 4; ++st) {
;       bf16x8 a0 = *(const bf16x8*)(Ab + st * 32);
;       bf16x8 a1 = *(const bf16x8*)(Ab + 32 * LSTR + st * 32);
;       bf16x8 b0 = *(const bf16x8*)(Bb + st * 32);
;       bf16x8 b1 = *(const bf16x8*)(Bb + 32 * LSTR + st * 32);
;       bf16x8 b2 = *(const bf16x8*)(Bb + 64 * LSTR + st * 32);
;       bf16x8 b3 = *(const bf16x8*)(Bb + 96 * LSTR + st * 32);
;       acc[0][0] = mfma32(a0, b0, acc[0][0]);
;       acc[0][1] = mfma32(a0, b1, acc[0][1]);
;       acc[0][2] = mfma32(a0, b2, acc[0][2]);
;       acc[0][3] = mfma32(a0, b3, acc[0][3]);
;       acc[1][0] = mfma32(a1, b0, acc[1][0]);
;       acc[1][1] = mfma32(a1, b1, acc[1][1]);
;       acc[1][2] = mfma32(a1, b2, acc[1][2]);
;       acc[1][3] = mfma32(a1, b3, acc[1][3]);
;     }
;     __builtin_amdgcn_s_setprio(0);
; __device__ __forceinline__ void expert1_tile(const Params& P, int e, int mt, int ntw, char* smem) {
;     ...
;   const int r = 32 * wave + (lane & 31), part = lane >> 5;
; #pragma unroll 1
;   for (int h = 0; h < 2; ++h) {
;     wide_acc_to_lds(acc, cs, h);
;     u16* dst = WSP(u16, OFF_HID) + ((size_t)e * EROWS + mt * 128 + r) * 2048 + (ntw * 2 + h) * 64 + part * 32;
	s_waitcnt vmcnt(11)
	ds_write_b128 v132, v[158:161]
	s_waitcnt vmcnt(10)
	ds_write_b128 v132, v[162:165] offset:4608
	s_waitcnt vmcnt(9)
	ds_write_b128 v132, v[166:169] offset:9216
	s_waitcnt vmcnt(8)
	ds_write_b128 v132, v[170:173] offset:13824
	s_waitcnt vmcnt(7)
	ds_write_b128 v132, v[174:177] offset:18432
	s_waitcnt vmcnt(6)
	ds_write_b128 v132, v[178:181] offset:23040
	s_waitcnt vmcnt(5)
	ds_write_b128 v132, v[182:185] offset:27648
	s_waitcnt vmcnt(4)
	ds_write_b128 v132, v[186:189] offset:32256
	s_waitcnt vmcnt(3)
	ds_write_b128 v132, v[190:193] offset:36864
	s_waitcnt vmcnt(2)
	ds_write_b128 v132, v[194:197] offset:41472
	s_waitcnt vmcnt(1)
	ds_write_b128 v132, v[198:201] offset:46080
	s_waitcnt vmcnt(0)
	ds_write_b128 v132, v[202:205] offset:50688
	s_waitcnt lgkmcnt(0)
	s_barrier
	v_add_co_u32_e32 v154, vcc, 0x780000, v136
	s_nop 0
	s_nop 0
	s_nop 0
	v_addc_co_u32_e32 v155, vcc, 0, v137, vcc
	v_add_co_u32_e32 v162, vcc, 0x781000, v136
	s_mov_b32 s18, 0
	s_nop 0
	v_addc_co_u32_e32 v163, vcc, 0, v137, vcc
	s_nop 0
	v_add_co_u32_e32 v154, vcc, 0x782000, v136
	s_nop 1
	v_addc_co_u32_e32 v155, vcc, 0, v137, vcc
	v_add_co_u32_e32 v170, vcc, 0x783000, v136
	s_nop 1
	v_addc_co_u32_e32 v171, vcc, 0, v137, vcc
	s_nop 0
	v_add_co_u32_e32 v154, vcc, 0x784000, v136
	s_nop 1
	v_addc_co_u32_e32 v155, vcc, 0, v137, vcc
	v_add_co_u32_e32 v178, vcc, 0x785000, v136
	s_nop 1
	v_addc_co_u32_e32 v179, vcc, 0, v137, vcc
	s_nop 0
	v_add_co_u32_e32 v154, vcc, 0x786000, v136
	s_nop 1
	v_addc_co_u32_e32 v155, vcc, 0, v137, vcc
	v_add_co_u32_e32 v136, vcc, 0x787000, v136
	s_nop 1
	v_addc_co_u32_e32 v137, vcc, 0, v137, vcc
	s_setprio 1
	ds_read_b128 v[190:193], v133 offset:0
	ds_read_b128 v[202:205], v156 offset:18432
	ds_read_b128 v[206:209], v156 offset:23040
	ds_read_b128 v[210:213], v156 offset:27648
	ds_read_b128 v[214:217], v156 offset:32256
	ds_read_b128 v[198:201], v133 offset:4608
	s_waitcnt lgkmcnt(4)
	v_mfma_f32_32x32x16_bf16 v[114:129], v[190:193], v[202:205], v[114:129]
	ds_read_b128 v[194:197], v133 offset:32
	ds_read_b128 v[218:221], v156 offset:18464
	s_waitcnt lgkmcnt(5)
	v_mfma_f32_32x32x16_bf16 v[98:113], v[190:193], v[206:209], v[98:113]
	ds_read_b128 v[224:227], v156 offset:23072
	s_waitcnt lgkmcnt(5)
	v_mfma_f32_32x32x16_bf16 v[82:97], v[190:193], v[210:213], v[82:97]
	ds_read_b128 v[228:231], v156 offset:27680
	s_waitcnt lgkmcnt(5)
	v_mfma_f32_32x32x16_bf16 v[66:81], v[190:193], v[214:217], v[66:81]
	ds_read_b128 v[232:235], v156 offset:32288
	s_waitcnt lgkmcnt(5)
	v_mfma_f32_32x32x16_bf16 v[50:65], v[198:201], v[202:205], v[50:65]
	v_mfma_f32_32x32x16_bf16 v[34:49], v[198:201], v[206:209], v[34:49]
	v_mfma_f32_32x32x16_bf16 v[18:33], v[198:201], v[210:213], v[18:33]
	v_mfma_f32_32x32x16_bf16 v[2:17], v[198:201], v[214:217], v[2:17]
	ds_read_b128 v[198:201], v133 offset:4640
	s_waitcnt lgkmcnt(4)
	v_mfma_f32_32x32x16_bf16 v[114:129], v[194:197], v[218:221], v[114:129]
	ds_read_b128 v[190:193], v133 offset:64
	ds_read_b128 v[202:205], v156 offset:18496
	s_waitcnt lgkmcnt(5)
	v_mfma_f32_32x32x16_bf16 v[98:113], v[194:197], v[224:227], v[98:113]
	ds_read_b128 v[206:209], v156 offset:23104
	s_waitcnt lgkmcnt(5)
	v_mfma_f32_32x32x16_bf16 v[82:97], v[194:197], v[228:231], v[82:97]
	ds_read_b128 v[210:213], v156 offset:27712
	s_waitcnt lgkmcnt(5)
	v_mfma_f32_32x32x16_bf16 v[66:81], v[194:197], v[232:235], v[66:81]
	ds_read_b128 v[214:217], v156 offset:32320
	s_waitcnt lgkmcnt(5)
	v_mfma_f32_32x32x16_bf16 v[50:65], v[198:201], v[218:221], v[50:65]
	v_mfma_f32_32x32x16_bf16 v[34:49], v[198:201], v[224:227], v[34:49]
	v_mfma_f32_32x32x16_bf16 v[18:33], v[198:201], v[228:231], v[18:33]
	v_mfma_f32_32x32x16_bf16 v[2:17], v[198:201], v[232:235], v[2:17]
	ds_read_b128 v[198:201], v133 offset:4672
	s_waitcnt lgkmcnt(4)
	v_mfma_f32_32x32x16_bf16 v[114:129], v[190:193], v[202:205], v[114:129]
	ds_read_b128 v[194:197], v133 offset:96
	ds_read_b128 v[218:221], v156 offset:18528
	s_waitcnt lgkmcnt(5)
	v_mfma_f32_32x32x16_bf16 v[98:113], v[190:193], v[206:209], v[98:113]
	ds_read_b128 v[224:227], v156 offset:23136
	s_waitcnt lgkmcnt(5)
	v_mfma_f32_32x32x16_bf16 v[82:97], v[190:193], v[210:213], v[82:97]
	ds_read_b128 v[228:231], v156 offset:27744
	s_waitcnt lgkmcnt(5)
	v_mfma_f32_32x32x16_bf16 v[66:81], v[190:193], v[214:217], v[66:81]
	ds_read_b128 v[232:235], v156 offset:32352
	s_waitcnt lgkmcnt(5)
	v_mfma_f32_32x32x16_bf16 v[50:65], v[198:201], v[202:205], v[50:65]
	v_mfma_f32_32x32x16_bf16 v[34:49], v[198:201], v[206:209], v[34:49]
	v_mfma_f32_32x32x16_bf16 v[18:33], v[198:201], v[210:213], v[18:33]
	v_mfma_f32_32x32x16_bf16 v[2:17], v[198:201], v[214:217], v[2:17]
	ds_read_b128 v[198:201], v133 offset:4704
	s_waitcnt lgkmcnt(4)
	v_mfma_f32_32x32x16_bf16 v[114:129], v[194:197], v[218:221], v[114:129]
	s_waitcnt lgkmcnt(3)
	v_mfma_f32_32x32x16_bf16 v[98:113], v[194:197], v[224:227], v[98:113]
	s_waitcnt lgkmcnt(2)
	v_mfma_f32_32x32x16_bf16 v[82:97], v[194:197], v[228:231], v[82:97]
	s_waitcnt lgkmcnt(1)
	v_mfma_f32_32x32x16_bf16 v[66:81], v[194:197], v[232:235], v[66:81]
	s_waitcnt lgkmcnt(0)
	v_mfma_f32_32x32x16_bf16 v[50:65], v[198:201], v[218:221], v[50:65]
	v_mfma_f32_32x32x16_bf16 v[34:49], v[198:201], v[224:227], v[34:49]
	v_mfma_f32_32x32x16_bf16 v[18:33], v[198:201], v[228:231], v[18:33]
	v_mfma_f32_32x32x16_bf16 v[2:17], v[198:201], v[232:235], v[2:17]
	s_setprio 0
	v_mov_b32_e32 v130, v134
	s_barrier
	s_waitcnt lgkmcnt(0)
	s_mul_hi_i32 s13, s14, 0x1100
	v_ashrrev_i32_e32 v132, 1, v130
	s_mulk_i32 s14, 0x1100
	v_bfi_b32 v132, s39, v132, v130
	s_add_u32 s14, s14, s16
	s_addc_u32 s15, s13, s17
	v_ashrrev_i32_e32 v133, 31, v132
	v_lshl_add_u64 v[136:137], s[14:15], 0, v[132:133]
	v_and_b32_e32 v130, 32, v130
	v_lshlrev_b64 v[136:137], 12, v[136:137]
	v_mul_lo_u32 v132, v132, s22
	v_lshl_add_u32 v138, v130, 2, v132
	v_lshl_add_u64 v[132:133], s[4:5], 0, v[136:137]
	v_lshlrev_b32_e32 v130, 1, v130
	s_lshl_b32 s16, s12, 7
	v_lshl_add_u64 v[132:133], v[132:133], 0, v[130:131]
	s_mov_b64 s[12:13], -1
	s_branch .LBB0_1038

;     ...
;   for (int kt = 0; kt < nk; ++kt) {
;     const int kn = (kt + 1 < nk) ? kt + 1 : kt;
;     GW_LOAD2(kn * 64, kn * bkstep)
;     __builtin_amdgcn_sched_barrier(0);
;     __builtin_amdgcn_s_setprio(1);
; #pragma unroll
;     for (int st = 0; st < 4; ++st) {
;       bf16x8 a0 = *(const bf16x8*)(Ab + st * 32);
;       bf16x8 a1 = *(const bf16x8*)(Ab + 32 * LSTR + st * 32);
;       bf16x8 b0 = *(const bf16x8*)(Bb + st * 32);
;       bf16x8 b1 = *(const bf16x8*)(Bb + 32 * LSTR + st * 32);
;       bf16x8 b2 = *(const bf16x8*)(Bb + 64 * LSTR + st * 32);
;       bf16x8 b3 = *(const bf16x8*)(Bb + 96 * LSTR + st * 32);
;       acc[0][0] = mfma32(a0, b0, acc[0][0]);
;       acc[0][1] = mfma32(a0, b1, acc[0][1]);
;       acc[0][2] = mfma32(a0, b2, acc[0][2]);
;       acc[0][3] = mfma32(a0, b3, acc[0][3]);
;       acc[1][0] = mfma32(a1, b0, acc[1][0]);
;       acc[1][1] = mfma32(a1, b1, acc[1][1]);
;       acc[1][2] = mfma32(a1, b2, acc[1][2]);
;       acc[1][3] = mfma32(a1, b3, acc[1][3]);
;     }
;     __builtin_amdgcn_s_setprio(0);
;     __builtin_amdgcn_sched_barrier(0);
.LBB0_1113:
	s_setprio 1
	ds_read_b128 v[200:203], v133 offset:0
	ds_read_b128 v[212:215], v150 offset:18432
	ds_read_b128 v[216:219], v150 offset:23040
	ds_read_b128 v[224:227], v150 offset:27648
	ds_read_b128 v[228:231], v150 offset:32256
	ds_read_b128 v[208:211], v133 offset:4608
	s_waitcnt lgkmcnt(4)
	v_mfma_f32_32x32x16_bf16 v[114:129], v[200:203], v[212:215], v[114:129]
	ds_read_b128 v[204:207], v133 offset:32
	ds_read_b128 v[232:235], v150 offset:18464
	s_waitcnt lgkmcnt(5)
	v_mfma_f32_32x32x16_bf16 v[98:113], v[200:203], v[216:219], v[98:113]
	ds_read_b128 v[236:239], v150 offset:23072
	s_waitcnt lgkmcnt(5)
	v_mfma_f32_32x32x16_bf16 v[82:97], v[200:203], v[224:227], v[82:97]
	ds_read_b128 v[240:243], v150 offset:27680
	s_waitcnt lgkmcnt(5)
	v_mfma_f32_32x32x16_bf16 v[66:81], v[200:203], v[228:231], v[66:81]
	ds_read_b128 v[244:247], v150 offset:32288
	s_waitcnt lgkmcnt(5)
	v_mfma_f32_32x32x16_bf16 v[50:65], v[208:211], v[212:215], v[50:65]
	v_lshl_add_u64 v[152:153], v[148:149], 0, v[130:131]
	v_add_co_u32_e32 v152, vcc, s37, v152
	s_nop 1
	v_addc_co_u32_e32 v153, vcc, 0, v153, vcc
	global_load_dwordx4 v[152:155], v[152:153], off offset:384
	v_mfma_f32_32x32x16_bf16 v[34:49], v[208:211], v[216:219], v[34:49]
	v_lshl_add_u64 v[156:157], v[148:149], 0, v[130:131]
	v_add_co_u32_e32 v156, vcc, s38, v156
	s_nop 1
	v_addc_co_u32_e32 v157, vcc, 0, v157, vcc
	global_load_dwordx4 v[156:159], v[156:157], off offset:384
	v_mfma_f32_32x32x16_bf16 v[18:33], v[208:211], v[224:227], v[18:33]
	v_lshl_add_u64 v[160:161], v[148:149], 0, v[130:131]
	v_add_co_u32_e32 v160, vcc, s39, v160
	s_nop 1
	v_addc_co_u32_e32 v161, vcc, 0, v161, vcc
	global_load_dwordx4 v[160:163], v[160:161], off offset:384
	v_mfma_f32_32x32x16_bf16 v[2:17], v[208:211], v[228:231], v[2:17]
	v_lshl_add_u64 v[164:165], v[148:149], 0, v[130:131]
	v_add_co_u32_e32 v164, vcc, s40, v164
	s_nop 1
	v_addc_co_u32_e32 v165, vcc, 0, v165, vcc
	global_load_dwordx4 v[164:167], v[164:165], off offset:384
	ds_read_b128 v[208:211], v133 offset:4640
	s_waitcnt lgkmcnt(4)
	v_mfma_f32_32x32x16_bf16 v[114:129], v[204:207], v[232:235], v[114:129]
	ds_read_b128 v[200:203], v133 offset:64
	ds_read_b128 v[212:215], v150 offset:18496
	s_waitcnt lgkmcnt(5)
	v_mfma_f32_32x32x16_bf16 v[98:113], v[204:207], v[236:239], v[98:113]
	ds_read_b128 v[216:219], v150 offset:23104
	s_waitcnt lgkmcnt(5)
	v_mfma_f32_32x32x16_bf16 v[82:97], v[204:207], v[240:243], v[82:97]
	ds_read_b128 v[224:227], v150 offset:27712
	s_waitcnt lgkmcnt(5)
	v_mfma_f32_32x32x16_bf16 v[66:81], v[204:207], v[244:247], v[66:81]
	ds_read_b128 v[228:231], v150 offset:32320
	s_waitcnt lgkmcnt(5)
	v_mfma_f32_32x32x16_bf16 v[50:65], v[208:211], v[232:235], v[50:65]
	v_lshl_add_u64 v[168:169], v[146:147], 0, v[130:131]
	v_add_co_u32_e32 v168, vcc, s41, v168
	s_nop 1
	v_addc_co_u32_e32 v169, vcc, 0, v169, vcc
	global_load_dwordx4 v[168:171], v[168:169], off offset:-4096
	v_mfma_f32_32x32x16_bf16 v[34:49], v[208:211], v[236:239], v[34:49]
	v_lshl_add_u64 v[172:173], v[146:147], 0, v[130:131]
	v_add_co_u32_e32 v172, vcc, s41, v172
	s_nop 1
	v_addc_co_u32_e32 v173, vcc, 0, v173, vcc
	global_load_dwordx4 v[172:175], v[172:173], off
	v_mfma_f32_32x32x16_bf16 v[18:33], v[208:211], v[240:243], v[18:33]
	v_lshl_add_u64 v[176:177], v[146:147], 0, v[130:131]
	v_add_co_u32_e32 v176, vcc, s42, v176
	s_nop 1
	v_addc_co_u32_e32 v177, vcc, 0, v177, vcc
	global_load_dwordx4 v[176:179], v[176:177], off offset:-4096
	v_mfma_f32_32x32x16_bf16 v[2:17], v[208:211], v[244:247], v[2:17]
	v_lshl_add_u64 v[180:181], v[146:147], 0, v[130:131]
	v_add_co_u32_e32 v180, vcc, s42, v180
	s_nop 1
	v_addc_co_u32_e32 v181, vcc, 0, v181, vcc
	global_load_dwordx4 v[180:183], v[180:181], off
	ds_read_b128 v[208:211], v133 offset:4672
	s_waitcnt lgkmcnt(4)
	v_mfma_f32_32x32x16_bf16 v[114:129], v[200:203], v[212:215], v[114:129]
	ds_read_b128 v[204:207], v133 offset:96
	ds_read_b128 v[232:235], v150 offset:18528
	s_waitcnt lgkmcnt(5)
	v_mfma_f32_32x32x16_bf16 v[98:113], v[200:203], v[216:219], v[98:113]
	ds_read_b128 v[236:239], v150 offset:23136
	s_waitcnt lgkmcnt(5)
	v_mfma_f32_32x32x16_bf16 v[82:97], v[200:203], v[224:227], v[82:97]
	ds_read_b128 v[240:243], v150 offset:27744
	s_waitcnt lgkmcnt(5)
	v_mfma_f32_32x32x16_bf16 v[66:81], v[200:203], v[228:231], v[66:81]
	ds_read_b128 v[244:247], v150 offset:32352
	s_waitcnt lgkmcnt(5)
	v_mfma_f32_32x32x16_bf16 v[50:65], v[208:211], v[212:215], v[50:65]
	v_lshl_add_u64 v[184:185], v[146:147], 0, v[130:131]
	v_add_co_u32_e32 v184, vcc, s43, v184
	s_nop 1
	v_addc_co_u32_e32 v185, vcc, 0, v185, vcc
	global_load_dwordx4 v[184:187], v[184:185], off offset:-4096
	v_mfma_f32_32x32x16_bf16 v[34:49], v[208:211], v[216:219], v[34:49]
	v_lshl_add_u64 v[188:189], v[146:147], 0, v[130:131]
	v_add_co_u32_e32 v188, vcc, s43, v188
	s_nop 1
	v_addc_co_u32_e32 v189, vcc, 0, v189, vcc
	global_load_dwordx4 v[188:191], v[188:189], off
	v_mfma_f32_32x32x16_bf16 v[18:33], v[208:211], v[224:227], v[18:33]
	v_lshl_add_u64 v[192:193], v[146:147], 0, v[130:131]
	v_add_co_u32_e32 v192, vcc, s44, v192
	s_nop 1
	v_addc_co_u32_e32 v193, vcc, 0, v193, vcc
	global_load_dwordx4 v[192:195], v[192:193], off offset:-4096
	v_mfma_f32_32x32x16_bf16 v[2:17], v[208:211], v[228:231], v[2:17]
	v_lshl_add_u64 v[196:197], v[146:147], 0, v[130:131]
	v_add_co_u32_e32 v196, vcc, s44, v196
	s_nop 1
	v_addc_co_u32_e32 v197, vcc, 0, v197, vcc
	global_load_dwordx4 v[196:199], v[196:197], off
	ds_read_b128 v[208:211], v133 offset:4704
	s_waitcnt lgkmcnt(4)
	v_mfma_f32_32x32x16_bf16 v[114:129], v[204:207], v[232:235], v[114:129]
	s_waitcnt lgkmcnt(3)
	v_mfma_f32_32x32x16_bf16 v[98:113], v[204:207], v[236:239], v[98:113]
	s_waitcnt lgkmcnt(2)
	v_mfma_f32_32x32x16_bf16 v[82:97], v[204:207], v[240:243], v[82:97]
	s_waitcnt lgkmcnt(1)
	v_mfma_f32_32x32x16_bf16 v[66:81], v[204:207], v[244:247], v[66:81]
	s_waitcnt lgkmcnt(0)
	v_mfma_f32_32x32x16_bf16 v[50:65], v[208:211], v[232:235], v[50:65]
	v_mfma_f32_32x32x16_bf16 v[34:49], v[208:211], v[236:239], v[34:49]
	v_mfma_f32_32x32x16_bf16 v[18:33], v[208:211], v[240:243], v[18:33]
	v_mfma_f32_32x32x16_bf16 v[2:17], v[208:211], v[244:247], v[2:17]
	s_setprio 0
	s_add_i32 s15, s15, -1
	v_lshl_add_u64 v[146:147], v[146:147], 0, s[4:5]
	s_cmp_lg_u32 s15, 0
	v_lshl_add_u64 v[148:149], v[148:149], 0, s[10:11]
	s_barrier
; #define GW_LOAD(KOFF) GW_LOAD2(KOFF, 0)
;     ...
;   GW_LOAD(0)
;   GW_STORE()
;   __syncthreads();
;   const int nk = K >> 6;
;   const char* Ab = smem + (wm * 64 + (lane & 31)) * LSTR + (lane >> 5) * 16;
;   const char* Bb = smem + WTILE_A + (wn * 128 + (lane & 31)) * LSTR + (lane >> 5) * 16;
;   for (int kt = 0; kt < nk; ++kt) {
;     const int kn = (kt + 1 < nk) ? kt + 1 : kt;
;     GW_LOAD2(kn * 64, kn * bkstep)
;     __builtin_amdgcn_sched_barrier(0);
;     __builtin_amdgcn_s_setprio(1);
; #pragma unroll
;     for (int st = 0; st < 4; ++st) {
;       bf16x8 a0 = *(const bf16x8*)(Ab + st * 32);
;       bf16x8 a1 = *(const bf16x8*)(Ab + 32 * LSTR + st * 32);
;       bf16x8 b0 = *(const bf16x8*)(Bb + st * 32);
;       bf16x8 b1 = *(const bf16x8*)(Bb + 32 * LSTR + st * 32);
;       bf16x8 b2 = *(const bf16x8*)(Bb + 64 * LSTR + st * 32);
;       bf16x8 b3 = *(const bf16x8*)(Bb + 96 * LSTR + st * 32);
;       acc[0][0] = mfma32(a0, b0, acc[0][0]);
;       acc[0][1] = mfma32(a0, b1, acc[0][1]);
;       acc[0][2] = mfma32(a0, b2, acc[0][2]);
;       acc[0][3] = mfma32(a0, b3, acc[0][3]);
;       acc[1][0] = mfma32(a1, b0, acc[1][0]);
;       acc[1][1] = mfma32(a1, b1, acc[1][1]);
;       acc[1][2] = mfma32(a1, b2, acc[1][2]);
;       acc[1][3] = mfma32(a1, b3, acc[1][3]);
;     }
;     __builtin_amdgcn_s_setprio(0);
;     __builtin_amdgcn_sched_barrier(0);
;     __syncthreads();
;     GW_STORE()
;     __syncthreads();
	s_waitcnt vmcnt(11)
	ds_write_b128 v132, v[152:155]
	s_waitcnt vmcnt(10)
	ds_write_b128 v132, v[156:159] offset:4608
	s_waitcnt vmcnt(9)
	ds_write_b128 v132, v[160:163] offset:9216
	s_waitcnt vmcnt(8)
	ds_write_b128 v132, v[164:167] offset:13824
	s_waitcnt vmcnt(7)
	ds_write_b128 v132, v[168:171] offset:18432
	s_waitcnt vmcnt(6)
	ds_write_b128 v132, v[172:175] offset:23040
	s_waitcnt vmcnt(5)
	ds_write_b128 v132, v[176:179] offset:27648
	s_waitcnt vmcnt(4)
	ds_write_b128 v132, v[180:183] offset:32256
	s_waitcnt vmcnt(3)
	ds_write_b128 v132, v[184:187] offset:36864
	s_waitcnt vmcnt(2)
	ds_write_b128 v132, v[188:191] offset:41472
	s_waitcnt vmcnt(1)
	ds_write_b128 v132, v[192:195] offset:46080
	s_waitcnt vmcnt(0)
	ds_write_b128 v132, v[196:199] offset:50688
	s_waitcnt lgkmcnt(0)
	s_barrier
	s_cbranch_scc1 .LBB0_1113
	s_setprio 1
	ds_read_b128 v[200:203], v133 offset:0
	ds_read_b128 v[212:215], v150 offset:18432
	ds_read_b128 v[216:219], v150 offset:23040
	ds_read_b128 v[224:227], v150 offset:27648
	ds_read_b128 v[228:231], v150 offset:32256
	ds_read_b128 v[208:211], v133 offset:4608
	s_waitcnt lgkmcnt(4)
	v_mfma_f32_32x32x16_bf16 v[114:129], v[200:203], v[212:215], v[114:129]
	ds_read_b128 v[204:207], v133 offset:32
	ds_read_b128 v[232:235], v150 offset:18464
	s_waitcnt lgkmcnt(5)
	v_mfma_f32_32x32x16_bf16 v[98:113], v[200:203], v[216:219], v[98:113]
	ds_read_b128 v[236:239], v150 offset:23072
	s_waitcnt lgkmcnt(5)
	v_mfma_f32_32x32x16_bf16 v[82:97], v[200:203], v[224:227], v[82:97]
	ds_read_b128 v[240:243], v150 offset:27680
	s_waitcnt lgkmcnt(5)
	v_mfma_f32_32x32x16_bf16 v[66:81], v[200:203], v[228:231], v[66:81]
	ds_read_b128 v[244:247], v150 offset:32288
	s_waitcnt lgkmcnt(5)
	v_mfma_f32_32x32x16_bf16 v[50:65], v[208:211], v[212:215], v[50:65]
	v_lshl_add_u64 v[152:153], v[148:149], 0, v[130:131]
	v_add_co_u32_e32 v152, vcc, s37, v152
	s_nop 1
	v_addc_co_u32_e32 v153, vcc, 0, v153, vcc
	global_load_dwordx4 v[152:155], v[152:153], off offset:384
	v_mfma_f32_32x32x16_bf16 v[34:49], v[208:211], v[216:219], v[34:49]
	v_lshl_add_u64 v[156:157], v[148:149], 0, v[130:131]
	v_add_co_u32_e32 v156, vcc, s38, v156
	s_nop 1
	v_addc_co_u32_e32 v157, vcc, 0, v157, vcc
	global_load_dwordx4 v[156:159], v[156:157], off offset:384
	v_mfma_f32_32x32x16_bf16 v[18:33], v[208:211], v[224:227], v[18:33]
	v_lshl_add_u64 v[160:161], v[148:149], 0, v[130:131]
	v_add_co_u32_e32 v160, vcc, s39, v160
	s_nop 1
	v_addc_co_u32_e32 v161, vcc, 0, v161, vcc
	global_load_dwordx4 v[160:163], v[160:161], off offset:384
	v_mfma_f32_32x32x16_bf16 v[2:17], v[208:211], v[228:231], v[2:17]
	v_lshl_add_u64 v[164:165], v[148:149], 0, v[130:131]
	v_add_co_u32_e32 v164, vcc, s40, v164
	s_nop 1
	v_addc_co_u32_e32 v165, vcc, 0, v165, vcc
	global_load_dwordx4 v[164:167], v[164:165], off offset:384
	ds_read_b128 v[208:211], v133 offset:4640
	s_waitcnt lgkmcnt(4)
	v_mfma_f32_32x32x16_bf16 v[114:129], v[204:207], v[232:235], v[114:129]
	ds_read_b128 v[200:203], v133 offset:64
	ds_read_b128 v[212:215], v150 offset:18496
	s_waitcnt lgkmcnt(5)
	v_mfma_f32_32x32x16_bf16 v[98:113], v[204:207], v[236:239], v[98:113]
	ds_read_b128 v[216:219], v150 offset:23104
	s_waitcnt lgkmcnt(5)
	v_mfma_f32_32x32x16_bf16 v[82:97], v[204:207], v[240:243], v[82:97]
	ds_read_b128 v[224:227], v150 offset:27712
	s_waitcnt lgkmcnt(5)
	v_mfma_f32_32x32x16_bf16 v[66:81], v[204:207], v[244:247], v[66:81]
	ds_read_b128 v[228:231], v150 offset:32320
	s_waitcnt lgkmcnt(5)
	v_mfma_f32_32x32x16_bf16 v[50:65], v[208:211], v[232:235], v[50:65]
	v_lshl_add_u64 v[168:169], v[146:147], 0, v[130:131]
	v_add_co_u32_e32 v168, vcc, s41, v168
	s_nop 1
	v_addc_co_u32_e32 v169, vcc, 0, v169, vcc
	global_load_dwordx4 v[168:171], v[168:169], off offset:-4096
	v_mfma_f32_32x32x16_bf16 v[34:49], v[208:211], v[236:239], v[34:49]
	v_lshl_add_u64 v[172:173], v[146:147], 0, v[130:131]
	v_add_co_u32_e32 v172, vcc, s41, v172
	s_nop 1
	v_addc_co_u32_e32 v173, vcc, 0, v173, vcc
	global_load_dwordx4 v[172:175], v[172:173], off
	v_mfma_f32_32x32x16_bf16 v[18:33], v[208:211], v[240:243], v[18:33]
	v_lshl_add_u64 v[176:177], v[146:147], 0, v[130:131]
	v_add_co_u32_e32 v176, vcc, s42, v176
	s_nop 1
	v_addc_co_u32_e32 v177, vcc, 0, v177, vcc
	global_load_dwordx4 v[176:179], v[176:177], off offset:-4096
	v_mfma_f32_32x32x16_bf16 v[2:17], v[208:211], v[244:247], v[2:17]
	v_lshl_add_u64 v[180:181], v[146:147], 0, v[130:131]
	v_add_co_u32_e32 v180, vcc, s42, v180
	s_nop 1
	v_addc_co_u32_e32 v181, vcc, 0, v181, vcc
	global_load_dwordx4 v[180:183], v[180:181], off
	ds_read_b128 v[208:211], v133 offset:4672
	s_waitcnt lgkmcnt(4)
	v_mfma_f32_32x32x16_bf16 v[114:129], v[200:203], v[212:215], v[114:129]
	ds_read_b128 v[204:207], v133 offset:96
	ds_read_b128 v[232:235], v150 offset:18528
	s_waitcnt lgkmcnt(5)
	v_mfma_f32_32x32x16_bf16 v[98:113], v[200:203], v[216:219], v[98:113]
	ds_read_b128 v[236:239], v150 offset:23136
	s_waitcnt lgkmcnt(5)
	v_mfma_f32_32x32x16_bf16 v[82:97], v[200:203], v[224:227], v[82:97]
	ds_read_b128 v[240:243], v150 offset:27744
	s_waitcnt lgkmcnt(5)
	v_mfma_f32_32x32x16_bf16 v[66:81], v[200:203], v[228:231], v[66:81]
	ds_read_b128 v[244:247], v150 offset:32352
	s_waitcnt lgkmcnt(5)
;     ...
; #pragma unroll
;     for (int st = 0; st < 4; ++st) {
;       bf16x8 a0 = *(const bf16x8*)(Ab + st * 32);
;       bf16x8 a1 = *(const bf16x8*)(Ab + 32 * LSTR + st * 32);
;       bf16x8 b0 = *(const bf16x8*)(Bb + st * 32);
;       bf16x8 b1 = *(const bf16x8*)(Bb + 32 * LSTR + st * 32);
;       bf16x8 b2 = *(const bf16x8*)(Bb + 64 * LSTR + st * 32);
;       bf16x8 b3 = *(const bf16x8*)(Bb + 96 * LSTR + st * 32);
;       acc[0][0] = mfma32(a0, b0, acc[0][0]);
;       acc[0][1] = mfma32(a0, b1, acc[0][1]);
;       acc[0][2] = mfma32(a0, b2, acc[0][2]);
;       acc[0][3] = mfma32(a0, b3, acc[0][3]);
;       acc[1][0] = mfma32(a1, b0, acc[1][0]);
;       acc[1][1] = mfma32(a1, b1, acc[1][1]);
;       acc[1][2] = mfma32(a1, b2, acc[1][2]);
;       acc[1][3] = mfma32(a1, b3, acc[1][3]);
;     }
;     __builtin_amdgcn_s_setprio(0);
;     __builtin_amdgcn_sched_barrier(0);
;     __syncthreads();
;     GW_STORE()
;     __syncthreads();
	v_mfma_f32_32x32x16_bf16 v[50:65], v[208:211], v[212:215], v[50:65]
	v_lshl_add_u64 v[184:185], v[146:147], 0, v[130:131]
	v_add_co_u32_e32 v184, vcc, s43, v184
	s_nop 1
	v_addc_co_u32_e32 v185, vcc, 0, v185, vcc
	global_load_dwordx4 v[184:187], v[184:185], off offset:-4096
	v_mfma_f32_32x32x16_bf16 v[34:49], v[208:211], v[216:219], v[34:49]
	v_lshl_add_u64 v[188:189], v[146:147], 0, v[130:131]
	v_add_co_u32_e32 v188, vcc, s43, v188
	s_nop 1
	v_addc_co_u32_e32 v189, vcc, 0, v189, vcc
	global_load_dwordx4 v[188:191], v[188:189], off
	v_mfma_f32_32x32x16_bf16 v[18:33], v[208:211], v[224:227], v[18:33]
	v_lshl_add_u64 v[192:193], v[146:147], 0, v[130:131]
	v_add_co_u32_e32 v192, vcc, s44, v192
	s_nop 1
	v_addc_co_u32_e32 v193, vcc, 0, v193, vcc
	global_load_dwordx4 v[192:195], v[192:193], off offset:-4096
	v_mfma_f32_32x32x16_bf16 v[2:17], v[208:211], v[228:231], v[2:17]
	v_lshl_add_u64 v[196:197], v[146:147], 0, v[130:131]
	v_add_co_u32_e32 v196, vcc, s44, v196
	s_nop 1
	v_addc_co_u32_e32 v197, vcc, 0, v197, vcc
	global_load_dwordx4 v[196:199], v[196:197], off
	ds_read_b128 v[208:211], v133 offset:4704
	s_waitcnt lgkmcnt(4)
	v_mfma_f32_32x32x16_bf16 v[114:129], v[204:207], v[232:235], v[114:129]
	s_waitcnt lgkmcnt(3)
	v_mfma_f32_32x32x16_bf16 v[98:113], v[204:207], v[236:239], v[98:113]
	s_waitcnt lgkmcnt(2)
	v_mfma_f32_32x32x16_bf16 v[82:97], v[204:207], v[240:243], v[82:97]
	s_waitcnt lgkmcnt(1)
	v_mfma_f32_32x32x16_bf16 v[66:81], v[204:207], v[244:247], v[66:81]
	s_waitcnt lgkmcnt(0)
	v_mfma_f32_32x32x16_bf16 v[50:65], v[208:211], v[232:235], v[50:65]
	v_mfma_f32_32x32x16_bf16 v[34:49], v[208:211], v[236:239], v[34:49]
	v_mfma_f32_32x32x16_bf16 v[18:33], v[208:211], v[240:243], v[18:33]
	v_mfma_f32_32x32x16_bf16 v[2:17], v[208:211], v[244:247], v[2:17]
	s_setprio 0
	v_lshl_add_u64 v[146:147], v[146:147], 0, s[4:5]
	v_lshl_add_u64 v[148:149], v[148:149], 0, s[10:11]
	s_barrier
	s_waitcnt vmcnt(11)
	ds_write_b128 v132, v[152:155]
	s_waitcnt vmcnt(10)
	ds_write_b128 v132, v[156:159] offset:4608
	s_waitcnt vmcnt(9)
	ds_write_b128 v132, v[160:163] offset:9216
	s_waitcnt vmcnt(8)
	ds_write_b128 v132, v[164:167] offset:13824
	s_waitcnt vmcnt(7)
	ds_write_b128 v132, v[168:171] offset:18432
	s_waitcnt vmcnt(6)
	ds_write_b128 v132, v[172:175] offset:23040
	s_waitcnt vmcnt(5)
	ds_write_b128 v132, v[176:179] offset:27648
	s_waitcnt vmcnt(4)
	ds_write_b128 v132, v[180:183] offset:32256
	s_waitcnt vmcnt(3)
	ds_write_b128 v132, v[184:187] offset:36864
	s_waitcnt vmcnt(2)
	ds_write_b128 v132, v[188:191] offset:41472
	s_waitcnt vmcnt(1)
	ds_write_b128 v132, v[192:195] offset:46080
	s_waitcnt vmcnt(0)
	ds_write_b128 v132, v[196:199] offset:50688
	s_waitcnt lgkmcnt(0)
	s_barrier
;     ...
; #pragma unroll
;     for (int st = 0; st < 4; ++st) {
;       bf16x8 a0 = *(const bf16x8*)(Ab + st * 32);
;       bf16x8 a1 = *(const bf16x8*)(Ab + 32 * LSTR + st * 32);
;       bf16x8 b0 = *(const bf16x8*)(Bb + st * 32);
;       bf16x8 b1 = *(const bf16x8*)(Bb + 32 * LSTR + st * 32);
;       bf16x8 b2 = *(const bf16x8*)(Bb + 64 * LSTR + st * 32);
;       bf16x8 b3 = *(const bf16x8*)(Bb + 96 * LSTR + st * 32);
;       acc[0][0] = mfma32(a0, b0, acc[0][0]);
;       acc[0][1] = mfma32(a0, b1, acc[0][1]);
;       acc[0][2] = mfma32(a0, b2, acc[0][2]);
;       acc[0][3] = mfma32(a0, b3, acc[0][3]);
;       acc[1][0] = mfma32(a1, b0, acc[1][0]);
;       acc[1][1] = mfma32(a1, b1, acc[1][1]);
;       acc[1][2] = mfma32(a1, b2, acc[1][2]);
;       acc[1][3] = mfma32(a1, b3, acc[1][3]);
;     }
;     __builtin_amdgcn_s_setprio(0);
	v_add_co_u32_e32 v156, vcc, 0x3e0000, v136
	s_nop 0
	s_nop 0
	s_nop 0
	v_addc_co_u32_e32 v157, vcc, 0, v137, vcc
	v_add_co_u32_e32 v160, vcc, 0x3e1000, v136
	s_mov_b32 s18, 0
	s_nop 0
	v_addc_co_u32_e32 v161, vcc, 0, v137, vcc
	v_add_co_u32_e32 v164, vcc, 0x3e2000, v136
	s_nop 0
	v_addc_co_u32_e32 v165, vcc, 0, v137, vcc
	v_add_co_u32_e32 v168, vcc, 0x3e3000, v136
	s_nop 1
	v_addc_co_u32_e32 v169, vcc, 0, v137, vcc
	v_add_co_u32_e32 v172, vcc, 0x3e4000, v136
	s_nop 0
	v_addc_co_u32_e32 v173, vcc, 0, v137, vcc
	v_add_co_u32_e32 v176, vcc, 0x3e5000, v136
	s_nop 1
	v_addc_co_u32_e32 v177, vcc, 0, v137, vcc
	v_add_co_u32_e32 v180, vcc, 0x3e6000, v136
	s_nop 0
	v_addc_co_u32_e32 v181, vcc, 0, v137, vcc
	v_add_co_u32_e32 v136, vcc, 0x3e7000, v136
	s_nop 1
	v_addc_co_u32_e32 v137, vcc, 0, v137, vcc
	s_nop 0
	s_setprio 1
	ds_read_b128 v[188:191], v133 offset:0
	ds_read_b128 v[200:203], v150 offset:18432
	ds_read_b128 v[204:207], v150 offset:23040
	ds_read_b128 v[208:211], v150 offset:27648
	ds_read_b128 v[212:215], v150 offset:32256
	ds_read_b128 v[196:199], v133 offset:4608
	s_waitcnt lgkmcnt(4)
	v_mfma_f32_32x32x16_bf16 v[114:129], v[188:191], v[200:203], v[114:129]
	ds_read_b128 v[192:195], v133 offset:32
	ds_read_b128 v[216:219], v150 offset:18464
	s_waitcnt lgkmcnt(5)
	v_mfma_f32_32x32x16_bf16 v[98:113], v[188:191], v[204:207], v[98:113]
	ds_read_b128 v[224:227], v150 offset:23072
	s_waitcnt lgkmcnt(5)
	v_mfma_f32_32x32x16_bf16 v[82:97], v[188:191], v[208:211], v[82:97]
	ds_read_b128 v[228:231], v150 offset:27680
	s_waitcnt lgkmcnt(5)
	v_mfma_f32_32x32x16_bf16 v[66:81], v[188:191], v[212:215], v[66:81]
	ds_read_b128 v[232:235], v150 offset:32288
	s_waitcnt lgkmcnt(5)
	v_mfma_f32_32x32x16_bf16 v[50:65], v[196:199], v[200:203], v[50:65]
	v_mfma_f32_32x32x16_bf16 v[34:49], v[196:199], v[204:207], v[34:49]
	v_mfma_f32_32x32x16_bf16 v[18:33], v[196:199], v[208:211], v[18:33]
	v_mfma_f32_32x32x16_bf16 v[2:17], v[196:199], v[212:215], v[2:17]
	ds_read_b128 v[196:199], v133 offset:4640
	s_waitcnt lgkmcnt(4)
	v_mfma_f32_32x32x16_bf16 v[114:129], v[192:195], v[216:219], v[114:129]
	ds_read_b128 v[188:191], v133 offset:64
	ds_read_b128 v[200:203], v150 offset:18496
	s_waitcnt lgkmcnt(5)
	v_mfma_f32_32x32x16_bf16 v[98:113], v[192:195], v[224:227], v[98:113]
	ds_read_b128 v[204:207], v150 offset:23104
	s_waitcnt lgkmcnt(5)
	v_mfma_f32_32x32x16_bf16 v[82:97], v[192:195], v[228:231], v[82:97]
	ds_read_b128 v[208:211], v150 offset:27712
	s_waitcnt lgkmcnt(5)
	v_mfma_f32_32x32x16_bf16 v[66:81], v[192:195], v[232:235], v[66:81]
	ds_read_b128 v[212:215], v150 offset:32320
	s_waitcnt lgkmcnt(5)
	v_mfma_f32_32x32x16_bf16 v[50:65], v[196:199], v[216:219], v[50:65]
	v_mfma_f32_32x32x16_bf16 v[34:49], v[196:199], v[224:227], v[34:49]
	v_mfma_f32_32x32x16_bf16 v[18:33], v[196:199], v[228:231], v[18:33]
	v_mfma_f32_32x32x16_bf16 v[2:17], v[196:199], v[232:235], v[2:17]
	ds_read_b128 v[196:199], v133 offset:4672
	s_waitcnt lgkmcnt(4)
	v_mfma_f32_32x32x16_bf16 v[114:129], v[188:191], v[200:203], v[114:129]
	ds_read_b128 v[192:195], v133 offset:96
	ds_read_b128 v[216:219], v150 offset:18528
	s_waitcnt lgkmcnt(5)
	v_mfma_f32_32x32x16_bf16 v[98:113], v[188:191], v[204:207], v[98:113]
	ds_read_b128 v[224:227], v150 offset:23136
	s_waitcnt lgkmcnt(5)
	v_mfma_f32_32x32x16_bf16 v[82:97], v[188:191], v[208:211], v[82:97]
	ds_read_b128 v[228:231], v150 offset:27744
	s_waitcnt lgkmcnt(5)
	v_mfma_f32_32x32x16_bf16 v[66:81], v[188:191], v[212:215], v[66:81]
	ds_read_b128 v[232:235], v150 offset:32352
	s_waitcnt lgkmcnt(5)
	v_mfma_f32_32x32x16_bf16 v[50:65], v[196:199], v[200:203], v[50:65]
	v_mfma_f32_32x32x16_bf16 v[34:49], v[196:199], v[204:207], v[34:49]
	v_mfma_f32_32x32x16_bf16 v[18:33], v[196:199], v[208:211], v[18:33]
	v_mfma_f32_32x32x16_bf16 v[2:17], v[196:199], v[212:215], v[2:17]
	ds_read_b128 v[196:199], v133 offset:4704
	s_waitcnt lgkmcnt(4)
	v_mfma_f32_32x32x16_bf16 v[114:129], v[192:195], v[216:219], v[114:129]
	s_waitcnt lgkmcnt(3)
	v_mfma_f32_32x32x16_bf16 v[98:113], v[192:195], v[224:227], v[98:113]
	s_waitcnt lgkmcnt(2)
	v_mfma_f32_32x32x16_bf16 v[82:97], v[192:195], v[228:231], v[82:97]
	s_waitcnt lgkmcnt(1)
	v_mfma_f32_32x32x16_bf16 v[66:81], v[192:195], v[232:235], v[66:81]
	s_waitcnt lgkmcnt(0)
	v_mfma_f32_32x32x16_bf16 v[50:65], v[196:199], v[216:219], v[50:65]
	v_mfma_f32_32x32x16_bf16 v[34:49], v[196:199], v[224:227], v[34:49]
	v_mfma_f32_32x32x16_bf16 v[18:33], v[196:199], v[228:231], v[18:33]
	v_mfma_f32_32x32x16_bf16 v[2:17], v[196:199], v[232:235], v[2:17]
	s_setprio 0
	v_readlane_b32 s48, v253, 37
	v_readlane_b32 s49, v253, 38
	v_readlane_b32 s50, v253, 39
	v_readlane_b32 s51, v253, 40
	v_readlane_b32 s52, v253, 41
	v_readlane_b32 s53, v253, 42
	v_readlane_b32 s54, v253, 43
	v_readlane_b32 s55, v253, 44
	v_readlane_b32 s56, v253, 45
	v_readlane_b32 s57, v253, 46
	v_readlane_b32 s58, v253, 47
	v_readlane_b32 s59, v253, 48
	v_readlane_b32 s60, v253, 49
	v_readlane_b32 s61, v253, 50
	v_readlane_b32 s62, v253, 51
	v_readlane_b32 s63, v253, 52
	s_mov_b64 s[48:49], s[56:57]
	s_lshl_b32 s19, s14, 8
	s_mov_b64 s[14:15], -1
	s_mov_b64 s[50:51], s[58:59]
	s_mov_b64 s[52:53], s[60:61]
	s_mov_b64 s[54:55], s[62:63]
	s_barrier
	s_waitcnt lgkmcnt(0)
	s_branch .LBB0_1116

;     ...
;   for (int kt = 0; kt < nk; ++kt) {
;     const int kn = (kt + 1 < nk) ? kt + 1 : kt;
;     GW_LOAD2(kn * 64, kn * bkstep)
;     __builtin_amdgcn_sched_barrier(0);
;     __builtin_amdgcn_s_setprio(1);
; #pragma unroll
;     for (int st = 0; st < 4; ++st) {
;       bf16x8 a0 = *(const bf16x8*)(Ab + st * 32);
;       bf16x8 a1 = *(const bf16x8*)(Ab + 32 * LSTR + st * 32);
;       bf16x8 b0 = *(const bf16x8*)(Bb + st * 32);
;       bf16x8 b1 = *(const bf16x8*)(Bb + 32 * LSTR + st * 32);
;       bf16x8 b2 = *(const bf16x8*)(Bb + 64 * LSTR + st * 32);
;       bf16x8 b3 = *(const bf16x8*)(Bb + 96 * LSTR + st * 32);
;       acc[0][0] = mfma32(a0, b0, acc[0][0]);
;       acc[0][1] = mfma32(a0, b1, acc[0][1]);
;       acc[0][2] = mfma32(a0, b2, acc[0][2]);
;       acc[0][3] = mfma32(a0, b3, acc[0][3]);
;       acc[1][0] = mfma32(a1, b0, acc[1][0]);
;       acc[1][1] = mfma32(a1, b1, acc[1][1]);
;       acc[1][2] = mfma32(a1, b2, acc[1][2]);
;       acc[1][3] = mfma32(a1, b3, acc[1][3]);
;     }
;     __builtin_amdgcn_s_setprio(0);
;     __builtin_amdgcn_sched_barrier(0);
.LBB0_1284:
	s_setprio 1
	ds_read_b128 v[204:207], v131 offset:0
	ds_read_b128 v[216:219], v138 offset:18432
	ds_read_b128 v[224:227], v138 offset:23040
	ds_read_b128 v[228:231], v138 offset:27648
	ds_read_b128 v[232:235], v138 offset:32256
	ds_read_b128 v[212:215], v131 offset:4608
	s_waitcnt lgkmcnt(4)
	v_mfma_f32_32x32x16_bf16 v[114:129], v[204:207], v[216:219], v[114:129]
	ds_read_b128 v[208:211], v131 offset:32
	ds_read_b128 v[236:239], v138 offset:18464
	s_waitcnt lgkmcnt(5)
	v_mfma_f32_32x32x16_bf16 v[98:113], v[204:207], v[224:227], v[98:113]
	ds_read_b128 v[240:243], v138 offset:23072
	s_waitcnt lgkmcnt(5)
	v_mfma_f32_32x32x16_bf16 v[82:97], v[204:207], v[228:231], v[82:97]
	ds_read_b128 v[244:247], v138 offset:27680
	s_waitcnt lgkmcnt(5)
	v_mfma_f32_32x32x16_bf16 v[66:81], v[204:207], v[232:235], v[66:81]
	ds_read_b128 v[248:251], v138 offset:32288
	s_waitcnt lgkmcnt(5)
	v_mfma_f32_32x32x16_bf16 v[50:65], v[212:215], v[216:219], v[50:65]
	v_lshl_add_u64 v[154:155], v[150:151], 0, s[8:9]
	v_add_co_u32_e32 v154, vcc, s43, v154
	s_nop 1
	v_addc_co_u32_e32 v155, vcc, 0, v155, vcc
	global_load_dwordx4 v[154:157], v[154:155], off offset:384
	v_mfma_f32_32x32x16_bf16 v[34:49], v[212:215], v[224:227], v[34:49]
	v_lshl_add_u64 v[158:159], v[150:151], 0, s[8:9]
	v_add_co_u32_e32 v158, vcc, s44, v158
	s_nop 1
	v_addc_co_u32_e32 v159, vcc, 0, v159, vcc
	global_load_dwordx4 v[158:161], v[158:159], off offset:384
	v_mfma_f32_32x32x16_bf16 v[18:33], v[212:215], v[228:231], v[18:33]
	v_lshl_add_u64 v[162:163], v[150:151], 0, s[8:9]
	v_add_co_u32_e32 v162, vcc, s45, v162
	s_nop 1
	v_addc_co_u32_e32 v163, vcc, 0, v163, vcc
	global_load_dwordx4 v[162:165], v[162:163], off offset:384
	v_mfma_f32_32x32x16_bf16 v[2:17], v[212:215], v[232:235], v[2:17]
	v_lshl_add_u64 v[166:167], v[150:151], 0, s[8:9]
	v_add_co_u32_e32 v166, vcc, s46, v166
	s_nop 1
	v_addc_co_u32_e32 v167, vcc, 0, v167, vcc
	global_load_dwordx4 v[166:169], v[166:167], off offset:384
	ds_read_b128 v[212:215], v131 offset:4640
	s_waitcnt lgkmcnt(4)
	v_mfma_f32_32x32x16_bf16 v[114:129], v[208:211], v[236:239], v[114:129]
	ds_read_b128 v[204:207], v131 offset:64
	ds_read_b128 v[216:219], v138 offset:18496
	s_waitcnt lgkmcnt(5)
	v_mfma_f32_32x32x16_bf16 v[98:113], v[208:211], v[240:243], v[98:113]
	ds_read_b128 v[224:227], v138 offset:23104
	s_waitcnt lgkmcnt(5)
	v_mfma_f32_32x32x16_bf16 v[82:97], v[208:211], v[244:247], v[82:97]
	ds_read_b128 v[228:231], v138 offset:27712
	s_waitcnt lgkmcnt(5)
	v_mfma_f32_32x32x16_bf16 v[66:81], v[208:211], v[248:251], v[66:81]
	ds_read_b128 v[232:235], v138 offset:32320
	s_waitcnt lgkmcnt(5)
	v_mfma_f32_32x32x16_bf16 v[50:65], v[212:215], v[236:239], v[50:65]
	v_lshl_add_u64 v[170:171], v[152:153], 0, s[8:9]
	v_add_co_u32_e32 v170, vcc, s35, v170
	s_nop 1
	v_addc_co_u32_e32 v171, vcc, 0, v171, vcc
	global_load_dwordx4 v[170:173], v[170:171], off offset:128
	v_mfma_f32_32x32x16_bf16 v[34:49], v[212:215], v[240:243], v[34:49]
	v_lshl_add_u64 v[174:175], v[152:153], 0, s[8:9]
	v_add_co_u32_e32 v174, vcc, s36, v174
	s_nop 1
	v_addc_co_u32_e32 v175, vcc, 0, v175, vcc
	global_load_dwordx4 v[174:177], v[174:175], off offset:128
	v_mfma_f32_32x32x16_bf16 v[18:33], v[212:215], v[244:247], v[18:33]
	v_lshl_add_u64 v[178:179], v[152:153], 0, s[8:9]
	v_add_co_u32_e32 v178, vcc, s37, v178
	s_nop 1
	v_addc_co_u32_e32 v179, vcc, 0, v179, vcc
	global_load_dwordx4 v[178:181], v[178:179], off offset:128
	v_mfma_f32_32x32x16_bf16 v[2:17], v[212:215], v[248:251], v[2:17]
	v_lshl_add_u64 v[184:185], v[152:153], 0, s[8:9]
	v_add_co_u32_e32 v184, vcc, s38, v184
	s_nop 1
	v_addc_co_u32_e32 v185, vcc, 0, v185, vcc
	global_load_dwordx4 v[184:187], v[184:185], off offset:128
	ds_read_b128 v[212:215], v131 offset:4672
	s_waitcnt lgkmcnt(4)
	v_mfma_f32_32x32x16_bf16 v[114:129], v[204:207], v[216:219], v[114:129]
	ds_read_b128 v[208:211], v131 offset:96
	ds_read_b128 v[236:239], v138 offset:18528
	s_waitcnt lgkmcnt(5)
	v_mfma_f32_32x32x16_bf16 v[98:113], v[204:207], v[224:227], v[98:113]
	ds_read_b128 v[240:243], v138 offset:23136
	s_waitcnt lgkmcnt(5)
	v_mfma_f32_32x32x16_bf16 v[82:97], v[204:207], v[228:231], v[82:97]
	ds_read_b128 v[244:247], v138 offset:27744
	s_waitcnt lgkmcnt(5)
	v_mfma_f32_32x32x16_bf16 v[66:81], v[204:207], v[232:235], v[66:81]
	ds_read_b128 v[248:251], v138 offset:32352
	s_waitcnt lgkmcnt(5)
	v_mfma_f32_32x32x16_bf16 v[50:65], v[212:215], v[216:219], v[50:65]
	v_lshl_add_u64 v[188:189], v[152:153], 0, s[8:9]
	v_add_co_u32_e32 v188, vcc, s39, v188
	s_nop 1
	v_addc_co_u32_e32 v189, vcc, 0, v189, vcc
	global_load_dwordx4 v[188:191], v[188:189], off offset:128
	v_mfma_f32_32x32x16_bf16 v[34:49], v[212:215], v[224:227], v[34:49]
	v_lshl_add_u64 v[192:193], v[152:153], 0, s[8:9]
	v_add_co_u32_e32 v192, vcc, s40, v192
	s_nop 1
	v_addc_co_u32_e32 v193, vcc, 0, v193, vcc
	global_load_dwordx4 v[192:195], v[192:193], off offset:128
	v_mfma_f32_32x32x16_bf16 v[18:33], v[212:215], v[228:231], v[18:33]
	v_lshl_add_u64 v[196:197], v[152:153], 0, s[8:9]
	v_add_co_u32_e32 v196, vcc, s41, v196
	s_nop 1
	v_addc_co_u32_e32 v197, vcc, 0, v197, vcc
	global_load_dwordx4 v[196:199], v[196:197], off offset:128
	v_mfma_f32_32x32x16_bf16 v[2:17], v[212:215], v[232:235], v[2:17]
	v_lshl_add_u64 v[200:201], v[152:153], 0, s[8:9]
	v_add_co_u32_e32 v200, vcc, s42, v200
	s_nop 1
	v_addc_co_u32_e32 v201, vcc, 0, v201, vcc
	global_load_dwordx4 v[200:203], v[200:201], off offset:128
	ds_read_b128 v[212:215], v131 offset:4704
	s_waitcnt lgkmcnt(4)
	v_mfma_f32_32x32x16_bf16 v[114:129], v[208:211], v[236:239], v[114:129]
	s_waitcnt lgkmcnt(3)
	v_mfma_f32_32x32x16_bf16 v[98:113], v[208:211], v[240:243], v[98:113]
	s_waitcnt lgkmcnt(2)
	v_mfma_f32_32x32x16_bf16 v[82:97], v[208:211], v[244:247], v[82:97]
	s_waitcnt lgkmcnt(1)
	v_mfma_f32_32x32x16_bf16 v[66:81], v[208:211], v[248:251], v[66:81]
	s_waitcnt lgkmcnt(0)
	v_mfma_f32_32x32x16_bf16 v[50:65], v[212:215], v[236:239], v[50:65]
	v_mfma_f32_32x32x16_bf16 v[34:49], v[212:215], v[240:243], v[34:49]
	v_mfma_f32_32x32x16_bf16 v[18:33], v[212:215], v[244:247], v[18:33]
	v_mfma_f32_32x32x16_bf16 v[2:17], v[212:215], v[248:251], v[2:17]
	s_setprio 0
	s_add_u32 s8, s8, 0x80
	s_addc_u32 s9, s9, 0
	s_cmpk_lg_i32 s8, 0x700
	s_barrier
; #define GW_LOAD(KOFF) GW_LOAD2(KOFF, 0)
;     ...
;   GW_LOAD(0)
;   GW_STORE()
;   __syncthreads();
;   const int nk = K >> 6;
;   const char* Ab = smem + (wm * 64 + (lane & 31)) * LSTR + (lane >> 5) * 16;
;   const char* Bb = smem + WTILE_A + (wn * 128 + (lane & 31)) * LSTR + (lane >> 5) * 16;
;   for (int kt = 0; kt < nk; ++kt) {
;     const int kn = (kt + 1 < nk) ? kt + 1 : kt;
;     GW_LOAD2(kn * 64, kn * bkstep)
;     __builtin_amdgcn_sched_barrier(0);
;     __builtin_amdgcn_s_setprio(1);
; #pragma unroll
;     for (int st = 0; st < 4; ++st) {
;       bf16x8 a0 = *(const bf16x8*)(Ab + st * 32);
;       bf16x8 a1 = *(const bf16x8*)(Ab + 32 * LSTR + st * 32);
;       bf16x8 b0 = *(const bf16x8*)(Bb + st * 32);
;       bf16x8 b1 = *(const bf16x8*)(Bb + 32 * LSTR + st * 32);
;       bf16x8 b2 = *(const bf16x8*)(Bb + 64 * LSTR + st * 32);
;       bf16x8 b3 = *(const bf16x8*)(Bb + 96 * LSTR + st * 32);
;       acc[0][0] = mfma32(a0, b0, acc[0][0]);
;       acc[0][1] = mfma32(a0, b1, acc[0][1]);
;       acc[0][2] = mfma32(a0, b2, acc[0][2]);
;       acc[0][3] = mfma32(a0, b3, acc[0][3]);
;       acc[1][0] = mfma32(a1, b0, acc[1][0]);
;       acc[1][1] = mfma32(a1, b1, acc[1][1]);
;       acc[1][2] = mfma32(a1, b2, acc[1][2]);
;       acc[1][3] = mfma32(a1, b3, acc[1][3]);
;     }
;     __builtin_amdgcn_s_setprio(0);
;     __builtin_amdgcn_sched_barrier(0);
;     __syncthreads();
;     GW_STORE()
;     __syncthreads();
	s_waitcnt vmcnt(11)
	ds_write_b128 v130, v[154:157]
	s_waitcnt vmcnt(10)
	ds_write_b128 v130, v[158:161] offset:4608
	s_waitcnt vmcnt(9)
	ds_write_b128 v130, v[162:165] offset:9216
	s_waitcnt vmcnt(8)
	ds_write_b128 v130, v[166:169] offset:13824
	s_waitcnt vmcnt(7)
	ds_write_b128 v130, v[170:173] offset:18432
	s_waitcnt vmcnt(6)
	ds_write_b128 v130, v[174:177] offset:23040
	s_waitcnt vmcnt(5)
	ds_write_b128 v130, v[178:181] offset:27648
	s_waitcnt vmcnt(4)
	ds_write_b128 v130, v[184:187] offset:32256
	s_waitcnt vmcnt(3)
	ds_write_b128 v130, v[188:191] offset:36864
	s_waitcnt vmcnt(2)
	ds_write_b128 v130, v[192:195] offset:41472
	s_waitcnt vmcnt(1)
	ds_write_b128 v130, v[196:199] offset:46080
	s_waitcnt vmcnt(0)
	ds_write_b128 v130, v[200:203] offset:50688
	s_waitcnt lgkmcnt(0)
	s_barrier
	s_cbranch_scc1 .LBB0_1284
	s_setprio 1
	ds_read_b128 v[204:207], v131 offset:0
	ds_read_b128 v[216:219], v138 offset:18432
	ds_read_b128 v[224:227], v138 offset:23040
	ds_read_b128 v[228:231], v138 offset:27648
	ds_read_b128 v[232:235], v138 offset:32256
	ds_read_b128 v[212:215], v131 offset:4608
	s_waitcnt lgkmcnt(4)
	v_mfma_f32_32x32x16_bf16 v[114:129], v[204:207], v[216:219], v[114:129]
	ds_read_b128 v[208:211], v131 offset:32
	ds_read_b128 v[236:239], v138 offset:18464
	s_waitcnt lgkmcnt(5)
	v_mfma_f32_32x32x16_bf16 v[98:113], v[204:207], v[224:227], v[98:113]
	ds_read_b128 v[240:243], v138 offset:23072
	s_waitcnt lgkmcnt(5)
	v_mfma_f32_32x32x16_bf16 v[82:97], v[204:207], v[228:231], v[82:97]
	ds_read_b128 v[244:247], v138 offset:27680
	s_waitcnt lgkmcnt(5)
	v_mfma_f32_32x32x16_bf16 v[66:81], v[204:207], v[232:235], v[66:81]
	ds_read_b128 v[248:251], v138 offset:32288
	s_waitcnt lgkmcnt(5)
	v_mfma_f32_32x32x16_bf16 v[50:65], v[212:215], v[216:219], v[50:65]
	v_lshl_add_u64 v[154:155], v[150:151], 0, s[8:9]
	v_add_co_u32_e32 v154, vcc, s43, v154
	s_nop 1
	v_addc_co_u32_e32 v155, vcc, 0, v155, vcc
	global_load_dwordx4 v[154:157], v[154:155], off offset:384
	v_mfma_f32_32x32x16_bf16 v[34:49], v[212:215], v[224:227], v[34:49]
	v_lshl_add_u64 v[158:159], v[150:151], 0, s[8:9]
	v_add_co_u32_e32 v158, vcc, s44, v158
	s_nop 1
	v_addc_co_u32_e32 v159, vcc, 0, v159, vcc
	global_load_dwordx4 v[158:161], v[158:159], off offset:384
	v_mfma_f32_32x32x16_bf16 v[18:33], v[212:215], v[228:231], v[18:33]
	v_lshl_add_u64 v[162:163], v[150:151], 0, s[8:9]
	v_add_co_u32_e32 v162, vcc, s45, v162
	s_nop 1
	v_addc_co_u32_e32 v163, vcc, 0, v163, vcc
	global_load_dwordx4 v[162:165], v[162:163], off offset:384
	v_mfma_f32_32x32x16_bf16 v[2:17], v[212:215], v[232:235], v[2:17]
	v_lshl_add_u64 v[166:167], v[150:151], 0, s[8:9]
	v_add_co_u32_e32 v166, vcc, s46, v166
	s_nop 1
	v_addc_co_u32_e32 v167, vcc, 0, v167, vcc
	global_load_dwordx4 v[166:169], v[166:167], off offset:384
	ds_read_b128 v[212:215], v131 offset:4640
	s_waitcnt lgkmcnt(4)
	v_mfma_f32_32x32x16_bf16 v[114:129], v[208:211], v[236:239], v[114:129]
	ds_read_b128 v[204:207], v131 offset:64
	ds_read_b128 v[216:219], v138 offset:18496
	s_waitcnt lgkmcnt(5)
	v_mfma_f32_32x32x16_bf16 v[98:113], v[208:211], v[240:243], v[98:113]
	ds_read_b128 v[224:227], v138 offset:23104
	s_waitcnt lgkmcnt(5)
	v_mfma_f32_32x32x16_bf16 v[82:97], v[208:211], v[244:247], v[82:97]
	ds_read_b128 v[228:231], v138 offset:27712
	s_waitcnt lgkmcnt(5)
	v_mfma_f32_32x32x16_bf16 v[66:81], v[208:211], v[248:251], v[66:81]
	ds_read_b128 v[232:235], v138 offset:32320
	s_waitcnt lgkmcnt(5)
	v_mfma_f32_32x32x16_bf16 v[50:65], v[212:215], v[236:239], v[50:65]
	v_lshl_add_u64 v[170:171], v[152:153], 0, s[8:9]
	v_add_co_u32_e32 v170, vcc, s35, v170
	s_nop 1
	v_addc_co_u32_e32 v171, vcc, 0, v171, vcc
	global_load_dwordx4 v[170:173], v[170:171], off offset:128
	v_mfma_f32_32x32x16_bf16 v[34:49], v[212:215], v[240:243], v[34:49]
	v_lshl_add_u64 v[174:175], v[152:153], 0, s[8:9]
	v_add_co_u32_e32 v174, vcc, s36, v174
	s_nop 1
	v_addc_co_u32_e32 v175, vcc, 0, v175, vcc
	global_load_dwordx4 v[174:177], v[174:175], off offset:128
	v_mfma_f32_32x32x16_bf16 v[18:33], v[212:215], v[244:247], v[18:33]
	v_lshl_add_u64 v[178:179], v[152:153], 0, s[8:9]
	v_add_co_u32_e32 v178, vcc, s37, v178
	s_nop 1
	v_addc_co_u32_e32 v179, vcc, 0, v179, vcc
	global_load_dwordx4 v[178:181], v[178:179], off offset:128
	v_mfma_f32_32x32x16_bf16 v[2:17], v[212:215], v[248:251], v[2:17]
	v_lshl_add_u64 v[184:185], v[152:153], 0, s[8:9]
	v_add_co_u32_e32 v184, vcc, s38, v184
	s_nop 1
	v_addc_co_u32_e32 v185, vcc, 0, v185, vcc
	global_load_dwordx4 v[184:187], v[184:185], off offset:128
	ds_read_b128 v[212:215], v131 offset:4672
	s_waitcnt lgkmcnt(4)
	v_mfma_f32_32x32x16_bf16 v[114:129], v[204:207], v[216:219], v[114:129]
	ds_read_b128 v[208:211], v131 offset:96
	ds_read_b128 v[236:239], v138 offset:18528
	s_waitcnt lgkmcnt(5)
	v_mfma_f32_32x32x16_bf16 v[98:113], v[204:207], v[224:227], v[98:113]
	ds_read_b128 v[240:243], v138 offset:23136
	s_waitcnt lgkmcnt(5)
	v_mfma_f32_32x32x16_bf16 v[82:97], v[204:207], v[228:231], v[82:97]
	ds_read_b128 v[244:247], v138 offset:27744
	s_waitcnt lgkmcnt(5)
	v_mfma_f32_32x32x16_bf16 v[66:81], v[204:207], v[232:235], v[66:81]
	ds_read_b128 v[248:251], v138 offset:32352
	s_waitcnt lgkmcnt(5)
	v_mfma_f32_32x32x16_bf16 v[50:65], v[212:215], v[216:219], v[50:65]
	v_lshl_add_u64 v[188:189], v[152:153], 0, s[8:9]
	v_add_co_u32_e32 v188, vcc, s39, v188
	s_nop 1
	v_addc_co_u32_e32 v189, vcc, 0, v189, vcc
	global_load_dwordx4 v[188:191], v[188:189], off offset:128
	v_mfma_f32_32x32x16_bf16 v[34:49], v[212:215], v[224:227], v[34:49]
	v_lshl_add_u64 v[192:193], v[152:153], 0, s[8:9]
	v_add_co_u32_e32 v192, vcc, s40, v192
	s_nop 1
	v_addc_co_u32_e32 v193, vcc, 0, v193, vcc
	global_load_dwordx4 v[192:195], v[192:193], off offset:128
	v_mfma_f32_32x32x16_bf16 v[18:33], v[212:215], v[228:231], v[18:33]
	v_lshl_add_u64 v[196:197], v[152:153], 0, s[8:9]
	v_add_co_u32_e32 v196, vcc, s41, v196
	s_nop 1
	v_addc_co_u32_e32 v197, vcc, 0, v197, vcc
	global_load_dwordx4 v[196:199], v[196:197], off offset:128
	v_mfma_f32_32x32x16_bf16 v[2:17], v[212:215], v[232:235], v[2:17]
	v_lshl_add_u64 v[200:201], v[152:153], 0, s[8:9]
	v_add_co_u32_e32 v200, vcc, s42, v200
	s_nop 1
	v_addc_co_u32_e32 v201, vcc, 0, v201, vcc
	global_load_dwordx4 v[200:203], v[200:201], off offset:128
	ds_read_b128 v[212:215], v131 offset:4704
	s_waitcnt lgkmcnt(4)
	v_mfma_f32_32x32x16_bf16 v[114:129], v[208:211], v[236:239], v[114:129]
	s_waitcnt lgkmcnt(3)
	v_mfma_f32_32x32x16_bf16 v[98:113], v[208:211], v[240:243], v[98:113]
	s_waitcnt lgkmcnt(2)
	v_mfma_f32_32x32x16_bf16 v[82:97], v[208:211], v[244:247], v[82:97]
	s_waitcnt lgkmcnt(1)
	v_mfma_f32_32x32x16_bf16 v[66:81], v[208:211], v[248:251], v[66:81]
	s_waitcnt lgkmcnt(0)
	v_mfma_f32_32x32x16_bf16 v[50:65], v[212:215], v[236:239], v[50:65]
	v_mfma_f32_32x32x16_bf16 v[34:49], v[212:215], v[240:243], v[34:49]
	v_mfma_f32_32x32x16_bf16 v[18:33], v[212:215], v[244:247], v[18:33]
	v_mfma_f32_32x32x16_bf16 v[2:17], v[212:215], v[248:251], v[2:17]
	s_setprio 0
	s_add_u32 s8, s8, 0x80
	s_addc_u32 s9, s9, 0
	s_barrier
; #define GW_LOAD(KOFF) GW_LOAD2(KOFF, 0)
;     ...
;   GW_LOAD(0)
;   GW_STORE()
;   __syncthreads();
;   const int nk = K >> 6;
;   const char* Ab = smem + (wm * 64 + (lane & 31)) * LSTR + (lane >> 5) * 16;
;   const char* Bb = smem + WTILE_A + (wn * 128 + (lane & 31)) * LSTR + (lane >> 5) * 16;
;   for (int kt = 0; kt < nk; ++kt) {
;     const int kn = (kt + 1 < nk) ? kt + 1 : kt;
;     GW_LOAD2(kn * 64, kn * bkstep)
;     __builtin_amdgcn_sched_barrier(0);
;     __builtin_amdgcn_s_setprio(1);
; #pragma unroll
;     for (int st = 0; st < 4; ++st) {
;       bf16x8 a0 = *(const bf16x8*)(Ab + st * 32);
;       bf16x8 a1 = *(const bf16x8*)(Ab + 32 * LSTR + st * 32);
;       bf16x8 b0 = *(const bf16x8*)(Bb + st * 32);
;       bf16x8 b1 = *(const bf16x8*)(Bb + 32 * LSTR + st * 32);
;       bf16x8 b2 = *(const bf16x8*)(Bb + 64 * LSTR + st * 32);
;       bf16x8 b3 = *(const bf16x8*)(Bb + 96 * LSTR + st * 32);
;       acc[0][0] = mfma32(a0, b0, acc[0][0]);
;       acc[0][1] = mfma32(a0, b1, acc[0][1]);
;       acc[0][2] = mfma32(a0, b2, acc[0][2]);
;       acc[0][3] = mfma32(a0, b3, acc[0][3]);
;       acc[1][0] = mfma32(a1, b0, acc[1][0]);
;       acc[1][1] = mfma32(a1, b1, acc[1][1]);
;       acc[1][2] = mfma32(a1, b2, acc[1][2]);
;       acc[1][3] = mfma32(a1, b3, acc[1][3]);
;     }
;     __builtin_amdgcn_s_setprio(0);
; __device__ __forceinline__ void inproj_tile(const Params& P, int l, int mt, int ntw, char* smem) {
;     ...
;   const int row0 = mt * 128;
;   const bool isctx = row0 >= NLAT;
;   const int b = isctx ? ((row0 - NLAT) >> 8) : (row0 >> 12);
;   const int pos0 = isctx ? ((row0 - NLAT) & 255) : (row0 & 4095);
	s_waitcnt vmcnt(11)
	ds_write_b128 v130, v[154:157]
	s_waitcnt vmcnt(10)
	ds_write_b128 v130, v[158:161] offset:4608
	s_waitcnt vmcnt(9)
	ds_write_b128 v130, v[162:165] offset:9216
	s_waitcnt vmcnt(8)
	ds_write_b128 v130, v[166:169] offset:13824
	s_waitcnt vmcnt(7)
	ds_write_b128 v130, v[170:173] offset:18432
	s_waitcnt vmcnt(6)
	ds_write_b128 v130, v[174:177] offset:23040
	s_waitcnt vmcnt(5)
	ds_write_b128 v130, v[178:181] offset:27648
	s_waitcnt vmcnt(4)
	ds_write_b128 v130, v[184:187] offset:32256
	s_waitcnt vmcnt(3)
	ds_write_b128 v130, v[188:191] offset:36864
	s_waitcnt vmcnt(2)
	ds_write_b128 v130, v[192:195] offset:41472
	s_waitcnt vmcnt(1)
	ds_write_b128 v130, v[196:199] offset:46080
	s_waitcnt vmcnt(0)
	ds_write_b128 v130, v[200:203] offset:50688
	s_waitcnt lgkmcnt(0)
	s_barrier
	s_nop 0
	s_nop 0
	v_add_co_u32_e32 v132, vcc, 0x10000, v142
	s_mov_b32 s58, 0
	s_nop 0
	v_addc_co_u32_e32 v133, vcc, 0, v143, vcc
	v_add_co_u32_e32 v132, vcc, 0x20000, v142
	s_nop 1
	v_addc_co_u32_e32 v133, vcc, 0, v143, vcc
	v_add_co_u32_e32 v148, vcc, 0x30000, v142
	s_nop 1
	v_addc_co_u32_e32 v149, vcc, 0, v143, vcc
	v_add_co_u32_e32 v132, vcc, 0x40000, v142
	s_nop 1
	v_addc_co_u32_e32 v133, vcc, 0, v143, vcc
	v_add_co_u32_e32 v148, vcc, 0x50000, v142
	s_nop 1
	v_addc_co_u32_e32 v149, vcc, 0, v143, vcc
	v_add_co_u32_e32 v132, vcc, 0x60000, v142
	s_nop 1
	v_addc_co_u32_e32 v133, vcc, 0, v143, vcc
	v_add_co_u32_e32 v142, vcc, 0x70000, v142
	s_nop 1
	v_addc_co_u32_e32 v143, vcc, 0, v143, vcc
	s_setprio 1
	ds_read_b128 v[196:199], v131 offset:0
	ds_read_b128 v[208:211], v138 offset:18432
	ds_read_b128 v[212:215], v138 offset:23040
	ds_read_b128 v[216:219], v138 offset:27648
	ds_read_b128 v[224:227], v138 offset:32256
	ds_read_b128 v[204:207], v131 offset:4608
	s_waitcnt lgkmcnt(4)
	v_mfma_f32_32x32x16_bf16 v[114:129], v[196:199], v[208:211], v[114:129]
	ds_read_b128 v[200:203], v131 offset:32
	ds_read_b128 v[228:231], v138 offset:18464
	s_waitcnt lgkmcnt(5)
	v_mfma_f32_32x32x16_bf16 v[98:113], v[196:199], v[212:215], v[98:113]
	ds_read_b128 v[232:235], v138 offset:23072
	s_waitcnt lgkmcnt(5)
	v_mfma_f32_32x32x16_bf16 v[82:97], v[196:199], v[216:219], v[82:97]
	ds_read_b128 v[236:239], v138 offset:27680
	s_waitcnt lgkmcnt(5)
	v_mfma_f32_32x32x16_bf16 v[66:81], v[196:199], v[224:227], v[66:81]
	ds_read_b128 v[240:243], v138 offset:32288
	s_waitcnt lgkmcnt(5)
	v_mfma_f32_32x32x16_bf16 v[50:65], v[204:207], v[208:211], v[50:65]
	v_mfma_f32_32x32x16_bf16 v[34:49], v[204:207], v[212:215], v[34:49]
	v_mfma_f32_32x32x16_bf16 v[18:33], v[204:207], v[216:219], v[18:33]
	v_mfma_f32_32x32x16_bf16 v[2:17], v[204:207], v[224:227], v[2:17]
	ds_read_b128 v[204:207], v131 offset:4640
	s_waitcnt lgkmcnt(4)
	v_mfma_f32_32x32x16_bf16 v[114:129], v[200:203], v[228:231], v[114:129]
	ds_read_b128 v[196:199], v131 offset:64
	ds_read_b128 v[208:211], v138 offset:18496
	s_waitcnt lgkmcnt(5)
	v_mfma_f32_32x32x16_bf16 v[98:113], v[200:203], v[232:235], v[98:113]
	ds_read_b128 v[212:215], v138 offset:23104
	s_waitcnt lgkmcnt(5)
	v_mfma_f32_32x32x16_bf16 v[82:97], v[200:203], v[236:239], v[82:97]
	ds_read_b128 v[216:219], v138 offset:27712
	s_waitcnt lgkmcnt(5)
	v_mfma_f32_32x32x16_bf16 v[66:81], v[200:203], v[240:243], v[66:81]
	ds_read_b128 v[224:227], v138 offset:32320
	s_waitcnt lgkmcnt(5)
	v_mfma_f32_32x32x16_bf16 v[50:65], v[204:207], v[228:231], v[50:65]
	v_mfma_f32_32x32x16_bf16 v[34:49], v[204:207], v[232:235], v[34:49]
	v_mfma_f32_32x32x16_bf16 v[18:33], v[204:207], v[236:239], v[18:33]
	v_mfma_f32_32x32x16_bf16 v[2:17], v[204:207], v[240:243], v[2:17]
	ds_read_b128 v[204:207], v131 offset:4672
	s_waitcnt lgkmcnt(4)
	v_mfma_f32_32x32x16_bf16 v[114:129], v[196:199], v[208:211], v[114:129]
	ds_read_b128 v[200:203], v131 offset:96
	ds_read_b128 v[228:231], v138 offset:18528
	s_waitcnt lgkmcnt(5)
	v_mfma_f32_32x32x16_bf16 v[98:113], v[196:199], v[212:215], v[98:113]
	ds_read_b128 v[232:235], v138 offset:23136
	s_waitcnt lgkmcnt(5)
	v_mfma_f32_32x32x16_bf16 v[82:97], v[196:199], v[216:219], v[82:97]
	ds_read_b128 v[236:239], v138 offset:27744
	s_waitcnt lgkmcnt(5)
	v_mfma_f32_32x32x16_bf16 v[66:81], v[196:199], v[224:227], v[66:81]
	ds_read_b128 v[240:243], v138 offset:32352
	s_waitcnt lgkmcnt(5)
	v_mfma_f32_32x32x16_bf16 v[50:65], v[204:207], v[208:211], v[50:65]
	v_mfma_f32_32x32x16_bf16 v[34:49], v[204:207], v[212:215], v[34:49]
	v_mfma_f32_32x32x16_bf16 v[18:33], v[204:207], v[216:219], v[18:33]
	v_mfma_f32_32x32x16_bf16 v[2:17], v[204:207], v[224:227], v[2:17]
	ds_read_b128 v[204:207], v131 offset:4704
	s_waitcnt lgkmcnt(4)
	v_mfma_f32_32x32x16_bf16 v[114:129], v[200:203], v[228:231], v[114:129]
	s_waitcnt lgkmcnt(3)
	v_mfma_f32_32x32x16_bf16 v[98:113], v[200:203], v[232:235], v[98:113]
	s_waitcnt lgkmcnt(2)
	v_mfma_f32_32x32x16_bf16 v[82:97], v[200:203], v[236:239], v[82:97]
	s_waitcnt lgkmcnt(1)
	v_mfma_f32_32x32x16_bf16 v[66:81], v[200:203], v[240:243], v[66:81]
	s_waitcnt lgkmcnt(0)
	v_mfma_f32_32x32x16_bf16 v[50:65], v[204:207], v[228:231], v[50:65]
	v_mfma_f32_32x32x16_bf16 v[34:49], v[204:207], v[232:235], v[34:49]
	v_mfma_f32_32x32x16_bf16 v[18:33], v[204:207], v[236:239], v[18:33]
	v_mfma_f32_32x32x16_bf16 v[2:17], v[204:207], v[240:243], v[2:17]
	s_setprio 0
	s_lshl_b32 s18, s10, 7
	s_cmpk_lt_i32 s10, 0x100
	s_cselect_b64 s[8:9], -1, 0
	s_add_i32 s6, s18, 0xffff8000
	s_and_b32 s57, s18, 0x80
	s_barrier
; __device__ __forceinline__ void inproj_tile(const Params& P, int l, int mt, int ntw, char* smem) {
;     ...
;   float* cs = (float*)smem;
;   const int row0 = mt * 128;
;   const bool isctx = row0 >= NLAT;
;   const int b = isctx ? ((row0 - NLAT) >> 8) : (row0 >> 12);
;   const int pos0 = isctx ? ((row0 - NLAT) & 255) : (row0 & 4095);
;   const int tk0 = isctx ? (SEQ + pos0) : pos0;
;   int tid_ = threadIdx.x;
;   asm volatile("" : "+v"(tid_));
;   const int lane = tid_ & 63, wave = tid_ >> 6;
;   const int r = 32 * wave + (lane & 31), half = lane >> 5;
;   const size_t grow = (size_t)row0 + r;
;   const float* crow = cs + r * CSTR + half * 64;
; #pragma unroll 1
;   for (int hsel = 0; hsel < 2; ++hsel) {
;     const int nt = ntw * 2 + hsel;
;     wide_acc_to_lds(acc, cs, hsel);
;     if (nt < 4) {
;       const int part = nt >> 1, cb = (nt & 1) * 128;
;       if (!isctx) {
;         u16* base = WSP(u16, OFF_FTT) + (size_t)b * 256 * 8192 + part * 4096 + pos0;
;         epi_transposed(cs, [&](int ch) { return base + (size_t)(cb + ch) * 8192; });
;       } else {
;         u16* base = WSP(u16, OFF_FTTC) + (size_t)b * 256 * 512 + part * 256 + pos0;
;         epi_transposed(cs, [&](int ch) { return base + (size_t)(cb + ch) * 512; });
;       }
;     } else if (nt < 7 || (nt >= 10 && nt < 13)) {
;       const bool isq = nt < 7;
;       const int head = (isq ? (nt - 4) : (nt - 10)) * 2 + half;
;       const float* g = (isq ? P.na_qn_g : P.na_kn_g) + l * 64;
;       float ss = 0.f;
; #pragma unroll
;       for (int q = 0; q < 16; ++q) {
;         float4 a = *(const float4*)(crow + q * 4);
;         ss += a.x * a.x + a.y * a.y + a.z * a.z + a.w * a.w;
;       }
;       const float rinv = rsqrtf(ss * (1.f / 64.f) + EPS) * (isq ? (0.125f * LOG2E) : 1.f);
;       u16* dst = WSP(u16, isq ? OFF_QN : OFF_KN) + grow * 384 + head * 64;
; #pragma unroll 1
;       for (int q = 0; q < 8; ++q) {
;         float4 a = *(const float4*)(crow + q * 8), c = *(const float4*)(crow + q * 8 + 4);
;         float4 ga = *(const float4*)(g + q * 8), gc = *(const float4*)(g + q * 8 + 4);
;         *(uint4*)(dst + q * 8) = pack8(a.x * rinv * ga.x, a.y * rinv * ga.y, a.z * rinv * ga.z, a.w * rinv * ga.w,
;                                        c.x * rinv * gc.x, c.y * rinv * gc.y, c.z * rinv * gc.z, c.w * rinv * gc.w);
;       }
;     } else if ((nt >= 7 && nt < 10) || (nt >= 16 && nt < 19)) {
	s_lshr_b32 s6, s6, 8
	s_ashr_i32 s12, s10, 5
	s_and_b32 s59, s18, 0xf80
	s_or_b32 s11, s57, 0x1000
	v_mov_b32_e32 v154, v134
	s_waitcnt lgkmcnt(0)
	s_cmpk_gt_i32 s10, 0xff
	s_cselect_b32 s60, s11, s59
	v_ashrrev_i32_e32 v155, 1, v154
	v_bfi_b32 v130, s47, v155, v154
	s_movk_i32 s11, 0x210
	v_lshlrev_b32_e32 v133, 1, v154
	s_cselect_b32 s13, s57, s59
	v_mul_lo_u32 v132, v130, s11
	v_and_b32_e32 v184, 64, v133
	s_cselect_b32 s10, s6, s12
	v_lshl_add_u32 v185, v184, 2, v132
	s_lshl_b32 s33, s16, 1
	v_add_u32_e32 v132, s13, v155
	s_ashr_i32 s13, s12, 31
	s_lshl_b32 s16, s16, 12
	s_ashr_i32 s19, s18, 31
	s_lshl_b64 s[20:21], s[12:13], 22
	s_ashr_i32 s17, s16, 31
	s_lshl_b64 s[22:23], s[6:7], 18
	s_mul_i32 s11, s10, 6
	s_cmp_gt_u32 s33, 9
	s_mul_i32 s61, s10, 0x330000
	s_mul_hi_i32 s62, s11, 0x88000
	s_cselect_b64 s[10:11], -1, 0
	s_cmp_gt_u32 s33, 21
	s_cselect_b64 s[12:13], -1, 0
	s_cmp_lt_u32 s33, 16
	v_ashrrev_i32_e32 v132, 2, v132
	s_cselect_b64 s[24:25], -1, 0
	v_ashrrev_i32_e32 v131, 31, v130
	v_and_b32_e32 v142, -16, v132
	v_lshlrev_b32_e32 v132, 4, v130
	s_and_b64 s[24:25], s[24:25], exec
	v_and_b32_e32 v138, 0x3f0, v132
	s_cselect_b32 s6, s49, 0x343b1100
	v_lshl_add_u64 v[130:131], s[18:19], 0, v[130:131]
	v_mov_b64_e32 v[132:133], s[90:91]
	s_cselect_b32 s56, s48, 0x1ffffed
	v_mad_u64_u32 v[146:147], s[18:19], v130, s50, v[132:133]
	s_add_u32 s6, s90, s6
	s_addc_u32 s18, s91, 0
	s_add_u32 s6, s6, s61
	s_addc_u32 s19, s18, s62
	s_lshl_b32 s18, s60, 1
	s_add_u32 s18, s6, s18
	s_addc_u32 s19, s19, 0
	v_mov_b32_e32 v141, v139
	s_add_u32 s6, s28, s20
	v_lshl_add_u64 v[148:149], s[18:19], 0, v[140:141]
	s_addc_u32 s18, s29, s21
	s_lshl_b64 s[16:17], s[16:17], 1
	s_add_u32 s6, s6, s16
	s_addc_u32 s17, s18, s17
	s_lshl_b32 s16, s59, 1
	s_add_u32 s16, s6, s16
	s_addc_u32 s17, s17, 0
	s_add_u32 s6, s30, s22
	v_lshl_add_u64 v[150:151], s[16:17], 0, v[140:141]
	s_addc_u32 s18, s31, s23
	s_lshl_b64 s[16:17], s[14:15], 1
	s_add_u32 s6, s6, s16
	s_addc_u32 s15, s18, s17
	s_lshl_b32 s16, s57, 1
	s_add_u32 s16, s6, s16
	v_and_b32_e32 v156, 31, v154
	v_mov_b64_e32 v[144:145], v[138:139]
	s_addc_u32 s17, s15, 0
	v_lshrrev_b32_e32 v132, 5, v155
	v_bfe_u32 v138, v154, 5, 1
	v_lshl_add_u64 v[152:153], s[16:17], 0, v[140:141]
	v_mul_lo_u32 v132, v132, s51
	v_mul_u32_u24_e32 v133, 0x210, v156
	v_lshlrev_b32_e32 v141, 8, v138
	v_add3_u32 v141, v132, v133, v141
	v_mad_u64_u32 v[132:133], s[16:17], v130, s52, 0
	v_mad_i32_i24 v147, v131, s50, v147
	v_mad_i32_i24 v131, v131, s52, v133
	v_lshl_or_b32 v130, v138, 7, v132
	v_ashrrev_i32_e32 v143, 31, v142
	v_lshl_add_u64 v[154:155], s[4:5], 0, v[130:131]
	s_add_i32 s57, s14, 0xfffff500
	s_mov_b64 s[14:15], -1
	s_branch .LBB0_1287

;     ...
;   for (int kt = 0; kt < nk; ++kt) {
;     const int kn = (kt + 1 < nk) ? kt + 1 : kt;
;     GW_LOAD2(kn * 64, kn * bkstep)
;     __builtin_amdgcn_sched_barrier(0);
;     __builtin_amdgcn_s_setprio(1);
; #pragma unroll
;     for (int st = 0; st < 4; ++st) {
;       bf16x8 a0 = *(const bf16x8*)(Ab + st * 32);
;       bf16x8 a1 = *(const bf16x8*)(Ab + 32 * LSTR + st * 32);
;       bf16x8 b0 = *(const bf16x8*)(Bb + st * 32);
;       bf16x8 b1 = *(const bf16x8*)(Bb + 32 * LSTR + st * 32);
;       bf16x8 b2 = *(const bf16x8*)(Bb + 64 * LSTR + st * 32);
;       bf16x8 b3 = *(const bf16x8*)(Bb + 96 * LSTR + st * 32);
;       acc[0][0] = mfma32(a0, b0, acc[0][0]);
;       acc[0][1] = mfma32(a0, b1, acc[0][1]);
;       acc[0][2] = mfma32(a0, b2, acc[0][2]);
;       acc[0][3] = mfma32(a0, b3, acc[0][3]);
;       acc[1][0] = mfma32(a1, b0, acc[1][0]);
;       acc[1][1] = mfma32(a1, b1, acc[1][1]);
;       acc[1][2] = mfma32(a1, b2, acc[1][2]);
;       acc[1][3] = mfma32(a1, b3, acc[1][3]);
;     }
;     __builtin_amdgcn_s_setprio(0);
;     __builtin_amdgcn_sched_barrier(0);
;     __syncthreads();
;     GW_STORE()
;     __syncthreads();
;   }
.LBB0_1715:
	s_setprio 1
	ds_read_b128 v[200:203], v130 offset:0
	ds_read_b128 v[212:215], v133 offset:18432
	ds_read_b128 v[216:219], v133 offset:23040
	ds_read_b128 v[224:227], v133 offset:27648
	ds_read_b128 v[228:231], v133 offset:32256
	ds_read_b128 v[208:211], v130 offset:4608
	s_waitcnt lgkmcnt(4)
	v_mfma_f32_32x32x16_bf16 v[114:129], v[200:203], v[212:215], v[114:129]
	ds_read_b128 v[204:207], v130 offset:32
	ds_read_b128 v[232:235], v133 offset:18464
	s_waitcnt lgkmcnt(5)
	v_mfma_f32_32x32x16_bf16 v[98:113], v[200:203], v[216:219], v[98:113]
	ds_read_b128 v[236:239], v133 offset:23072
	s_waitcnt lgkmcnt(5)
	v_mfma_f32_32x32x16_bf16 v[82:97], v[200:203], v[224:227], v[82:97]
	ds_read_b128 v[240:243], v133 offset:27680
	s_waitcnt lgkmcnt(5)
	v_mfma_f32_32x32x16_bf16 v[66:81], v[200:203], v[228:231], v[66:81]
	ds_read_b128 v[244:247], v133 offset:32288
	s_waitcnt lgkmcnt(5)
	v_mfma_f32_32x32x16_bf16 v[50:65], v[208:211], v[212:215], v[50:65]
	v_lshl_add_u64 v[152:153], v[148:149], 0, s[14:15]
	v_add_co_u32_e32 v152, vcc, s37, v152
	s_nop 1
	v_addc_co_u32_e32 v153, vcc, 0, v153, vcc
	global_load_dwordx4 v[152:155], v[152:153], off offset:384
	v_mfma_f32_32x32x16_bf16 v[34:49], v[208:211], v[216:219], v[34:49]
	v_lshl_add_u64 v[156:157], v[148:149], 0, s[14:15]
	v_add_co_u32_e32 v156, vcc, s38, v156
	s_nop 1
	v_addc_co_u32_e32 v157, vcc, 0, v157, vcc
	global_load_dwordx4 v[156:159], v[156:157], off offset:384
	v_mfma_f32_32x32x16_bf16 v[18:33], v[208:211], v[224:227], v[18:33]
	v_lshl_add_u64 v[160:161], v[148:149], 0, s[14:15]
	v_add_co_u32_e32 v160, vcc, s39, v160
	s_nop 1
	v_addc_co_u32_e32 v161, vcc, 0, v161, vcc
	global_load_dwordx4 v[160:163], v[160:161], off offset:384
	v_mfma_f32_32x32x16_bf16 v[2:17], v[208:211], v[228:231], v[2:17]
	v_lshl_add_u64 v[164:165], v[148:149], 0, s[14:15]
	v_add_co_u32_e32 v164, vcc, s40, v164
	s_nop 1
	v_addc_co_u32_e32 v165, vcc, 0, v165, vcc
	global_load_dwordx4 v[164:167], v[164:165], off offset:384
	ds_read_b128 v[208:211], v130 offset:4640
	s_waitcnt lgkmcnt(4)
	v_mfma_f32_32x32x16_bf16 v[114:129], v[204:207], v[232:235], v[114:129]
	ds_read_b128 v[200:203], v130 offset:64
	ds_read_b128 v[212:215], v133 offset:18496
	s_waitcnt lgkmcnt(5)
	v_mfma_f32_32x32x16_bf16 v[98:113], v[204:207], v[236:239], v[98:113]
	ds_read_b128 v[216:219], v133 offset:23104
	s_waitcnt lgkmcnt(5)
	v_mfma_f32_32x32x16_bf16 v[82:97], v[204:207], v[240:243], v[82:97]
	ds_read_b128 v[224:227], v133 offset:27712
	s_waitcnt lgkmcnt(5)
	v_mfma_f32_32x32x16_bf16 v[66:81], v[204:207], v[244:247], v[66:81]
	ds_read_b128 v[228:231], v133 offset:32320
	s_waitcnt lgkmcnt(5)
	v_mfma_f32_32x32x16_bf16 v[50:65], v[208:211], v[232:235], v[50:65]
	v_lshl_add_u64 v[168:169], v[150:151], 0, s[14:15]
	v_add_co_u32_e32 v168, vcc, s41, v168
	s_nop 1
	v_addc_co_u32_e32 v169, vcc, 0, v169, vcc
	global_load_dwordx4 v[168:171], v[168:169], off offset:128
	v_mfma_f32_32x32x16_bf16 v[34:49], v[208:211], v[236:239], v[34:49]
	v_lshl_add_u64 v[172:173], v[150:151], 0, s[14:15]
	v_add_co_u32_e32 v172, vcc, s42, v172
	s_nop 1
	v_addc_co_u32_e32 v173, vcc, 0, v173, vcc
	global_load_dwordx4 v[172:175], v[172:173], off offset:128
	v_mfma_f32_32x32x16_bf16 v[18:33], v[208:211], v[240:243], v[18:33]
	v_lshl_add_u64 v[176:177], v[150:151], 0, s[14:15]
	v_add_co_u32_e32 v176, vcc, s43, v176
	s_nop 1
	v_addc_co_u32_e32 v177, vcc, 0, v177, vcc
	global_load_dwordx4 v[176:179], v[176:177], off offset:128
	v_mfma_f32_32x32x16_bf16 v[2:17], v[208:211], v[244:247], v[2:17]
	v_lshl_add_u64 v[180:181], v[150:151], 0, s[14:15]
	v_add_co_u32_e32 v180, vcc, s44, v180
	s_nop 1
	v_addc_co_u32_e32 v181, vcc, 0, v181, vcc
	global_load_dwordx4 v[180:183], v[180:181], off offset:128
	ds_read_b128 v[208:211], v130 offset:4672
	s_waitcnt lgkmcnt(4)
	v_mfma_f32_32x32x16_bf16 v[114:129], v[200:203], v[212:215], v[114:129]
	ds_read_b128 v[204:207], v130 offset:96
	ds_read_b128 v[232:235], v133 offset:18528
	s_waitcnt lgkmcnt(5)
	v_mfma_f32_32x32x16_bf16 v[98:113], v[200:203], v[216:219], v[98:113]
	ds_read_b128 v[236:239], v133 offset:23136
	s_waitcnt lgkmcnt(5)
	v_mfma_f32_32x32x16_bf16 v[82:97], v[200:203], v[224:227], v[82:97]
	ds_read_b128 v[240:243], v133 offset:27744
	s_waitcnt lgkmcnt(5)
	v_mfma_f32_32x32x16_bf16 v[66:81], v[200:203], v[228:231], v[66:81]
	ds_read_b128 v[244:247], v133 offset:32352
	s_waitcnt lgkmcnt(5)
	v_mfma_f32_32x32x16_bf16 v[50:65], v[208:211], v[212:215], v[50:65]
	v_lshl_add_u64 v[184:185], v[150:151], 0, s[14:15]
	v_add_co_u32_e32 v184, vcc, s45, v184
	s_nop 1
	v_addc_co_u32_e32 v185, vcc, 0, v185, vcc
	global_load_dwordx4 v[184:187], v[184:185], off offset:128
	v_mfma_f32_32x32x16_bf16 v[34:49], v[208:211], v[216:219], v[34:49]
	v_lshl_add_u64 v[188:189], v[150:151], 0, s[14:15]
	v_add_co_u32_e32 v188, vcc, s46, v188
	s_nop 1
	v_addc_co_u32_e32 v189, vcc, 0, v189, vcc
	global_load_dwordx4 v[188:191], v[188:189], off offset:128
	v_mfma_f32_32x32x16_bf16 v[18:33], v[208:211], v[224:227], v[18:33]
	v_lshl_add_u64 v[192:193], v[150:151], 0, s[14:15]
	v_add_co_u32_e32 v192, vcc, s47, v192
	s_nop 1
	v_addc_co_u32_e32 v193, vcc, 0, v193, vcc
	global_load_dwordx4 v[192:195], v[192:193], off offset:128
	v_mfma_f32_32x32x16_bf16 v[2:17], v[208:211], v[228:231], v[2:17]
	v_lshl_add_u64 v[196:197], v[150:151], 0, s[14:15]
	v_add_co_u32_e32 v196, vcc, s48, v196
	s_nop 1
	v_addc_co_u32_e32 v197, vcc, 0, v197, vcc
	global_load_dwordx4 v[196:199], v[196:197], off offset:128
	ds_read_b128 v[208:211], v130 offset:4704
	s_waitcnt lgkmcnt(4)
	v_mfma_f32_32x32x16_bf16 v[114:129], v[204:207], v[232:235], v[114:129]
	s_waitcnt lgkmcnt(3)
	v_mfma_f32_32x32x16_bf16 v[98:113], v[204:207], v[236:239], v[98:113]
	s_waitcnt lgkmcnt(2)
	v_mfma_f32_32x32x16_bf16 v[82:97], v[204:207], v[240:243], v[82:97]
	s_waitcnt lgkmcnt(1)
	v_mfma_f32_32x32x16_bf16 v[66:81], v[204:207], v[244:247], v[66:81]
	s_waitcnt lgkmcnt(0)
	v_mfma_f32_32x32x16_bf16 v[50:65], v[208:211], v[232:235], v[50:65]
	v_mfma_f32_32x32x16_bf16 v[34:49], v[208:211], v[236:239], v[34:49]
	v_mfma_f32_32x32x16_bf16 v[18:33], v[208:211], v[240:243], v[18:33]
	v_mfma_f32_32x32x16_bf16 v[2:17], v[208:211], v[244:247], v[2:17]
	s_setprio 0
	s_add_u32 s14, s14, 0x80
	s_addc_u32 s15, s15, 0
	s_cmpk_lg_i32 s14, 0x700
	s_barrier
; #define GW_LOAD(KOFF) GW_LOAD2(KOFF, 0)
;     ...
;   GW_LOAD(0)
;   GW_STORE()
;   __syncthreads();
;   const int nk = K >> 6;
;   const char* Ab = smem + (wm * 64 + (lane & 31)) * LSTR + (lane >> 5) * 16;
;   const char* Bb = smem + WTILE_A + (wn * 128 + (lane & 31)) * LSTR + (lane >> 5) * 16;
;   for (int kt = 0; kt < nk; ++kt) {
;     const int kn = (kt + 1 < nk) ? kt + 1 : kt;
;     GW_LOAD2(kn * 64, kn * bkstep)
;     __builtin_amdgcn_sched_barrier(0);
;     __builtin_amdgcn_s_setprio(1);
; #pragma unroll
;     for (int st = 0; st < 4; ++st) {
;       bf16x8 a0 = *(const bf16x8*)(Ab + st * 32);
;       bf16x8 a1 = *(const bf16x8*)(Ab + 32 * LSTR + st * 32);
;       bf16x8 b0 = *(const bf16x8*)(Bb + st * 32);
;       bf16x8 b1 = *(const bf16x8*)(Bb + 32 * LSTR + st * 32);
;       bf16x8 b2 = *(const bf16x8*)(Bb + 64 * LSTR + st * 32);
;       bf16x8 b3 = *(const bf16x8*)(Bb + 96 * LSTR + st * 32);
;       acc[0][0] = mfma32(a0, b0, acc[0][0]);
;       acc[0][1] = mfma32(a0, b1, acc[0][1]);
;       acc[0][2] = mfma32(a0, b2, acc[0][2]);
;       acc[0][3] = mfma32(a0, b3, acc[0][3]);
;       acc[1][0] = mfma32(a1, b0, acc[1][0]);
;       acc[1][1] = mfma32(a1, b1, acc[1][1]);
;       acc[1][2] = mfma32(a1, b2, acc[1][2]);
;       acc[1][3] = mfma32(a1, b3, acc[1][3]);
;     }
;     __builtin_amdgcn_s_setprio(0);
;     __builtin_amdgcn_sched_barrier(0);
;     __syncthreads();
;     GW_STORE()
;     __syncthreads();
	s_waitcnt vmcnt(11)
	ds_write_b128 v132, v[152:155]
	s_waitcnt vmcnt(10)
	ds_write_b128 v132, v[156:159] offset:4608
	s_waitcnt vmcnt(9)
	ds_write_b128 v132, v[160:163] offset:9216
	s_waitcnt vmcnt(8)
	ds_write_b128 v132, v[164:167] offset:13824
	s_waitcnt vmcnt(7)
	ds_write_b128 v132, v[168:171] offset:18432
	s_waitcnt vmcnt(6)
	ds_write_b128 v132, v[172:175] offset:23040
	s_waitcnt vmcnt(5)
	ds_write_b128 v132, v[176:179] offset:27648
	s_waitcnt vmcnt(4)
	ds_write_b128 v132, v[180:183] offset:32256
	s_waitcnt vmcnt(3)
	ds_write_b128 v132, v[184:187] offset:36864
	s_waitcnt vmcnt(2)
	ds_write_b128 v132, v[188:191] offset:41472
	s_waitcnt vmcnt(1)
	ds_write_b128 v132, v[192:195] offset:46080
	s_waitcnt vmcnt(0)
	ds_write_b128 v132, v[196:199] offset:50688
	s_waitcnt lgkmcnt(0)
	s_barrier
	s_cbranch_scc1 .LBB0_1715
	s_setprio 1
	ds_read_b128 v[200:203], v130 offset:0
	ds_read_b128 v[212:215], v133 offset:18432
	ds_read_b128 v[216:219], v133 offset:23040
	ds_read_b128 v[224:227], v133 offset:27648
	ds_read_b128 v[228:231], v133 offset:32256
	ds_read_b128 v[208:211], v130 offset:4608
	s_waitcnt lgkmcnt(4)
	v_mfma_f32_32x32x16_bf16 v[114:129], v[200:203], v[212:215], v[114:129]
	ds_read_b128 v[204:207], v130 offset:32
	ds_read_b128 v[232:235], v133 offset:18464
	s_waitcnt lgkmcnt(5)
	v_mfma_f32_32x32x16_bf16 v[98:113], v[200:203], v[216:219], v[98:113]
	ds_read_b128 v[236:239], v133 offset:23072
	s_waitcnt lgkmcnt(5)
	v_mfma_f32_32x32x16_bf16 v[82:97], v[200:203], v[224:227], v[82:97]
	ds_read_b128 v[240:243], v133 offset:27680
	s_waitcnt lgkmcnt(5)
	v_mfma_f32_32x32x16_bf16 v[66:81], v[200:203], v[228:231], v[66:81]
	ds_read_b128 v[244:247], v133 offset:32288
	s_waitcnt lgkmcnt(5)
	v_mfma_f32_32x32x16_bf16 v[50:65], v[208:211], v[212:215], v[50:65]
	v_lshl_add_u64 v[152:153], v[148:149], 0, s[14:15]
	v_add_co_u32_e32 v152, vcc, s37, v152
	s_nop 1
	v_addc_co_u32_e32 v153, vcc, 0, v153, vcc
	global_load_dwordx4 v[152:155], v[152:153], off offset:384
	v_mfma_f32_32x32x16_bf16 v[34:49], v[208:211], v[216:219], v[34:49]
	v_lshl_add_u64 v[156:157], v[148:149], 0, s[14:15]
	v_add_co_u32_e32 v156, vcc, s38, v156
	s_nop 1
	v_addc_co_u32_e32 v157, vcc, 0, v157, vcc
	global_load_dwordx4 v[156:159], v[156:157], off offset:384
	v_mfma_f32_32x32x16_bf16 v[18:33], v[208:211], v[224:227], v[18:33]
	v_lshl_add_u64 v[160:161], v[148:149], 0, s[14:15]
	v_add_co_u32_e32 v160, vcc, s39, v160
	s_nop 1
	v_addc_co_u32_e32 v161, vcc, 0, v161, vcc
	global_load_dwordx4 v[160:163], v[160:161], off offset:384
	v_mfma_f32_32x32x16_bf16 v[2:17], v[208:211], v[228:231], v[2:17]
	v_lshl_add_u64 v[164:165], v[148:149], 0, s[14:15]
	v_add_co_u32_e32 v164, vcc, s40, v164
	s_nop 1
	v_addc_co_u32_e32 v165, vcc, 0, v165, vcc
	global_load_dwordx4 v[164:167], v[164:165], off offset:384
	ds_read_b128 v[208:211], v130 offset:4640
	s_waitcnt lgkmcnt(4)
	v_mfma_f32_32x32x16_bf16 v[114:129], v[204:207], v[232:235], v[114:129]
	ds_read_b128 v[200:203], v130 offset:64
	ds_read_b128 v[212:215], v133 offset:18496
	s_waitcnt lgkmcnt(5)
	v_mfma_f32_32x32x16_bf16 v[98:113], v[204:207], v[236:239], v[98:113]
	ds_read_b128 v[216:219], v133 offset:23104
	s_waitcnt lgkmcnt(5)
	v_mfma_f32_32x32x16_bf16 v[82:97], v[204:207], v[240:243], v[82:97]
	ds_read_b128 v[224:227], v133 offset:27712
	s_waitcnt lgkmcnt(5)
	v_mfma_f32_32x32x16_bf16 v[66:81], v[204:207], v[244:247], v[66:81]
	ds_read_b128 v[228:231], v133 offset:32320
	s_waitcnt lgkmcnt(5)
	v_mfma_f32_32x32x16_bf16 v[50:65], v[208:211], v[232:235], v[50:65]
	v_lshl_add_u64 v[168:169], v[150:151], 0, s[14:15]
	v_add_co_u32_e32 v168, vcc, s41, v168
	s_nop 1
	v_addc_co_u32_e32 v169, vcc, 0, v169, vcc
	global_load_dwordx4 v[168:171], v[168:169], off offset:128
	v_mfma_f32_32x32x16_bf16 v[34:49], v[208:211], v[236:239], v[34:49]
	v_lshl_add_u64 v[172:173], v[150:151], 0, s[14:15]
	v_add_co_u32_e32 v172, vcc, s42, v172
	s_nop 1
	v_addc_co_u32_e32 v173, vcc, 0, v173, vcc
	global_load_dwordx4 v[172:175], v[172:173], off offset:128
	v_mfma_f32_32x32x16_bf16 v[18:33], v[208:211], v[240:243], v[18:33]
	v_lshl_add_u64 v[176:177], v[150:151], 0, s[14:15]
	v_add_co_u32_e32 v176, vcc, s43, v176
	s_nop 1
	v_addc_co_u32_e32 v177, vcc, 0, v177, vcc
	global_load_dwordx4 v[176:179], v[176:177], off offset:128
	v_mfma_f32_32x32x16_bf16 v[2:17], v[208:211], v[244:247], v[2:17]
	v_lshl_add_u64 v[180:181], v[150:151], 0, s[14:15]
	v_add_co_u32_e32 v180, vcc, s44, v180
	s_nop 1
	v_addc_co_u32_e32 v181, vcc, 0, v181, vcc
	global_load_dwordx4 v[180:183], v[180:181], off offset:128
	ds_read_b128 v[208:211], v130 offset:4672
	s_waitcnt lgkmcnt(4)
	v_mfma_f32_32x32x16_bf16 v[114:129], v[200:203], v[212:215], v[114:129]
	ds_read_b128 v[204:207], v130 offset:96
	ds_read_b128 v[232:235], v133 offset:18528
	s_waitcnt lgkmcnt(5)
	v_mfma_f32_32x32x16_bf16 v[98:113], v[200:203], v[216:219], v[98:113]
	ds_read_b128 v[236:239], v133 offset:23136
	s_waitcnt lgkmcnt(5)
	v_mfma_f32_32x32x16_bf16 v[82:97], v[200:203], v[224:227], v[82:97]
	ds_read_b128 v[240:243], v133 offset:27744
	s_waitcnt lgkmcnt(5)
	v_mfma_f32_32x32x16_bf16 v[66:81], v[200:203], v[228:231], v[66:81]
	ds_read_b128 v[244:247], v133 offset:32352
	s_waitcnt lgkmcnt(5)
;     ...
;   for (int kt = 0; kt < nk; ++kt) {
;     const int kn = (kt + 1 < nk) ? kt + 1 : kt;
;     GW_LOAD2(kn * 64, kn * bkstep)
;     __builtin_amdgcn_sched_barrier(0);
;     __builtin_amdgcn_s_setprio(1);
; #pragma unroll
;     for (int st = 0; st < 4; ++st) {
;       bf16x8 a0 = *(const bf16x8*)(Ab + st * 32);
;       bf16x8 a1 = *(const bf16x8*)(Ab + 32 * LSTR + st * 32);
;       bf16x8 b0 = *(const bf16x8*)(Bb + st * 32);
;       bf16x8 b1 = *(const bf16x8*)(Bb + 32 * LSTR + st * 32);
;       bf16x8 b2 = *(const bf16x8*)(Bb + 64 * LSTR + st * 32);
;       bf16x8 b3 = *(const bf16x8*)(Bb + 96 * LSTR + st * 32);
;       acc[0][0] = mfma32(a0, b0, acc[0][0]);
;       acc[0][1] = mfma32(a0, b1, acc[0][1]);
;       acc[0][2] = mfma32(a0, b2, acc[0][2]);
;       acc[0][3] = mfma32(a0, b3, acc[0][3]);
;       acc[1][0] = mfma32(a1, b0, acc[1][0]);
;       acc[1][1] = mfma32(a1, b1, acc[1][1]);
;       acc[1][2] = mfma32(a1, b2, acc[1][2]);
;       acc[1][3] = mfma32(a1, b3, acc[1][3]);
;     }
;     __builtin_amdgcn_s_setprio(0);
;     __builtin_amdgcn_sched_barrier(0);
;     __syncthreads();
;     GW_STORE()
;     __syncthreads();
	v_mfma_f32_32x32x16_bf16 v[50:65], v[208:211], v[212:215], v[50:65]
	v_lshl_add_u64 v[184:185], v[150:151], 0, s[14:15]
	v_add_co_u32_e32 v184, vcc, s45, v184
	s_nop 1
	v_addc_co_u32_e32 v185, vcc, 0, v185, vcc
	global_load_dwordx4 v[184:187], v[184:185], off offset:128
	v_mfma_f32_32x32x16_bf16 v[34:49], v[208:211], v[216:219], v[34:49]
	v_lshl_add_u64 v[188:189], v[150:151], 0, s[14:15]
	v_add_co_u32_e32 v188, vcc, s46, v188
	s_nop 1
	v_addc_co_u32_e32 v189, vcc, 0, v189, vcc
	global_load_dwordx4 v[188:191], v[188:189], off offset:128
	v_mfma_f32_32x32x16_bf16 v[18:33], v[208:211], v[224:227], v[18:33]
	v_lshl_add_u64 v[192:193], v[150:151], 0, s[14:15]
	v_add_co_u32_e32 v192, vcc, s47, v192
	s_nop 1
	v_addc_co_u32_e32 v193, vcc, 0, v193, vcc
	global_load_dwordx4 v[192:195], v[192:193], off offset:128
	v_mfma_f32_32x32x16_bf16 v[2:17], v[208:211], v[228:231], v[2:17]
	v_lshl_add_u64 v[196:197], v[150:151], 0, s[14:15]
	v_add_co_u32_e32 v196, vcc, s48, v196
	s_nop 1
	v_addc_co_u32_e32 v197, vcc, 0, v197, vcc
	global_load_dwordx4 v[196:199], v[196:197], off offset:128
	ds_read_b128 v[208:211], v130 offset:4704
	s_waitcnt lgkmcnt(4)
	v_mfma_f32_32x32x16_bf16 v[114:129], v[204:207], v[232:235], v[114:129]
	s_waitcnt lgkmcnt(3)
	v_mfma_f32_32x32x16_bf16 v[98:113], v[204:207], v[236:239], v[98:113]
	s_waitcnt lgkmcnt(2)
	v_mfma_f32_32x32x16_bf16 v[82:97], v[204:207], v[240:243], v[82:97]
	s_waitcnt lgkmcnt(1)
	v_mfma_f32_32x32x16_bf16 v[66:81], v[204:207], v[244:247], v[66:81]
	s_waitcnt lgkmcnt(0)
	v_mfma_f32_32x32x16_bf16 v[50:65], v[208:211], v[232:235], v[50:65]
	v_mfma_f32_32x32x16_bf16 v[34:49], v[208:211], v[236:239], v[34:49]
	v_mfma_f32_32x32x16_bf16 v[18:33], v[208:211], v[240:243], v[18:33]
	v_mfma_f32_32x32x16_bf16 v[2:17], v[208:211], v[244:247], v[2:17]
	s_setprio 0
	s_add_u32 s14, s14, 0x80
	s_addc_u32 s15, s15, 0
	s_barrier
	s_waitcnt vmcnt(11)
	ds_write_b128 v132, v[152:155]
	s_waitcnt vmcnt(10)
	ds_write_b128 v132, v[156:159] offset:4608
	s_waitcnt vmcnt(9)
	ds_write_b128 v132, v[160:163] offset:9216
	s_waitcnt vmcnt(8)
	ds_write_b128 v132, v[164:167] offset:13824
	s_waitcnt vmcnt(7)
	ds_write_b128 v132, v[168:171] offset:18432
	s_waitcnt vmcnt(6)
	ds_write_b128 v132, v[172:175] offset:23040
	s_waitcnt vmcnt(5)
	ds_write_b128 v132, v[176:179] offset:27648
	s_waitcnt vmcnt(4)
	ds_write_b128 v132, v[180:183] offset:32256
	s_waitcnt vmcnt(3)
	ds_write_b128 v132, v[184:187] offset:36864
	s_waitcnt vmcnt(2)
	ds_write_b128 v132, v[188:191] offset:41472
	s_waitcnt vmcnt(1)
	ds_write_b128 v132, v[192:195] offset:46080
	s_waitcnt vmcnt(0)
	ds_write_b128 v132, v[196:199] offset:50688
	s_waitcnt lgkmcnt(0)
	s_barrier
;     ...
;   for (int kt = 0; kt < nk; ++kt) {
;     const int kn = (kt + 1 < nk) ? kt + 1 : kt;
;     GW_LOAD2(kn * 64, kn * bkstep)
;     __builtin_amdgcn_sched_barrier(0);
;     __builtin_amdgcn_s_setprio(1);
; #pragma unroll
;     for (int st = 0; st < 4; ++st) {
;       bf16x8 a0 = *(const bf16x8*)(Ab + st * 32);
;       bf16x8 a1 = *(const bf16x8*)(Ab + 32 * LSTR + st * 32);
;       bf16x8 b0 = *(const bf16x8*)(Bb + st * 32);
;       bf16x8 b1 = *(const bf16x8*)(Bb + 32 * LSTR + st * 32);
;       bf16x8 b2 = *(const bf16x8*)(Bb + 64 * LSTR + st * 32);
;       bf16x8 b3 = *(const bf16x8*)(Bb + 96 * LSTR + st * 32);
;       acc[0][0] = mfma32(a0, b0, acc[0][0]);
;       acc[0][1] = mfma32(a0, b1, acc[0][1]);
;       acc[0][2] = mfma32(a0, b2, acc[0][2]);
;       acc[0][3] = mfma32(a0, b3, acc[0][3]);
;       acc[1][0] = mfma32(a1, b0, acc[1][0]);
;       acc[1][1] = mfma32(a1, b1, acc[1][1]);
;       acc[1][2] = mfma32(a1, b2, acc[1][2]);
;       acc[1][3] = mfma32(a1, b3, acc[1][3]);
;     }
;     __builtin_amdgcn_s_setprio(0);
	v_add_co_u32_e32 v160, vcc, 0x10000, v138
	s_nop 0
	s_nop 0
	s_nop 0
	v_addc_co_u32_e32 v161, vcc, 0, v139, vcc
	v_add_co_u32_e32 v164, vcc, 0x20000, v138
	s_nop 0
	v_addc_co_u32_e32 v165, vcc, 0, v139, vcc
	v_add_co_u32_e32 v168, vcc, 0x30000, v138
	s_lshl_b64 s[12:13], s[12:13], 7
	s_nop 0
	v_addc_co_u32_e32 v169, vcc, 0, v139, vcc
	v_add_co_u32_e32 v172, vcc, 0x40000, v138
	s_nop 0
	v_addc_co_u32_e32 v173, vcc, 0, v139, vcc
	v_add_co_u32_e32 v176, vcc, 0x50000, v138
	s_mov_b32 s53, 0
	s_nop 0
	v_addc_co_u32_e32 v177, vcc, 0, v139, vcc
	v_add_co_u32_e32 v180, vcc, 0x60000, v138
	s_nop 0
	v_addc_co_u32_e32 v181, vcc, 0, v139, vcc
	v_add_co_u32_e32 v138, vcc, 0x70000, v138
	s_nop 1
	v_addc_co_u32_e32 v139, vcc, 0, v139, vcc
	s_nop 0
	s_setprio 1
	ds_read_b128 v[188:191], v130 offset:0
	ds_read_b128 v[200:203], v133 offset:18432
	ds_read_b128 v[204:207], v133 offset:23040
	ds_read_b128 v[208:211], v133 offset:27648
	ds_read_b128 v[212:215], v133 offset:32256
	ds_read_b128 v[196:199], v130 offset:4608
	s_waitcnt lgkmcnt(4)
	v_mfma_f32_32x32x16_bf16 v[114:129], v[188:191], v[200:203], v[114:129]
	ds_read_b128 v[192:195], v130 offset:32
	ds_read_b128 v[216:219], v133 offset:18464
	s_waitcnt lgkmcnt(5)
	v_mfma_f32_32x32x16_bf16 v[98:113], v[188:191], v[204:207], v[98:113]
	ds_read_b128 v[224:227], v133 offset:23072
	s_waitcnt lgkmcnt(5)
	v_mfma_f32_32x32x16_bf16 v[82:97], v[188:191], v[208:211], v[82:97]
	ds_read_b128 v[228:231], v133 offset:27680
	s_waitcnt lgkmcnt(5)
	v_mfma_f32_32x32x16_bf16 v[66:81], v[188:191], v[212:215], v[66:81]
	ds_read_b128 v[232:235], v133 offset:32288
	s_waitcnt lgkmcnt(5)
	v_mfma_f32_32x32x16_bf16 v[50:65], v[196:199], v[200:203], v[50:65]
	v_mfma_f32_32x32x16_bf16 v[34:49], v[196:199], v[204:207], v[34:49]
	v_mfma_f32_32x32x16_bf16 v[18:33], v[196:199], v[208:211], v[18:33]
	v_mfma_f32_32x32x16_bf16 v[2:17], v[196:199], v[212:215], v[2:17]
	ds_read_b128 v[196:199], v130 offset:4640
	s_waitcnt lgkmcnt(4)
	v_mfma_f32_32x32x16_bf16 v[114:129], v[192:195], v[216:219], v[114:129]
	ds_read_b128 v[188:191], v130 offset:64
	ds_read_b128 v[200:203], v133 offset:18496
	s_waitcnt lgkmcnt(5)
	v_mfma_f32_32x32x16_bf16 v[98:113], v[192:195], v[224:227], v[98:113]
	ds_read_b128 v[204:207], v133 offset:23104
	s_waitcnt lgkmcnt(5)
	v_mfma_f32_32x32x16_bf16 v[82:97], v[192:195], v[228:231], v[82:97]
	ds_read_b128 v[208:211], v133 offset:27712
	s_waitcnt lgkmcnt(5)
	v_mfma_f32_32x32x16_bf16 v[66:81], v[192:195], v[232:235], v[66:81]
	ds_read_b128 v[212:215], v133 offset:32320
	s_waitcnt lgkmcnt(5)
	v_mfma_f32_32x32x16_bf16 v[50:65], v[196:199], v[216:219], v[50:65]
	v_mfma_f32_32x32x16_bf16 v[34:49], v[196:199], v[224:227], v[34:49]
	v_mfma_f32_32x32x16_bf16 v[18:33], v[196:199], v[228:231], v[18:33]
	v_mfma_f32_32x32x16_bf16 v[2:17], v[196:199], v[232:235], v[2:17]
	ds_read_b128 v[196:199], v130 offset:4672
	s_waitcnt lgkmcnt(4)
	v_mfma_f32_32x32x16_bf16 v[114:129], v[188:191], v[200:203], v[114:129]
	ds_read_b128 v[192:195], v130 offset:96
	ds_read_b128 v[216:219], v133 offset:18528
	s_waitcnt lgkmcnt(5)
	v_mfma_f32_32x32x16_bf16 v[98:113], v[188:191], v[204:207], v[98:113]
	ds_read_b128 v[224:227], v133 offset:23136
	s_waitcnt lgkmcnt(5)
	v_mfma_f32_32x32x16_bf16 v[82:97], v[188:191], v[208:211], v[82:97]
	ds_read_b128 v[228:231], v133 offset:27744
	s_waitcnt lgkmcnt(5)
	v_mfma_f32_32x32x16_bf16 v[66:81], v[188:191], v[212:215], v[66:81]
	ds_read_b128 v[232:235], v133 offset:32352
	s_waitcnt lgkmcnt(5)
	v_mfma_f32_32x32x16_bf16 v[50:65], v[196:199], v[200:203], v[50:65]
	v_mfma_f32_32x32x16_bf16 v[34:49], v[196:199], v[204:207], v[34:49]
	v_mfma_f32_32x32x16_bf16 v[18:33], v[196:199], v[208:211], v[18:33]
	v_mfma_f32_32x32x16_bf16 v[2:17], v[196:199], v[212:215], v[2:17]
	ds_read_b128 v[196:199], v130 offset:4704
	s_waitcnt lgkmcnt(4)
	v_mfma_f32_32x32x16_bf16 v[114:129], v[192:195], v[216:219], v[114:129]
	s_waitcnt lgkmcnt(3)
	v_mfma_f32_32x32x16_bf16 v[98:113], v[192:195], v[224:227], v[98:113]
	s_waitcnt lgkmcnt(2)
	v_mfma_f32_32x32x16_bf16 v[82:97], v[192:195], v[228:231], v[82:97]
	s_waitcnt lgkmcnt(1)
	v_mfma_f32_32x32x16_bf16 v[66:81], v[192:195], v[232:235], v[66:81]
	s_waitcnt lgkmcnt(0)
	v_mfma_f32_32x32x16_bf16 v[50:65], v[196:199], v[216:219], v[50:65]
	v_mfma_f32_32x32x16_bf16 v[34:49], v[196:199], v[224:227], v[34:49]
	v_mfma_f32_32x32x16_bf16 v[18:33], v[196:199], v[228:231], v[18:33]
	v_mfma_f32_32x32x16_bf16 v[2:17], v[196:199], v[232:235], v[2:17]
	s_setprio 0
	s_mov_b64 s[16:17], -1
	s_barrier
	s_waitcnt lgkmcnt(0)

;     ...
;   for (int kt = 0; kt < nk; ++kt) {
;     const int kn = (kt + 1 < nk) ? kt + 1 : kt;
;     GW_LOAD2(kn * 64, kn * bkstep)
;     __builtin_amdgcn_sched_barrier(0);
;     __builtin_amdgcn_s_setprio(1);
; #pragma unroll
;     for (int st = 0; st < 4; ++st) {
;       bf16x8 a0 = *(const bf16x8*)(Ab + st * 32);
;       bf16x8 a1 = *(const bf16x8*)(Ab + 32 * LSTR + st * 32);
;       bf16x8 b0 = *(const bf16x8*)(Bb + st * 32);
;       bf16x8 b1 = *(const bf16x8*)(Bb + 32 * LSTR + st * 32);
;       bf16x8 b2 = *(const bf16x8*)(Bb + 64 * LSTR + st * 32);
;       bf16x8 b3 = *(const bf16x8*)(Bb + 96 * LSTR + st * 32);
;       acc[0][0] = mfma32(a0, b0, acc[0][0]);
;       acc[0][1] = mfma32(a0, b1, acc[0][1]);
;       acc[0][2] = mfma32(a0, b2, acc[0][2]);
;       acc[0][3] = mfma32(a0, b3, acc[0][3]);
;       acc[1][0] = mfma32(a1, b0, acc[1][0]);
;       acc[1][1] = mfma32(a1, b1, acc[1][1]);
;       acc[1][2] = mfma32(a1, b2, acc[1][2]);
;       acc[1][3] = mfma32(a1, b3, acc[1][3]);
;     }
;     __builtin_amdgcn_s_setprio(0);
;     __builtin_amdgcn_sched_barrier(0);
;     __syncthreads();
;     GW_STORE()
;     __syncthreads();
;   }
.LBB0_2065:
	s_setprio 1
	ds_read_b128 v[206:209], v133 offset:0
	ds_read_b128 v[218:221], v137 offset:18432
	ds_read_b128 v[224:227], v137 offset:23040
	ds_read_b128 v[228:231], v137 offset:27648
	ds_read_b128 v[232:235], v137 offset:32256
	ds_read_b128 v[214:217], v133 offset:4608
	s_waitcnt lgkmcnt(4)
	v_mfma_f32_32x32x16_bf16 v[114:129], v[206:209], v[218:221], v[114:129]
	ds_read_b128 v[210:213], v133 offset:32
	ds_read_b128 v[236:239], v137 offset:18464
	s_waitcnt lgkmcnt(5)
	v_mfma_f32_32x32x16_bf16 v[98:113], v[206:209], v[224:227], v[98:113]
	ds_read_b128 v[240:243], v137 offset:23072
	s_waitcnt lgkmcnt(5)
	v_mfma_f32_32x32x16_bf16 v[82:97], v[206:209], v[228:231], v[82:97]
	ds_read_b128 v[244:247], v137 offset:27680
	s_waitcnt lgkmcnt(5)
	v_mfma_f32_32x32x16_bf16 v[66:81], v[206:209], v[232:235], v[66:81]
	ds_read_b128 v[248:251], v137 offset:32288
	s_waitcnt lgkmcnt(5)
	v_mfma_f32_32x32x16_bf16 v[50:65], v[214:217], v[218:221], v[50:65]
	v_lshl_add_u64 v[158:159], v[150:151], 0, v[130:131]
	global_load_dwordx4 v[158:161], v[158:159], off
	v_mfma_f32_32x32x16_bf16 v[34:49], v[214:217], v[224:227], v[34:49]
	v_lshl_add_u64 v[162:163], v[152:153], 0, v[130:131]
	global_load_dwordx4 v[162:165], v[162:163], off
	v_mfma_f32_32x32x16_bf16 v[18:33], v[214:217], v[228:231], v[18:33]
	v_lshl_add_u64 v[166:167], v[154:155], 0, v[130:131]
	global_load_dwordx4 v[166:169], v[166:167], off
	v_mfma_f32_32x32x16_bf16 v[2:17], v[214:217], v[232:235], v[2:17]
	v_lshl_add_u64 v[170:171], v[156:157], 0, v[130:131]
	global_load_dwordx4 v[170:173], v[170:171], off
	ds_read_b128 v[214:217], v133 offset:4640
	s_waitcnt lgkmcnt(4)
	v_mfma_f32_32x32x16_bf16 v[114:129], v[210:213], v[236:239], v[114:129]
	ds_read_b128 v[206:209], v133 offset:64
	ds_read_b128 v[218:221], v137 offset:18496
	s_waitcnt lgkmcnt(5)
	v_mfma_f32_32x32x16_bf16 v[98:113], v[210:213], v[240:243], v[98:113]
	ds_read_b128 v[224:227], v137 offset:23104
	s_waitcnt lgkmcnt(5)
	v_mfma_f32_32x32x16_bf16 v[82:97], v[210:213], v[244:247], v[82:97]
	ds_read_b128 v[228:231], v137 offset:27712
	s_waitcnt lgkmcnt(5)
	v_mfma_f32_32x32x16_bf16 v[66:81], v[210:213], v[248:251], v[66:81]
	ds_read_b128 v[232:235], v137 offset:32320
	s_waitcnt lgkmcnt(5)
	v_mfma_f32_32x32x16_bf16 v[50:65], v[214:217], v[236:239], v[50:65]
	v_lshl_add_u64 v[174:175], v[148:149], 0, v[130:131]
	v_add_co_u32_e32 v174, vcc, s35, v174
	s_nop 1
	v_addc_co_u32_e32 v175, vcc, 0, v175, vcc
	global_load_dwordx4 v[174:177], v[174:175], off offset:-4096
	v_mfma_f32_32x32x16_bf16 v[34:49], v[214:217], v[240:243], v[34:49]
	v_lshl_add_u64 v[178:179], v[148:149], 0, v[130:131]
	v_add_co_u32_e32 v178, vcc, s35, v178
	s_nop 1
	v_addc_co_u32_e32 v179, vcc, 0, v179, vcc
	global_load_dwordx4 v[178:181], v[178:179], off
	v_mfma_f32_32x32x16_bf16 v[18:33], v[214:217], v[244:247], v[18:33]
	v_lshl_add_u64 v[182:183], v[148:149], 0, v[130:131]
	v_add_co_u32_e32 v182, vcc, s36, v182
	s_nop 1
	v_addc_co_u32_e32 v183, vcc, 0, v183, vcc
	global_load_dwordx4 v[182:185], v[182:183], off offset:-4096
	v_mfma_f32_32x32x16_bf16 v[2:17], v[214:217], v[248:251], v[2:17]
	v_lshl_add_u64 v[186:187], v[148:149], 0, v[130:131]
	v_add_co_u32_e32 v186, vcc, s36, v186
	s_nop 1
	v_addc_co_u32_e32 v187, vcc, 0, v187, vcc
	global_load_dwordx4 v[186:189], v[186:187], off
	ds_read_b128 v[214:217], v133 offset:4672
	s_waitcnt lgkmcnt(4)
	v_mfma_f32_32x32x16_bf16 v[114:129], v[206:209], v[218:221], v[114:129]
	ds_read_b128 v[210:213], v133 offset:96
	ds_read_b128 v[236:239], v137 offset:18528
	s_waitcnt lgkmcnt(5)
	v_mfma_f32_32x32x16_bf16 v[98:113], v[206:209], v[224:227], v[98:113]
	ds_read_b128 v[240:243], v137 offset:23136
	s_waitcnt lgkmcnt(5)
	v_mfma_f32_32x32x16_bf16 v[82:97], v[206:209], v[228:231], v[82:97]
	ds_read_b128 v[244:247], v137 offset:27744
	s_waitcnt lgkmcnt(5)
	v_mfma_f32_32x32x16_bf16 v[66:81], v[206:209], v[232:235], v[66:81]
	ds_read_b128 v[248:251], v137 offset:32352
	s_waitcnt lgkmcnt(5)
	v_mfma_f32_32x32x16_bf16 v[50:65], v[214:217], v[218:221], v[50:65]
	v_lshl_add_u64 v[190:191], v[148:149], 0, v[130:131]
	v_add_co_u32_e32 v190, vcc, s37, v190
	s_nop 1
	v_addc_co_u32_e32 v191, vcc, 0, v191, vcc
	global_load_dwordx4 v[190:193], v[190:191], off offset:-4096
	v_mfma_f32_32x32x16_bf16 v[34:49], v[214:217], v[224:227], v[34:49]
	v_lshl_add_u64 v[194:195], v[148:149], 0, v[130:131]
	v_add_co_u32_e32 v194, vcc, s37, v194
	s_nop 1
	v_addc_co_u32_e32 v195, vcc, 0, v195, vcc
	global_load_dwordx4 v[194:197], v[194:195], off
	v_mfma_f32_32x32x16_bf16 v[18:33], v[214:217], v[228:231], v[18:33]
	v_lshl_add_u64 v[198:199], v[148:149], 0, v[130:131]
	v_add_co_u32_e32 v198, vcc, s38, v198
	s_nop 1
	v_addc_co_u32_e32 v199, vcc, 0, v199, vcc
	global_load_dwordx4 v[198:201], v[198:199], off offset:-4096
	v_mfma_f32_32x32x16_bf16 v[2:17], v[214:217], v[232:235], v[2:17]
	v_lshl_add_u64 v[202:203], v[148:149], 0, v[130:131]
	v_add_co_u32_e32 v202, vcc, s38, v202
	s_nop 1
	v_addc_co_u32_e32 v203, vcc, 0, v203, vcc
	global_load_dwordx4 v[202:205], v[202:203], off
	ds_read_b128 v[214:217], v133 offset:4704
	s_waitcnt lgkmcnt(4)
	v_mfma_f32_32x32x16_bf16 v[114:129], v[210:213], v[236:239], v[114:129]
	s_waitcnt lgkmcnt(3)
	v_mfma_f32_32x32x16_bf16 v[98:113], v[210:213], v[240:243], v[98:113]
	s_waitcnt lgkmcnt(2)
	v_mfma_f32_32x32x16_bf16 v[82:97], v[210:213], v[244:247], v[82:97]
	s_waitcnt lgkmcnt(1)
	v_mfma_f32_32x32x16_bf16 v[66:81], v[210:213], v[248:251], v[66:81]
	s_waitcnt lgkmcnt(0)
	v_mfma_f32_32x32x16_bf16 v[50:65], v[214:217], v[236:239], v[50:65]
	v_mfma_f32_32x32x16_bf16 v[34:49], v[214:217], v[240:243], v[34:49]
	v_mfma_f32_32x32x16_bf16 v[18:33], v[214:217], v[244:247], v[18:33]
	v_mfma_f32_32x32x16_bf16 v[2:17], v[214:217], v[248:251], v[2:17]
	s_setprio 0
	s_add_i32 s41, s41, -1
	v_lshl_add_u64 v[148:149], v[148:149], 0, s[8:9]
	v_lshl_add_u64 v[150:151], v[150:151], 0, s[10:11]
	v_lshl_add_u64 v[152:153], v[152:153], 0, s[10:11]
	v_lshl_add_u64 v[154:155], v[154:155], 0, s[10:11]
	s_cmp_lg_u32 s41, 0
	v_lshl_add_u64 v[156:157], v[156:157], 0, s[10:11]
	s_barrier
; #define GW_LOAD(KOFF) GW_LOAD2(KOFF, 0)
;     ...
;   GW_LOAD(0)
;   GW_STORE()
;   __syncthreads();
;   const int nk = K >> 6;
;   const char* Ab = smem + (wm * 64 + (lane & 31)) * LSTR + (lane >> 5) * 16;
;   const char* Bb = smem + WTILE_A + (wn * 128 + (lane & 31)) * LSTR + (lane >> 5) * 16;
;   for (int kt = 0; kt < nk; ++kt) {
;     const int kn = (kt + 1 < nk) ? kt + 1 : kt;
;     GW_LOAD2(kn * 64, kn * bkstep)
;     __builtin_amdgcn_sched_barrier(0);
;     __builtin_amdgcn_s_setprio(1);
; #pragma unroll
;     for (int st = 0; st < 4; ++st) {
;       bf16x8 a0 = *(const bf16x8*)(Ab + st * 32);
;       bf16x8 a1 = *(const bf16x8*)(Ab + 32 * LSTR + st * 32);
;       bf16x8 b0 = *(const bf16x8*)(Bb + st * 32);
;       bf16x8 b1 = *(const bf16x8*)(Bb + 32 * LSTR + st * 32);
;       bf16x8 b2 = *(const bf16x8*)(Bb + 64 * LSTR + st * 32);
;       bf16x8 b3 = *(const bf16x8*)(Bb + 96 * LSTR + st * 32);
;       acc[0][0] = mfma32(a0, b0, acc[0][0]);
;       acc[0][1] = mfma32(a0, b1, acc[0][1]);
;       acc[0][2] = mfma32(a0, b2, acc[0][2]);
;       acc[0][3] = mfma32(a0, b3, acc[0][3]);
;       acc[1][0] = mfma32(a1, b0, acc[1][0]);
;       acc[1][1] = mfma32(a1, b1, acc[1][1]);
;       acc[1][2] = mfma32(a1, b2, acc[1][2]);
;       acc[1][3] = mfma32(a1, b3, acc[1][3]);
;     }
;     __builtin_amdgcn_s_setprio(0);
;     __builtin_amdgcn_sched_barrier(0);
;     __syncthreads();
;     GW_STORE()
;     __syncthreads();
	s_waitcnt vmcnt(11)
	ds_write_b128 v132, v[158:161]
	s_waitcnt vmcnt(10)
	ds_write_b128 v132, v[162:165] offset:4608
	s_waitcnt vmcnt(9)
	ds_write_b128 v132, v[166:169] offset:9216
	s_waitcnt vmcnt(8)
	ds_write_b128 v132, v[170:173] offset:13824
	s_waitcnt vmcnt(7)
	ds_write_b128 v132, v[174:177] offset:18432
	s_waitcnt vmcnt(6)
	ds_write_b128 v132, v[178:181] offset:23040
	s_waitcnt vmcnt(5)
	ds_write_b128 v132, v[182:185] offset:27648
	s_waitcnt vmcnt(4)
	ds_write_b128 v132, v[186:189] offset:32256
	s_waitcnt vmcnt(3)
	ds_write_b128 v132, v[190:193] offset:36864
	s_waitcnt vmcnt(2)
	ds_write_b128 v132, v[194:197] offset:41472
	s_waitcnt vmcnt(1)
	ds_write_b128 v132, v[198:201] offset:46080
	s_waitcnt vmcnt(0)
	ds_write_b128 v132, v[202:205] offset:50688
	s_waitcnt lgkmcnt(0)
	s_barrier
	s_cbranch_scc1 .LBB0_2065
	s_setprio 1
	ds_read_b128 v[206:209], v133 offset:0
	ds_read_b128 v[218:221], v137 offset:18432
	ds_read_b128 v[224:227], v137 offset:23040
	ds_read_b128 v[228:231], v137 offset:27648
	ds_read_b128 v[232:235], v137 offset:32256
	ds_read_b128 v[214:217], v133 offset:4608
	s_waitcnt lgkmcnt(4)
	v_mfma_f32_32x32x16_bf16 v[114:129], v[206:209], v[218:221], v[114:129]
	ds_read_b128 v[210:213], v133 offset:32
	ds_read_b128 v[236:239], v137 offset:18464
	s_waitcnt lgkmcnt(5)
	v_mfma_f32_32x32x16_bf16 v[98:113], v[206:209], v[224:227], v[98:113]
	ds_read_b128 v[240:243], v137 offset:23072
	s_waitcnt lgkmcnt(5)
	v_mfma_f32_32x32x16_bf16 v[82:97], v[206:209], v[228:231], v[82:97]
	ds_read_b128 v[244:247], v137 offset:27680
	s_waitcnt lgkmcnt(5)
	v_mfma_f32_32x32x16_bf16 v[66:81], v[206:209], v[232:235], v[66:81]
	ds_read_b128 v[248:251], v137 offset:32288
	s_waitcnt lgkmcnt(5)
	v_mfma_f32_32x32x16_bf16 v[50:65], v[214:217], v[218:221], v[50:65]
	v_lshl_add_u64 v[158:159], v[150:151], 0, v[130:131]
	global_load_dwordx4 v[158:161], v[158:159], off
	v_mfma_f32_32x32x16_bf16 v[34:49], v[214:217], v[224:227], v[34:49]
	v_lshl_add_u64 v[162:163], v[152:153], 0, v[130:131]
	global_load_dwordx4 v[162:165], v[162:163], off
	v_mfma_f32_32x32x16_bf16 v[18:33], v[214:217], v[228:231], v[18:33]
	v_lshl_add_u64 v[166:167], v[154:155], 0, v[130:131]
	global_load_dwordx4 v[166:169], v[166:167], off
	v_mfma_f32_32x32x16_bf16 v[2:17], v[214:217], v[232:235], v[2:17]
	v_lshl_add_u64 v[170:171], v[156:157], 0, v[130:131]
	global_load_dwordx4 v[170:173], v[170:171], off
	ds_read_b128 v[214:217], v133 offset:4640
	s_waitcnt lgkmcnt(4)
	v_mfma_f32_32x32x16_bf16 v[114:129], v[210:213], v[236:239], v[114:129]
	ds_read_b128 v[206:209], v133 offset:64
	ds_read_b128 v[218:221], v137 offset:18496
	s_waitcnt lgkmcnt(5)
	v_mfma_f32_32x32x16_bf16 v[98:113], v[210:213], v[240:243], v[98:113]
	ds_read_b128 v[224:227], v137 offset:23104
	s_waitcnt lgkmcnt(5)
	v_mfma_f32_32x32x16_bf16 v[82:97], v[210:213], v[244:247], v[82:97]
	ds_read_b128 v[228:231], v137 offset:27712
	s_waitcnt lgkmcnt(5)
	v_mfma_f32_32x32x16_bf16 v[66:81], v[210:213], v[248:251], v[66:81]
	ds_read_b128 v[232:235], v137 offset:32320
	s_waitcnt lgkmcnt(5)
	v_mfma_f32_32x32x16_bf16 v[50:65], v[214:217], v[236:239], v[50:65]
	v_lshl_add_u64 v[174:175], v[148:149], 0, v[130:131]
	v_add_co_u32_e32 v174, vcc, s35, v174
	s_nop 1
	v_addc_co_u32_e32 v175, vcc, 0, v175, vcc
	global_load_dwordx4 v[174:177], v[174:175], off offset:-4096
	v_mfma_f32_32x32x16_bf16 v[34:49], v[214:217], v[240:243], v[34:49]
	v_lshl_add_u64 v[178:179], v[148:149], 0, v[130:131]
	v_add_co_u32_e32 v178, vcc, s35, v178
	s_nop 1
	v_addc_co_u32_e32 v179, vcc, 0, v179, vcc
	global_load_dwordx4 v[178:181], v[178:179], off
	v_mfma_f32_32x32x16_bf16 v[18:33], v[214:217], v[244:247], v[18:33]
	v_lshl_add_u64 v[182:183], v[148:149], 0, v[130:131]
	v_add_co_u32_e32 v182, vcc, s36, v182
	s_nop 1
	v_addc_co_u32_e32 v183, vcc, 0, v183, vcc
	global_load_dwordx4 v[182:185], v[182:183], off offset:-4096
	v_mfma_f32_32x32x16_bf16 v[2:17], v[214:217], v[248:251], v[2:17]
	v_lshl_add_u64 v[186:187], v[148:149], 0, v[130:131]
	v_add_co_u32_e32 v186, vcc, s36, v186
	s_nop 1
	v_addc_co_u32_e32 v187, vcc, 0, v187, vcc
	global_load_dwordx4 v[186:189], v[186:187], off
	ds_read_b128 v[214:217], v133 offset:4672
	s_waitcnt lgkmcnt(4)
	v_mfma_f32_32x32x16_bf16 v[114:129], v[206:209], v[218:221], v[114:129]
	ds_read_b128 v[210:213], v133 offset:96
	ds_read_b128 v[236:239], v137 offset:18528
	s_waitcnt lgkmcnt(5)
	v_mfma_f32_32x32x16_bf16 v[98:113], v[206:209], v[224:227], v[98:113]
	ds_read_b128 v[240:243], v137 offset:23136
	s_waitcnt lgkmcnt(5)
	v_mfma_f32_32x32x16_bf16 v[82:97], v[206:209], v[228:231], v[82:97]
	ds_read_b128 v[244:247], v137 offset:27744
	s_waitcnt lgkmcnt(5)
	v_mfma_f32_32x32x16_bf16 v[66:81], v[206:209], v[232:235], v[66:81]
	ds_read_b128 v[248:251], v137 offset:32352
	s_waitcnt lgkmcnt(5)
	v_mfma_f32_32x32x16_bf16 v[50:65], v[214:217], v[218:221], v[50:65]
	v_lshl_add_u64 v[190:191], v[148:149], 0, v[130:131]
	v_add_co_u32_e32 v190, vcc, s37, v190
	s_nop 1
	v_addc_co_u32_e32 v191, vcc, 0, v191, vcc
	global_load_dwordx4 v[190:193], v[190:191], off offset:-4096
	v_mfma_f32_32x32x16_bf16 v[34:49], v[214:217], v[224:227], v[34:49]
	v_lshl_add_u64 v[194:195], v[148:149], 0, v[130:131]
	v_add_co_u32_e32 v194, vcc, s37, v194
	s_nop 1
	v_addc_co_u32_e32 v195, vcc, 0, v195, vcc
	global_load_dwordx4 v[194:197], v[194:195], off
	v_mfma_f32_32x32x16_bf16 v[18:33], v[214:217], v[228:231], v[18:33]
	v_lshl_add_u64 v[198:199], v[148:149], 0, v[130:131]
	v_add_co_u32_e32 v198, vcc, s38, v198
	s_nop 1
	v_addc_co_u32_e32 v199, vcc, 0, v199, vcc
	global_load_dwordx4 v[198:201], v[198:199], off offset:-4096
	v_mfma_f32_32x32x16_bf16 v[2:17], v[214:217], v[232:235], v[2:17]
	v_lshl_add_u64 v[202:203], v[148:149], 0, v[130:131]
	v_add_co_u32_e32 v202, vcc, s38, v202
	s_nop 1
	v_addc_co_u32_e32 v203, vcc, 0, v203, vcc
	global_load_dwordx4 v[202:205], v[202:203], off
	ds_read_b128 v[214:217], v133 offset:4704
	s_waitcnt lgkmcnt(4)
	v_mfma_f32_32x32x16_bf16 v[114:129], v[210:213], v[236:239], v[114:129]
	s_waitcnt lgkmcnt(3)
	v_mfma_f32_32x32x16_bf16 v[98:113], v[210:213], v[240:243], v[98:113]
	s_waitcnt lgkmcnt(2)
	v_mfma_f32_32x32x16_bf16 v[82:97], v[210:213], v[244:247], v[82:97]
	s_waitcnt lgkmcnt(1)
	v_mfma_f32_32x32x16_bf16 v[66:81], v[210:213], v[248:251], v[66:81]
	s_waitcnt lgkmcnt(0)
	v_mfma_f32_32x32x16_bf16 v[50:65], v[214:217], v[236:239], v[50:65]
	v_mfma_f32_32x32x16_bf16 v[34:49], v[214:217], v[240:243], v[34:49]
	v_mfma_f32_32x32x16_bf16 v[18:33], v[214:217], v[244:247], v[18:33]
	v_mfma_f32_32x32x16_bf16 v[2:17], v[214:217], v[248:251], v[2:17]
	s_setprio 0
	v_lshl_add_u64 v[148:149], v[148:149], 0, s[8:9]
	v_lshl_add_u64 v[150:151], v[150:151], 0, s[10:11]
	v_lshl_add_u64 v[152:153], v[152:153], 0, s[10:11]
	v_lshl_add_u64 v[154:155], v[154:155], 0, s[10:11]
	v_lshl_add_u64 v[156:157], v[156:157], 0, s[10:11]
	s_barrier
; #define GW_LOAD(KOFF) GW_LOAD2(KOFF, 0)
;     ...
;   GW_LOAD(0)
;   GW_STORE()
;   __syncthreads();
;   const int nk = K >> 6;
;   const char* Ab = smem + (wm * 64 + (lane & 31)) * LSTR + (lane >> 5) * 16;
;   const char* Bb = smem + WTILE_A + (wn * 128 + (lane & 31)) * LSTR + (lane >> 5) * 16;
;   for (int kt = 0; kt < nk; ++kt) {
;     const int kn = (kt + 1 < nk) ? kt + 1 : kt;
;     GW_LOAD2(kn * 64, kn * bkstep)
;     __builtin_amdgcn_sched_barrier(0);
;     __builtin_amdgcn_s_setprio(1);
; #pragma unroll
;     for (int st = 0; st < 4; ++st) {
;       bf16x8 a0 = *(const bf16x8*)(Ab + st * 32);
;       bf16x8 a1 = *(const bf16x8*)(Ab + 32 * LSTR + st * 32);
;       bf16x8 b0 = *(const bf16x8*)(Bb + st * 32);
;       bf16x8 b1 = *(const bf16x8*)(Bb + 32 * LSTR + st * 32);
;       bf16x8 b2 = *(const bf16x8*)(Bb + 64 * LSTR + st * 32);
;       bf16x8 b3 = *(const bf16x8*)(Bb + 96 * LSTR + st * 32);
;       acc[0][0] = mfma32(a0, b0, acc[0][0]);
;       acc[0][1] = mfma32(a0, b1, acc[0][1]);
;       acc[0][2] = mfma32(a0, b2, acc[0][2]);
;       acc[0][3] = mfma32(a0, b3, acc[0][3]);
;       acc[1][0] = mfma32(a1, b0, acc[1][0]);
;       acc[1][1] = mfma32(a1, b1, acc[1][1]);
;       acc[1][2] = mfma32(a1, b2, acc[1][2]);
;       acc[1][3] = mfma32(a1, b3, acc[1][3]);
;     }
;     __builtin_amdgcn_s_setprio(0);
;     __builtin_amdgcn_sched_barrier(0);
;     __syncthreads();
;     GW_STORE()
;     __syncthreads();
; __device__ __forceinline__ void expert1_tile(const Params& P, int e, int mt, int ntw, char* smem) {
;     ...
;   float* cs = (float*)smem;
;   int tid_ = threadIdx.x;
;   asm volatile("" : "+v"(tid_));
;   const int lane = tid_ & 63, wave = tid_ >> 6;
;   const int r = 32 * wave + (lane & 31), part = lane >> 5;
; #pragma unroll 1
;   for (int h = 0; h < 2; ++h) {
;     wide_acc_to_lds(acc, cs, h);
;     u16* dst = WSP(u16, OFF_HID) + ((size_t)e * EROWS + mt * 128 + r) * 2048 + (ntw * 2 + h) * 64 + part * 32;
	s_waitcnt vmcnt(11)
	ds_write_b128 v132, v[158:161]
	s_waitcnt vmcnt(10)
	ds_write_b128 v132, v[162:165] offset:4608
	s_waitcnt vmcnt(9)
	ds_write_b128 v132, v[166:169] offset:9216
	s_waitcnt vmcnt(8)
	ds_write_b128 v132, v[170:173] offset:13824
	s_waitcnt vmcnt(7)
	ds_write_b128 v132, v[174:177] offset:18432
	s_waitcnt vmcnt(6)
	ds_write_b128 v132, v[178:181] offset:23040
	s_waitcnt vmcnt(5)
	ds_write_b128 v132, v[182:185] offset:27648
	s_waitcnt vmcnt(4)
	ds_write_b128 v132, v[186:189] offset:32256
	s_waitcnt vmcnt(3)
	ds_write_b128 v132, v[190:193] offset:36864
	s_waitcnt vmcnt(2)
	ds_write_b128 v132, v[194:197] offset:41472
	s_waitcnt vmcnt(1)
	ds_write_b128 v132, v[198:201] offset:46080
	s_waitcnt vmcnt(0)
	ds_write_b128 v132, v[202:205] offset:50688
	s_waitcnt lgkmcnt(0)
	s_barrier
	v_add_co_u32_e32 v156, vcc, 0x780000, v138
	s_nop 0
	s_nop 0
	s_nop 0
	v_addc_co_u32_e32 v157, vcc, 0, v139, vcc
	v_add_co_u32_e32 v160, vcc, 0x781000, v138
	s_mov_b32 s18, 0
	s_nop 0
	v_addc_co_u32_e32 v161, vcc, 0, v139, vcc
	v_add_co_u32_e32 v164, vcc, 0x782000, v138
	s_nop 0
	v_addc_co_u32_e32 v165, vcc, 0, v139, vcc
	v_add_co_u32_e32 v168, vcc, 0x783000, v138
	s_nop 1
	v_addc_co_u32_e32 v169, vcc, 0, v139, vcc
	v_add_co_u32_e32 v172, vcc, 0x784000, v138
	s_nop 0
	v_addc_co_u32_e32 v173, vcc, 0, v139, vcc
	v_add_co_u32_e32 v176, vcc, 0x785000, v138
	s_nop 1
	v_addc_co_u32_e32 v177, vcc, 0, v139, vcc
	v_add_co_u32_e32 v180, vcc, 0x786000, v138
	s_nop 0
	v_addc_co_u32_e32 v181, vcc, 0, v139, vcc
	v_add_co_u32_e32 v138, vcc, 0x787000, v138
	s_nop 1
	v_addc_co_u32_e32 v139, vcc, 0, v139, vcc
	s_nop 0
	s_setprio 1
	ds_read_b128 v[188:191], v133 offset:0
	ds_read_b128 v[200:203], v137 offset:18432
	ds_read_b128 v[204:207], v137 offset:23040
	ds_read_b128 v[208:211], v137 offset:27648
	ds_read_b128 v[212:215], v137 offset:32256
	ds_read_b128 v[196:199], v133 offset:4608
	s_waitcnt lgkmcnt(4)
	v_mfma_f32_32x32x16_bf16 v[114:129], v[188:191], v[200:203], v[114:129]
	ds_read_b128 v[192:195], v133 offset:32
	ds_read_b128 v[216:219], v137 offset:18464
	s_waitcnt lgkmcnt(5)
	v_mfma_f32_32x32x16_bf16 v[98:113], v[188:191], v[204:207], v[98:113]
	ds_read_b128 v[224:227], v137 offset:23072
	s_waitcnt lgkmcnt(5)
	v_mfma_f32_32x32x16_bf16 v[82:97], v[188:191], v[208:211], v[82:97]
	ds_read_b128 v[228:231], v137 offset:27680
	s_waitcnt lgkmcnt(5)
	v_mfma_f32_32x32x16_bf16 v[66:81], v[188:191], v[212:215], v[66:81]
	ds_read_b128 v[232:235], v137 offset:32288
	s_waitcnt lgkmcnt(5)
	v_mfma_f32_32x32x16_bf16 v[50:65], v[196:199], v[200:203], v[50:65]
	v_mfma_f32_32x32x16_bf16 v[34:49], v[196:199], v[204:207], v[34:49]
	v_mfma_f32_32x32x16_bf16 v[18:33], v[196:199], v[208:211], v[18:33]
	v_mfma_f32_32x32x16_bf16 v[2:17], v[196:199], v[212:215], v[2:17]
	ds_read_b128 v[196:199], v133 offset:4640
	s_waitcnt lgkmcnt(4)
	v_mfma_f32_32x32x16_bf16 v[114:129], v[192:195], v[216:219], v[114:129]
	ds_read_b128 v[188:191], v133 offset:64
	ds_read_b128 v[200:203], v137 offset:18496
	s_waitcnt lgkmcnt(5)
	v_mfma_f32_32x32x16_bf16 v[98:113], v[192:195], v[224:227], v[98:113]
	ds_read_b128 v[204:207], v137 offset:23104
	s_waitcnt lgkmcnt(5)
	v_mfma_f32_32x32x16_bf16 v[82:97], v[192:195], v[228:231], v[82:97]
	ds_read_b128 v[208:211], v137 offset:27712
	s_waitcnt lgkmcnt(5)
	v_mfma_f32_32x32x16_bf16 v[66:81], v[192:195], v[232:235], v[66:81]
	ds_read_b128 v[212:215], v137 offset:32320
	s_waitcnt lgkmcnt(5)
	v_mfma_f32_32x32x16_bf16 v[50:65], v[196:199], v[216:219], v[50:65]
	v_mfma_f32_32x32x16_bf16 v[34:49], v[196:199], v[224:227], v[34:49]
	v_mfma_f32_32x32x16_bf16 v[18:33], v[196:199], v[228:231], v[18:33]
	v_mfma_f32_32x32x16_bf16 v[2:17], v[196:199], v[232:235], v[2:17]
	ds_read_b128 v[196:199], v133 offset:4672
	s_waitcnt lgkmcnt(4)
	v_mfma_f32_32x32x16_bf16 v[114:129], v[188:191], v[200:203], v[114:129]
	ds_read_b128 v[192:195], v133 offset:96
	ds_read_b128 v[216:219], v137 offset:18528
	s_waitcnt lgkmcnt(5)
	v_mfma_f32_32x32x16_bf16 v[98:113], v[188:191], v[204:207], v[98:113]
	ds_read_b128 v[224:227], v137 offset:23136
	s_waitcnt lgkmcnt(5)
	v_mfma_f32_32x32x16_bf16 v[82:97], v[188:191], v[208:211], v[82:97]
	ds_read_b128 v[228:231], v137 offset:27744
	s_waitcnt lgkmcnt(5)
	v_mfma_f32_32x32x16_bf16 v[66:81], v[188:191], v[212:215], v[66:81]
	ds_read_b128 v[232:235], v137 offset:32352
	s_waitcnt lgkmcnt(5)
	v_mfma_f32_32x32x16_bf16 v[50:65], v[196:199], v[200:203], v[50:65]
	v_mfma_f32_32x32x16_bf16 v[34:49], v[196:199], v[204:207], v[34:49]
	v_mfma_f32_32x32x16_bf16 v[18:33], v[196:199], v[208:211], v[18:33]
	v_mfma_f32_32x32x16_bf16 v[2:17], v[196:199], v[212:215], v[2:17]
	ds_read_b128 v[196:199], v133 offset:4704
	s_waitcnt lgkmcnt(4)
	v_mfma_f32_32x32x16_bf16 v[114:129], v[192:195], v[216:219], v[114:129]
	s_waitcnt lgkmcnt(3)
	v_mfma_f32_32x32x16_bf16 v[98:113], v[192:195], v[224:227], v[98:113]
	s_waitcnt lgkmcnt(2)
	v_mfma_f32_32x32x16_bf16 v[82:97], v[192:195], v[228:231], v[82:97]
	s_waitcnt lgkmcnt(1)
	v_mfma_f32_32x32x16_bf16 v[66:81], v[192:195], v[232:235], v[66:81]
	s_waitcnt lgkmcnt(0)
	v_mfma_f32_32x32x16_bf16 v[50:65], v[196:199], v[216:219], v[50:65]
	v_mfma_f32_32x32x16_bf16 v[34:49], v[196:199], v[224:227], v[34:49]
	v_mfma_f32_32x32x16_bf16 v[18:33], v[196:199], v[228:231], v[18:33]
	v_mfma_f32_32x32x16_bf16 v[2:17], v[196:199], v[232:235], v[2:17]
	s_setprio 0
	v_mov_b32_e32 v130, v134
	s_barrier
	s_waitcnt lgkmcnt(0)
	s_mul_hi_i32 s13, s14, 0x1100
	v_ashrrev_i32_e32 v132, 1, v130
	s_mulk_i32 s14, 0x1100
	v_bfi_b32 v132, s39, v132, v130
	s_add_u32 s14, s14, s16
	s_addc_u32 s15, s13, s17
	v_ashrrev_i32_e32 v133, 31, v132
	v_lshl_add_u64 v[138:139], s[14:15], 0, v[132:133]
	v_and_b32_e32 v130, 32, v130
	v_lshlrev_b64 v[138:139], 12, v[138:139]
	v_mul_lo_u32 v132, v132, s22
	v_lshl_add_u32 v137, v130, 2, v132
	v_lshl_add_u64 v[132:133], s[4:5], 0, v[138:139]
	v_lshlrev_b32_e32 v130, 1, v130
	s_lshl_b32 s16, s12, 7
	v_lshl_add_u64 v[132:133], v[132:133], 0, v[130:131]
	s_mov_b64 s[12:13], -1
	s_branch .LBB0_2068

;     ...
;   for (int kt = 0; kt < nk; ++kt) {
;     const int kn = (kt + 1 < nk) ? kt + 1 : kt;
;     GW_LOAD2(kn * 64, kn * bkstep)
;     __builtin_amdgcn_sched_barrier(0);
;     __builtin_amdgcn_s_setprio(1);
; #pragma unroll
;     for (int st = 0; st < 4; ++st) {
;       bf16x8 a0 = *(const bf16x8*)(Ab + st * 32);
;       bf16x8 a1 = *(const bf16x8*)(Ab + 32 * LSTR + st * 32);
;       bf16x8 b0 = *(const bf16x8*)(Bb + st * 32);
;       bf16x8 b1 = *(const bf16x8*)(Bb + 32 * LSTR + st * 32);
;       bf16x8 b2 = *(const bf16x8*)(Bb + 64 * LSTR + st * 32);
;       bf16x8 b3 = *(const bf16x8*)(Bb + 96 * LSTR + st * 32);
;       acc[0][0] = mfma32(a0, b0, acc[0][0]);
;       acc[0][1] = mfma32(a0, b1, acc[0][1]);
;       acc[0][2] = mfma32(a0, b2, acc[0][2]);
;       acc[0][3] = mfma32(a0, b3, acc[0][3]);
;       acc[1][0] = mfma32(a1, b0, acc[1][0]);
;       acc[1][1] = mfma32(a1, b1, acc[1][1]);
;       acc[1][2] = mfma32(a1, b2, acc[1][2]);
;       acc[1][3] = mfma32(a1, b3, acc[1][3]);
;     }
;     __builtin_amdgcn_s_setprio(0);
;     __builtin_amdgcn_sched_barrier(0);
;     __syncthreads();
;     GW_STORE()
;     __syncthreads();
;   }
.LBB0_2143:
	s_setprio 1
	ds_read_b128 v[200:203], v133 offset:0
	ds_read_b128 v[212:215], v137 offset:18432
	ds_read_b128 v[216:219], v137 offset:23040
	ds_read_b128 v[224:227], v137 offset:27648
	ds_read_b128 v[228:231], v137 offset:32256
	ds_read_b128 v[208:211], v133 offset:4608
	s_waitcnt lgkmcnt(4)
	v_mfma_f32_32x32x16_bf16 v[114:129], v[200:203], v[212:215], v[114:129]
	ds_read_b128 v[204:207], v133 offset:32
	ds_read_b128 v[232:235], v137 offset:18464
	s_waitcnt lgkmcnt(5)
	v_mfma_f32_32x32x16_bf16 v[98:113], v[200:203], v[216:219], v[98:113]
	ds_read_b128 v[236:239], v137 offset:23072
	s_waitcnt lgkmcnt(5)
	v_mfma_f32_32x32x16_bf16 v[82:97], v[200:203], v[224:227], v[82:97]
	ds_read_b128 v[240:243], v137 offset:27680
	s_waitcnt lgkmcnt(5)
	v_mfma_f32_32x32x16_bf16 v[66:81], v[200:203], v[228:231], v[66:81]
	ds_read_b128 v[244:247], v137 offset:32288
	s_waitcnt lgkmcnt(5)
	v_mfma_f32_32x32x16_bf16 v[50:65], v[208:211], v[212:215], v[50:65]
	v_lshl_add_u64 v[152:153], v[150:151], 0, v[130:131]
	v_add_co_u32_e32 v152, vcc, s37, v152
	s_nop 1
	v_addc_co_u32_e32 v153, vcc, 0, v153, vcc
	global_load_dwordx4 v[152:155], v[152:153], off offset:384
	v_mfma_f32_32x32x16_bf16 v[34:49], v[208:211], v[216:219], v[34:49]
	v_lshl_add_u64 v[156:157], v[150:151], 0, v[130:131]
	v_add_co_u32_e32 v156, vcc, s38, v156
	s_nop 1
	v_addc_co_u32_e32 v157, vcc, 0, v157, vcc
	global_load_dwordx4 v[156:159], v[156:157], off offset:384
	v_mfma_f32_32x32x16_bf16 v[18:33], v[208:211], v[224:227], v[18:33]
	v_lshl_add_u64 v[160:161], v[150:151], 0, v[130:131]
	v_add_co_u32_e32 v160, vcc, s39, v160
	s_nop 1
	v_addc_co_u32_e32 v161, vcc, 0, v161, vcc
	global_load_dwordx4 v[160:163], v[160:161], off offset:384
	v_mfma_f32_32x32x16_bf16 v[2:17], v[208:211], v[228:231], v[2:17]
	v_lshl_add_u64 v[164:165], v[150:151], 0, v[130:131]
	v_add_co_u32_e32 v164, vcc, s40, v164
	s_nop 1
	v_addc_co_u32_e32 v165, vcc, 0, v165, vcc
	global_load_dwordx4 v[164:167], v[164:165], off offset:384
	ds_read_b128 v[208:211], v133 offset:4640
	s_waitcnt lgkmcnt(4)
	v_mfma_f32_32x32x16_bf16 v[114:129], v[204:207], v[232:235], v[114:129]
	ds_read_b128 v[200:203], v133 offset:64
	ds_read_b128 v[212:215], v137 offset:18496
	s_waitcnt lgkmcnt(5)
	v_mfma_f32_32x32x16_bf16 v[98:113], v[204:207], v[236:239], v[98:113]
	ds_read_b128 v[216:219], v137 offset:23104
	s_waitcnt lgkmcnt(5)
	v_mfma_f32_32x32x16_bf16 v[82:97], v[204:207], v[240:243], v[82:97]
	ds_read_b128 v[224:227], v137 offset:27712
	s_waitcnt lgkmcnt(5)
	v_mfma_f32_32x32x16_bf16 v[66:81], v[204:207], v[244:247], v[66:81]
	ds_read_b128 v[228:231], v137 offset:32320
	s_waitcnt lgkmcnt(5)
	v_mfma_f32_32x32x16_bf16 v[50:65], v[208:211], v[232:235], v[50:65]
	v_lshl_add_u64 v[168:169], v[148:149], 0, v[130:131]
	v_add_co_u32_e32 v168, vcc, s41, v168
	s_nop 1
	v_addc_co_u32_e32 v169, vcc, 0, v169, vcc
	global_load_dwordx4 v[168:171], v[168:169], off offset:-4096
	v_mfma_f32_32x32x16_bf16 v[34:49], v[208:211], v[236:239], v[34:49]
	v_lshl_add_u64 v[172:173], v[148:149], 0, v[130:131]
	v_add_co_u32_e32 v172, vcc, s41, v172
	s_nop 1
	v_addc_co_u32_e32 v173, vcc, 0, v173, vcc
	global_load_dwordx4 v[172:175], v[172:173], off
	v_mfma_f32_32x32x16_bf16 v[18:33], v[208:211], v[240:243], v[18:33]
	v_lshl_add_u64 v[176:177], v[148:149], 0, v[130:131]
	v_add_co_u32_e32 v176, vcc, s42, v176
	s_nop 1
	v_addc_co_u32_e32 v177, vcc, 0, v177, vcc
	global_load_dwordx4 v[176:179], v[176:177], off offset:-4096
	v_mfma_f32_32x32x16_bf16 v[2:17], v[208:211], v[244:247], v[2:17]
	v_lshl_add_u64 v[180:181], v[148:149], 0, v[130:131]
	v_add_co_u32_e32 v180, vcc, s42, v180
	s_nop 1
	v_addc_co_u32_e32 v181, vcc, 0, v181, vcc
	global_load_dwordx4 v[180:183], v[180:181], off
	ds_read_b128 v[208:211], v133 offset:4672
	s_waitcnt lgkmcnt(4)
	v_mfma_f32_32x32x16_bf16 v[114:129], v[200:203], v[212:215], v[114:129]
	ds_read_b128 v[204:207], v133 offset:96
	ds_read_b128 v[232:235], v137 offset:18528
	s_waitcnt lgkmcnt(5)
	v_mfma_f32_32x32x16_bf16 v[98:113], v[200:203], v[216:219], v[98:113]
	ds_read_b128 v[236:239], v137 offset:23136
	s_waitcnt lgkmcnt(5)
	v_mfma_f32_32x32x16_bf16 v[82:97], v[200:203], v[224:227], v[82:97]
	ds_read_b128 v[240:243], v137 offset:27744
	s_waitcnt lgkmcnt(5)
	v_mfma_f32_32x32x16_bf16 v[66:81], v[200:203], v[228:231], v[66:81]
	ds_read_b128 v[244:247], v137 offset:32352
	s_waitcnt lgkmcnt(5)
	v_mfma_f32_32x32x16_bf16 v[50:65], v[208:211], v[212:215], v[50:65]
	v_lshl_add_u64 v[184:185], v[148:149], 0, v[130:131]
	v_add_co_u32_e32 v184, vcc, s43, v184
	s_nop 1
	v_addc_co_u32_e32 v185, vcc, 0, v185, vcc
	global_load_dwordx4 v[184:187], v[184:185], off offset:-4096
	v_mfma_f32_32x32x16_bf16 v[34:49], v[208:211], v[216:219], v[34:49]
	v_lshl_add_u64 v[188:189], v[148:149], 0, v[130:131]
	v_add_co_u32_e32 v188, vcc, s43, v188
	s_nop 1
	v_addc_co_u32_e32 v189, vcc, 0, v189, vcc
	global_load_dwordx4 v[188:191], v[188:189], off
	v_mfma_f32_32x32x16_bf16 v[18:33], v[208:211], v[224:227], v[18:33]
	v_lshl_add_u64 v[192:193], v[148:149], 0, v[130:131]
	v_add_co_u32_e32 v192, vcc, s44, v192
	s_nop 1
	v_addc_co_u32_e32 v193, vcc, 0, v193, vcc
	global_load_dwordx4 v[192:195], v[192:193], off offset:-4096
	v_mfma_f32_32x32x16_bf16 v[2:17], v[208:211], v[228:231], v[2:17]
	v_lshl_add_u64 v[196:197], v[148:149], 0, v[130:131]
	v_add_co_u32_e32 v196, vcc, s44, v196
	s_nop 1
	v_addc_co_u32_e32 v197, vcc, 0, v197, vcc
	global_load_dwordx4 v[196:199], v[196:197], off
	ds_read_b128 v[208:211], v133 offset:4704
	s_waitcnt lgkmcnt(4)
	v_mfma_f32_32x32x16_bf16 v[114:129], v[204:207], v[232:235], v[114:129]
	s_waitcnt lgkmcnt(3)
	v_mfma_f32_32x32x16_bf16 v[98:113], v[204:207], v[236:239], v[98:113]
	s_waitcnt lgkmcnt(2)
	v_mfma_f32_32x32x16_bf16 v[82:97], v[204:207], v[240:243], v[82:97]
	s_waitcnt lgkmcnt(1)
	v_mfma_f32_32x32x16_bf16 v[66:81], v[204:207], v[244:247], v[66:81]
	s_waitcnt lgkmcnt(0)
	v_mfma_f32_32x32x16_bf16 v[50:65], v[208:211], v[232:235], v[50:65]
	v_mfma_f32_32x32x16_bf16 v[34:49], v[208:211], v[236:239], v[34:49]
	v_mfma_f32_32x32x16_bf16 v[18:33], v[208:211], v[240:243], v[18:33]
	v_mfma_f32_32x32x16_bf16 v[2:17], v[208:211], v[244:247], v[2:17]
	s_setprio 0
	s_add_i32 s15, s15, -1
	v_lshl_add_u64 v[148:149], v[148:149], 0, s[4:5]
	s_cmp_lg_u32 s15, 0
	v_lshl_add_u64 v[150:151], v[150:151], 0, s[10:11]
	s_barrier
; #define GW_LOAD(KOFF) GW_LOAD2(KOFF, 0)
;     ...
;   GW_LOAD(0)
;   GW_STORE()
;   __syncthreads();
;   const int nk = K >> 6;
;   const char* Ab = smem + (wm * 64 + (lane & 31)) * LSTR + (lane >> 5) * 16;
;   const char* Bb = smem + WTILE_A + (wn * 128 + (lane & 31)) * LSTR + (lane >> 5) * 16;
;   for (int kt = 0; kt < nk; ++kt) {
;     const int kn = (kt + 1 < nk) ? kt + 1 : kt;
;     GW_LOAD2(kn * 64, kn * bkstep)
;     __builtin_amdgcn_sched_barrier(0);
;     __builtin_amdgcn_s_setprio(1);
; #pragma unroll
;     for (int st = 0; st < 4; ++st) {
;       bf16x8 a0 = *(const bf16x8*)(Ab + st * 32);
;       bf16x8 a1 = *(const bf16x8*)(Ab + 32 * LSTR + st * 32);
;       bf16x8 b0 = *(const bf16x8*)(Bb + st * 32);
;       bf16x8 b1 = *(const bf16x8*)(Bb + 32 * LSTR + st * 32);
;       bf16x8 b2 = *(const bf16x8*)(Bb + 64 * LSTR + st * 32);
;       bf16x8 b3 = *(const bf16x8*)(Bb + 96 * LSTR + st * 32);
;       acc[0][0] = mfma32(a0, b0, acc[0][0]);
;       acc[0][1] = mfma32(a0, b1, acc[0][1]);
;       acc[0][2] = mfma32(a0, b2, acc[0][2]);
;       acc[0][3] = mfma32(a0, b3, acc[0][3]);
;       acc[1][0] = mfma32(a1, b0, acc[1][0]);
;       acc[1][1] = mfma32(a1, b1, acc[1][1]);
;       acc[1][2] = mfma32(a1, b2, acc[1][2]);
;       acc[1][3] = mfma32(a1, b3, acc[1][3]);
;     }
;     __builtin_amdgcn_s_setprio(0);
;     __builtin_amdgcn_sched_barrier(0);
;     __syncthreads();
;     GW_STORE()
;     __syncthreads();
	s_waitcnt vmcnt(11)
	ds_write_b128 v132, v[152:155]
	s_waitcnt vmcnt(10)
	ds_write_b128 v132, v[156:159] offset:4608
	s_waitcnt vmcnt(9)
	ds_write_b128 v132, v[160:163] offset:9216
	s_waitcnt vmcnt(8)
	ds_write_b128 v132, v[164:167] offset:13824
	s_waitcnt vmcnt(7)
	ds_write_b128 v132, v[168:171] offset:18432
	s_waitcnt vmcnt(6)
	ds_write_b128 v132, v[172:175] offset:23040
	s_waitcnt vmcnt(5)
	ds_write_b128 v132, v[176:179] offset:27648
	s_waitcnt vmcnt(4)
	ds_write_b128 v132, v[180:183] offset:32256
	s_waitcnt vmcnt(3)
	ds_write_b128 v132, v[184:187] offset:36864
	s_waitcnt vmcnt(2)
	ds_write_b128 v132, v[188:191] offset:41472
	s_waitcnt vmcnt(1)
	ds_write_b128 v132, v[192:195] offset:46080
	s_waitcnt vmcnt(0)
	ds_write_b128 v132, v[196:199] offset:50688
	s_waitcnt lgkmcnt(0)
	s_barrier
	s_cbranch_scc1 .LBB0_2143
	s_setprio 1
	ds_read_b128 v[200:203], v133 offset:0
	ds_read_b128 v[212:215], v137 offset:18432
	ds_read_b128 v[216:219], v137 offset:23040
	ds_read_b128 v[224:227], v137 offset:27648
	ds_read_b128 v[228:231], v137 offset:32256
	ds_read_b128 v[208:211], v133 offset:4608
	s_waitcnt lgkmcnt(4)
	v_mfma_f32_32x32x16_bf16 v[114:129], v[200:203], v[212:215], v[114:129]
	ds_read_b128 v[204:207], v133 offset:32
	ds_read_b128 v[232:235], v137 offset:18464
	s_waitcnt lgkmcnt(5)
	v_mfma_f32_32x32x16_bf16 v[98:113], v[200:203], v[216:219], v[98:113]
	ds_read_b128 v[236:239], v137 offset:23072
	s_waitcnt lgkmcnt(5)
	v_mfma_f32_32x32x16_bf16 v[82:97], v[200:203], v[224:227], v[82:97]
	ds_read_b128 v[240:243], v137 offset:27680
	s_waitcnt lgkmcnt(5)
	v_mfma_f32_32x32x16_bf16 v[66:81], v[200:203], v[228:231], v[66:81]
	ds_read_b128 v[244:247], v137 offset:32288
	s_waitcnt lgkmcnt(5)
	v_mfma_f32_32x32x16_bf16 v[50:65], v[208:211], v[212:215], v[50:65]
	v_lshl_add_u64 v[152:153], v[150:151], 0, v[130:131]
	v_add_co_u32_e32 v152, vcc, s37, v152
	s_nop 1
	v_addc_co_u32_e32 v153, vcc, 0, v153, vcc
	global_load_dwordx4 v[152:155], v[152:153], off offset:384
	v_mfma_f32_32x32x16_bf16 v[34:49], v[208:211], v[216:219], v[34:49]
	v_lshl_add_u64 v[156:157], v[150:151], 0, v[130:131]
	v_add_co_u32_e32 v156, vcc, s38, v156
	s_nop 1
	v_addc_co_u32_e32 v157, vcc, 0, v157, vcc
	global_load_dwordx4 v[156:159], v[156:157], off offset:384
	v_mfma_f32_32x32x16_bf16 v[18:33], v[208:211], v[224:227], v[18:33]
	v_lshl_add_u64 v[160:161], v[150:151], 0, v[130:131]
	v_add_co_u32_e32 v160, vcc, s39, v160
	s_nop 1
	v_addc_co_u32_e32 v161, vcc, 0, v161, vcc
	global_load_dwordx4 v[160:163], v[160:161], off offset:384
	v_mfma_f32_32x32x16_bf16 v[2:17], v[208:211], v[228:231], v[2:17]
	v_lshl_add_u64 v[164:165], v[150:151], 0, v[130:131]
	v_add_co_u32_e32 v164, vcc, s40, v164
	s_nop 1
	v_addc_co_u32_e32 v165, vcc, 0, v165, vcc
	global_load_dwordx4 v[164:167], v[164:165], off offset:384
	ds_read_b128 v[208:211], v133 offset:4640
	s_waitcnt lgkmcnt(4)
	v_mfma_f32_32x32x16_bf16 v[114:129], v[204:207], v[232:235], v[114:129]
	ds_read_b128 v[200:203], v133 offset:64
	ds_read_b128 v[212:215], v137 offset:18496
	s_waitcnt lgkmcnt(5)
	v_mfma_f32_32x32x16_bf16 v[98:113], v[204:207], v[236:239], v[98:113]
	ds_read_b128 v[216:219], v137 offset:23104
	s_waitcnt lgkmcnt(5)
	v_mfma_f32_32x32x16_bf16 v[82:97], v[204:207], v[240:243], v[82:97]
	ds_read_b128 v[224:227], v137 offset:27712
	s_waitcnt lgkmcnt(5)
	v_mfma_f32_32x32x16_bf16 v[66:81], v[204:207], v[244:247], v[66:81]
	ds_read_b128 v[228:231], v137 offset:32320
	s_waitcnt lgkmcnt(5)
	v_mfma_f32_32x32x16_bf16 v[50:65], v[208:211], v[232:235], v[50:65]
	v_lshl_add_u64 v[168:169], v[148:149], 0, v[130:131]
	v_add_co_u32_e32 v168, vcc, s41, v168
	s_nop 1
	v_addc_co_u32_e32 v169, vcc, 0, v169, vcc
	global_load_dwordx4 v[168:171], v[168:169], off offset:-4096
	v_mfma_f32_32x32x16_bf16 v[34:49], v[208:211], v[236:239], v[34:49]
	v_lshl_add_u64 v[172:173], v[148:149], 0, v[130:131]
	v_add_co_u32_e32 v172, vcc, s41, v172
	s_nop 1
	v_addc_co_u32_e32 v173, vcc, 0, v173, vcc
	global_load_dwordx4 v[172:175], v[172:173], off
	v_mfma_f32_32x32x16_bf16 v[18:33], v[208:211], v[240:243], v[18:33]
	v_lshl_add_u64 v[176:177], v[148:149], 0, v[130:131]
	v_add_co_u32_e32 v176, vcc, s42, v176
	s_nop 1
	v_addc_co_u32_e32 v177, vcc, 0, v177, vcc
	global_load_dwordx4 v[176:179], v[176:177], off offset:-4096
	v_mfma_f32_32x32x16_bf16 v[2:17], v[208:211], v[244:247], v[2:17]
	v_lshl_add_u64 v[180:181], v[148:149], 0, v[130:131]
	v_add_co_u32_e32 v180, vcc, s42, v180
	s_nop 1
	v_addc_co_u32_e32 v181, vcc, 0, v181, vcc
	global_load_dwordx4 v[180:183], v[180:181], off
	ds_read_b128 v[208:211], v133 offset:4672
	s_waitcnt lgkmcnt(4)
	v_mfma_f32_32x32x16_bf16 v[114:129], v[200:203], v[212:215], v[114:129]
	ds_read_b128 v[204:207], v133 offset:96
	ds_read_b128 v[232:235], v137 offset:18528
	s_waitcnt lgkmcnt(5)
	v_mfma_f32_32x32x16_bf16 v[98:113], v[200:203], v[216:219], v[98:113]
	ds_read_b128 v[236:239], v137 offset:23136
	s_waitcnt lgkmcnt(5)
	v_mfma_f32_32x32x16_bf16 v[82:97], v[200:203], v[224:227], v[82:97]
	ds_read_b128 v[240:243], v137 offset:27744
	s_waitcnt lgkmcnt(5)
	v_mfma_f32_32x32x16_bf16 v[66:81], v[200:203], v[228:231], v[66:81]
	ds_read_b128 v[244:247], v137 offset:32352
	s_waitcnt lgkmcnt(5)
;     ...
;   for (int kt = 0; kt < nk; ++kt) {
;     const int kn = (kt + 1 < nk) ? kt + 1 : kt;
;     GW_LOAD2(kn * 64, kn * bkstep)
;     __builtin_amdgcn_sched_barrier(0);
;     __builtin_amdgcn_s_setprio(1);
; #pragma unroll
;     for (int st = 0; st < 4; ++st) {
;       bf16x8 a0 = *(const bf16x8*)(Ab + st * 32);
;       bf16x8 a1 = *(const bf16x8*)(Ab + 32 * LSTR + st * 32);
;       bf16x8 b0 = *(const bf16x8*)(Bb + st * 32);
;       bf16x8 b1 = *(const bf16x8*)(Bb + 32 * LSTR + st * 32);
;       bf16x8 b2 = *(const bf16x8*)(Bb + 64 * LSTR + st * 32);
;       bf16x8 b3 = *(const bf16x8*)(Bb + 96 * LSTR + st * 32);
;       acc[0][0] = mfma32(a0, b0, acc[0][0]);
;       acc[0][1] = mfma32(a0, b1, acc[0][1]);
;       acc[0][2] = mfma32(a0, b2, acc[0][2]);
;       acc[0][3] = mfma32(a0, b3, acc[0][3]);
;       acc[1][0] = mfma32(a1, b0, acc[1][0]);
;       acc[1][1] = mfma32(a1, b1, acc[1][1]);
;       acc[1][2] = mfma32(a1, b2, acc[1][2]);
;       acc[1][3] = mfma32(a1, b3, acc[1][3]);
;     }
;     __builtin_amdgcn_s_setprio(0);
;     __builtin_amdgcn_sched_barrier(0);
;     __syncthreads();
;     GW_STORE()
;     __syncthreads();
	v_mfma_f32_32x32x16_bf16 v[50:65], v[208:211], v[212:215], v[50:65]
	v_lshl_add_u64 v[184:185], v[148:149], 0, v[130:131]
	v_add_co_u32_e32 v184, vcc, s43, v184
	s_nop 1
	v_addc_co_u32_e32 v185, vcc, 0, v185, vcc
	global_load_dwordx4 v[184:187], v[184:185], off offset:-4096
	v_mfma_f32_32x32x16_bf16 v[34:49], v[208:211], v[216:219], v[34:49]
	v_lshl_add_u64 v[188:189], v[148:149], 0, v[130:131]
	v_add_co_u32_e32 v188, vcc, s43, v188
	s_nop 1
	v_addc_co_u32_e32 v189, vcc, 0, v189, vcc
	global_load_dwordx4 v[188:191], v[188:189], off
	v_mfma_f32_32x32x16_bf16 v[18:33], v[208:211], v[224:227], v[18:33]
	v_lshl_add_u64 v[192:193], v[148:149], 0, v[130:131]
	v_add_co_u32_e32 v192, vcc, s44, v192
	s_nop 1
	v_addc_co_u32_e32 v193, vcc, 0, v193, vcc
	global_load_dwordx4 v[192:195], v[192:193], off offset:-4096
	v_mfma_f32_32x32x16_bf16 v[2:17], v[208:211], v[228:231], v[2:17]
	v_lshl_add_u64 v[196:197], v[148:149], 0, v[130:131]
	v_add_co_u32_e32 v196, vcc, s44, v196
	s_nop 1
	v_addc_co_u32_e32 v197, vcc, 0, v197, vcc
	global_load_dwordx4 v[196:199], v[196:197], off
	ds_read_b128 v[208:211], v133 offset:4704
	s_waitcnt lgkmcnt(4)
	v_mfma_f32_32x32x16_bf16 v[114:129], v[204:207], v[232:235], v[114:129]
	s_waitcnt lgkmcnt(3)
	v_mfma_f32_32x32x16_bf16 v[98:113], v[204:207], v[236:239], v[98:113]
	s_waitcnt lgkmcnt(2)
	v_mfma_f32_32x32x16_bf16 v[82:97], v[204:207], v[240:243], v[82:97]
	s_waitcnt lgkmcnt(1)
	v_mfma_f32_32x32x16_bf16 v[66:81], v[204:207], v[244:247], v[66:81]
	s_waitcnt lgkmcnt(0)
	v_mfma_f32_32x32x16_bf16 v[50:65], v[208:211], v[232:235], v[50:65]
	v_mfma_f32_32x32x16_bf16 v[34:49], v[208:211], v[236:239], v[34:49]
	v_mfma_f32_32x32x16_bf16 v[18:33], v[208:211], v[240:243], v[18:33]
	v_mfma_f32_32x32x16_bf16 v[2:17], v[208:211], v[244:247], v[2:17]
	s_setprio 0
	v_lshl_add_u64 v[148:149], v[148:149], 0, s[4:5]
	v_lshl_add_u64 v[150:151], v[150:151], 0, s[10:11]
	s_barrier
	s_waitcnt vmcnt(11)
	ds_write_b128 v132, v[152:155]
	s_waitcnt vmcnt(10)
	ds_write_b128 v132, v[156:159] offset:4608
	s_waitcnt vmcnt(9)
	ds_write_b128 v132, v[160:163] offset:9216
	s_waitcnt vmcnt(8)
	ds_write_b128 v132, v[164:167] offset:13824
	s_waitcnt vmcnt(7)
	ds_write_b128 v132, v[168:171] offset:18432
	s_waitcnt vmcnt(6)
	ds_write_b128 v132, v[172:175] offset:23040
	s_waitcnt vmcnt(5)
	ds_write_b128 v132, v[176:179] offset:27648
	s_waitcnt vmcnt(4)
	ds_write_b128 v132, v[180:183] offset:32256
	s_waitcnt vmcnt(3)
	ds_write_b128 v132, v[184:187] offset:36864
	s_waitcnt vmcnt(2)
	ds_write_b128 v132, v[188:191] offset:41472
	s_waitcnt vmcnt(1)
	ds_write_b128 v132, v[192:195] offset:46080
	s_waitcnt vmcnt(0)
	ds_write_b128 v132, v[196:199] offset:50688
	s_waitcnt lgkmcnt(0)
	s_barrier
;     ...
;   for (int kt = 0; kt < nk; ++kt) {
;     const int kn = (kt + 1 < nk) ? kt + 1 : kt;
;     GW_LOAD2(kn * 64, kn * bkstep)
;     __builtin_amdgcn_sched_barrier(0);
;     __builtin_amdgcn_s_setprio(1);
; #pragma unroll
;     for (int st = 0; st < 4; ++st) {
;       bf16x8 a0 = *(const bf16x8*)(Ab + st * 32);
;       bf16x8 a1 = *(const bf16x8*)(Ab + 32 * LSTR + st * 32);
;       bf16x8 b0 = *(const bf16x8*)(Bb + st * 32);
;       bf16x8 b1 = *(const bf16x8*)(Bb + 32 * LSTR + st * 32);
;       bf16x8 b2 = *(const bf16x8*)(Bb + 64 * LSTR + st * 32);
;       bf16x8 b3 = *(const bf16x8*)(Bb + 96 * LSTR + st * 32);
;       acc[0][0] = mfma32(a0, b0, acc[0][0]);
;       acc[0][1] = mfma32(a0, b1, acc[0][1]);
;       acc[0][2] = mfma32(a0, b2, acc[0][2]);
;       acc[0][3] = mfma32(a0, b3, acc[0][3]);
;       acc[1][0] = mfma32(a1, b0, acc[1][0]);
;       acc[1][1] = mfma32(a1, b1, acc[1][1]);
;       acc[1][2] = mfma32(a1, b2, acc[1][2]);
;       acc[1][3] = mfma32(a1, b3, acc[1][3]);
;     }
;     __builtin_amdgcn_s_setprio(0);
	v_add_co_u32_e32 v156, vcc, 0x3e0000, v138
	s_nop 0
	s_nop 0
	s_nop 0
	v_addc_co_u32_e32 v157, vcc, 0, v139, vcc
	v_add_co_u32_e32 v160, vcc, 0x3e1000, v138
	s_mov_b32 s18, 0
	s_nop 0
	v_addc_co_u32_e32 v161, vcc, 0, v139, vcc
	v_add_co_u32_e32 v164, vcc, 0x3e2000, v138
	s_nop 0
	v_addc_co_u32_e32 v165, vcc, 0, v139, vcc
	v_add_co_u32_e32 v168, vcc, 0x3e3000, v138
	s_nop 1
	v_addc_co_u32_e32 v169, vcc, 0, v139, vcc
	v_add_co_u32_e32 v172, vcc, 0x3e4000, v138
	s_nop 0
	v_addc_co_u32_e32 v173, vcc, 0, v139, vcc
	v_add_co_u32_e32 v176, vcc, 0x3e5000, v138
	s_nop 1
	v_addc_co_u32_e32 v177, vcc, 0, v139, vcc
	v_add_co_u32_e32 v180, vcc, 0x3e6000, v138
	s_nop 0
	v_addc_co_u32_e32 v181, vcc, 0, v139, vcc
	v_add_co_u32_e32 v138, vcc, 0x3e7000, v138
	s_nop 1
	v_addc_co_u32_e32 v139, vcc, 0, v139, vcc
	s_nop 0
	s_setprio 1
	ds_read_b128 v[188:191], v133 offset:0
	ds_read_b128 v[200:203], v137 offset:18432
	ds_read_b128 v[204:207], v137 offset:23040
	ds_read_b128 v[208:211], v137 offset:27648
	ds_read_b128 v[212:215], v137 offset:32256
	ds_read_b128 v[196:199], v133 offset:4608
	s_waitcnt lgkmcnt(4)
	v_mfma_f32_32x32x16_bf16 v[114:129], v[188:191], v[200:203], v[114:129]
	ds_read_b128 v[192:195], v133 offset:32
	ds_read_b128 v[216:219], v137 offset:18464
	s_waitcnt lgkmcnt(5)
	v_mfma_f32_32x32x16_bf16 v[98:113], v[188:191], v[204:207], v[98:113]
	ds_read_b128 v[224:227], v137 offset:23072
	s_waitcnt lgkmcnt(5)
	v_mfma_f32_32x32x16_bf16 v[82:97], v[188:191], v[208:211], v[82:97]
	ds_read_b128 v[228:231], v137 offset:27680
	s_waitcnt lgkmcnt(5)
	v_mfma_f32_32x32x16_bf16 v[66:81], v[188:191], v[212:215], v[66:81]
	ds_read_b128 v[232:235], v137 offset:32288
	s_waitcnt lgkmcnt(5)
	v_mfma_f32_32x32x16_bf16 v[50:65], v[196:199], v[200:203], v[50:65]
	v_mfma_f32_32x32x16_bf16 v[34:49], v[196:199], v[204:207], v[34:49]
	v_mfma_f32_32x32x16_bf16 v[18:33], v[196:199], v[208:211], v[18:33]
	v_mfma_f32_32x32x16_bf16 v[2:17], v[196:199], v[212:215], v[2:17]
	ds_read_b128 v[196:199], v133 offset:4640
	s_waitcnt lgkmcnt(4)
	v_mfma_f32_32x32x16_bf16 v[114:129], v[192:195], v[216:219], v[114:129]
	ds_read_b128 v[188:191], v133 offset:64
	ds_read_b128 v[200:203], v137 offset:18496
	s_waitcnt lgkmcnt(5)
	v_mfma_f32_32x32x16_bf16 v[98:113], v[192:195], v[224:227], v[98:113]
	ds_read_b128 v[204:207], v137 offset:23104
	s_waitcnt lgkmcnt(5)
	v_mfma_f32_32x32x16_bf16 v[82:97], v[192:195], v[228:231], v[82:97]
	ds_read_b128 v[208:211], v137 offset:27712
	s_waitcnt lgkmcnt(5)
	v_mfma_f32_32x32x16_bf16 v[66:81], v[192:195], v[232:235], v[66:81]
	ds_read_b128 v[212:215], v137 offset:32320
	s_waitcnt lgkmcnt(5)
	v_mfma_f32_32x32x16_bf16 v[50:65], v[196:199], v[216:219], v[50:65]
	v_mfma_f32_32x32x16_bf16 v[34:49], v[196:199], v[224:227], v[34:49]
	v_mfma_f32_32x32x16_bf16 v[18:33], v[196:199], v[228:231], v[18:33]
	v_mfma_f32_32x32x16_bf16 v[2:17], v[196:199], v[232:235], v[2:17]
	ds_read_b128 v[196:199], v133 offset:4672
	s_waitcnt lgkmcnt(4)
	v_mfma_f32_32x32x16_bf16 v[114:129], v[188:191], v[200:203], v[114:129]
	ds_read_b128 v[192:195], v133 offset:96
	ds_read_b128 v[216:219], v137 offset:18528
	s_waitcnt lgkmcnt(5)
	v_mfma_f32_32x32x16_bf16 v[98:113], v[188:191], v[204:207], v[98:113]
	ds_read_b128 v[224:227], v137 offset:23136
	s_waitcnt lgkmcnt(5)
	v_mfma_f32_32x32x16_bf16 v[82:97], v[188:191], v[208:211], v[82:97]
	ds_read_b128 v[228:231], v137 offset:27744
	s_waitcnt lgkmcnt(5)
	v_mfma_f32_32x32x16_bf16 v[66:81], v[188:191], v[212:215], v[66:81]
	ds_read_b128 v[232:235], v137 offset:32352
	s_waitcnt lgkmcnt(5)
	v_mfma_f32_32x32x16_bf16 v[50:65], v[196:199], v[200:203], v[50:65]
	v_mfma_f32_32x32x16_bf16 v[34:49], v[196:199], v[204:207], v[34:49]
	v_mfma_f32_32x32x16_bf16 v[18:33], v[196:199], v[208:211], v[18:33]
	v_mfma_f32_32x32x16_bf16 v[2:17], v[196:199], v[212:215], v[2:17]
	ds_read_b128 v[196:199], v133 offset:4704
	s_waitcnt lgkmcnt(4)
	v_mfma_f32_32x32x16_bf16 v[114:129], v[192:195], v[216:219], v[114:129]
	s_waitcnt lgkmcnt(3)
	v_mfma_f32_32x32x16_bf16 v[98:113], v[192:195], v[224:227], v[98:113]
	s_waitcnt lgkmcnt(2)
	v_mfma_f32_32x32x16_bf16 v[82:97], v[192:195], v[228:231], v[82:97]
	s_waitcnt lgkmcnt(1)
	v_mfma_f32_32x32x16_bf16 v[66:81], v[192:195], v[232:235], v[66:81]
	s_waitcnt lgkmcnt(0)
	v_mfma_f32_32x32x16_bf16 v[50:65], v[196:199], v[216:219], v[50:65]
	v_mfma_f32_32x32x16_bf16 v[34:49], v[196:199], v[224:227], v[34:49]
	v_mfma_f32_32x32x16_bf16 v[18:33], v[196:199], v[228:231], v[18:33]
	v_mfma_f32_32x32x16_bf16 v[2:17], v[196:199], v[232:235], v[2:17]
	s_setprio 0
	s_lshl_b32 s19, s14, 8
	s_mov_b64 s[14:15], -1
	s_barrier
	s_waitcnt lgkmcnt(0)
	s_branch .LBB0_2146
